# sc1 write-through stores for the in-projection tiles (before the P1|P2 grid seam) and for the recurrence + SWA outputs (before the P2|P3 grid seam)
# baseline (speedup 1.0000x reference)
; __device__ __forceinline__ float frsq(float x) { return __builtin_amdgcn_rsqf(x); }
;     __device__ __forceinline__ void operator()(Acc& acc, const Unit& u, int wr, int wc, int fr, int fq) const {
;     ...
;                 const bool isk = (pn == 10);
;                 const float* gp = isk ? kng : qng; const float osc = isk ? 1.0f : 0.125f * 1.4426950408889634f;
;                 f32x4 g[2][2];
; #pragma unroll
;                 for (int bj = 0; bj < 2; ++bj)
; #pragma unroll
;                     for (int n = 0; n < 2; ++n) g[bj][n] = *(const f32x4*)(gp + bj * 32 + 8 * fq + 4 * n) * osc;
;                 bf16_t* ob = isk ? (SK + wc * 64 + 8 * fq) : (SQ + (pn - 8) * 256 + wc * 64 + 8 * fq); const int ld = isk ? 128 : 512;
; #pragma unroll
;                 for (int ai = 0; ai < 2; ++ai) {
; #pragma unroll
;                   for (int mh = 0; mh < 2; ++mh) {
;                     f32x4 rc[2][2], rs[2][2];
; #pragma unroll
;                     for (int m2 = 0; m2 < 2; ++m2) { const float* rp = rope + (size_t)(row0 + ai * HALF + (2 * mh + m2) * 16) * 16;
; #pragma unroll
;                         for (int n = 0; n < 2; ++n) { rc[m2][n] = *(const f32x4*)(rp + 4 * n); rs[m2][n] = *(const f32x4*)(rp + 8 + 4 * n); } }
;                     __builtin_amdgcn_sched_barrier(0);
; #pragma unroll
;                     for (int m2 = 0; m2 < 2; ++m2) { const int m = 2 * mh + m2;
;                         const int row = row0 + ai * HALF + m * 16;
;                         float ss = 0.f;
; #pragma unroll
;                         for (int bj = 0; bj < 2; ++bj)
; #pragma unroll
;                             for (int n = 0; n < 2; ++n) { const f32x4 v = acc[ai][bj][m][n]; ss += (v[0] * v[0] + v[1] * v[1]) + (v[2] * v[2] + v[3] * v[3]); }
;                         ss += __shfl_xor(ss, 16); ss += __shfl_xor(ss, 32);
;                         const float rstd = frsq(ss * (1.0f / 64.0f) + EPS);
.LBB0_175:
	v_mov_b32_e32 v128, v210
	v_mov_b32_e32 v219, v209
	s_lshl_b32 s4, s84, 8
	s_add_i32 s4, s4, s27
	v_lshlrev_b32_e32 v176, 3, v128
	v_add_u32_e32 v174, s4, v219
	v_add_u32_e32 v172, s28, v176
	s_cmp_lg_u32 s39, 1
	s_mov_b64 s[4:5], -1
	s_cbranch_scc0 .LBB0_198
	s_cmp_gt_i32 s40, 3
	s_cbranch_scc0 .LBB0_190
	s_cmp_gt_u32 s40, 5
	s_cbranch_scc0 .LBB0_187
	s_cmp_gt_u32 s40, 7
	s_cbranch_scc0 .LBB0_184
	s_cmp_eq_u32 s40, 10
	s_cselect_b64 s[70:71], -1, 0
	s_and_b64 s[48:49], s[70:71], s[56:57]
	s_andn2_b64 vcc, exec, s[48:49]
	v_ashrrev_i32_e32 v177, 31, v176
	s_cbranch_vccz .LBB0_181
	s_and_b64 s[4:5], s[70:71], exec
	s_mov_b64 s[4:5], s[62:63]
	s_mov_b32 s12, s55
	s_mov_b32 s39, s58
	s_mov_b64 s[80:81], s[52:53]
	s_mov_b64 vcc, s[56:57]
	v_readlane_b32 s48, v254, 24
	v_readlane_b32 s52, v254, 28
	v_readlane_b32 s53, v254, 29
	v_readlane_b32 s54, v254, 30
	v_readlane_b32 s55, v254, 31
	v_readlane_b32 s56, v254, 32
	v_readlane_b32 s57, v254, 33
	v_readlane_b32 s58, v254, 34
	v_readlane_b32 s59, v254, 35
	v_readlane_b32 s60, v254, 36
	v_readlane_b32 s61, v254, 37
	v_readlane_b32 s62, v254, 38
	v_readlane_b32 s63, v254, 39
	v_readlane_b32 s52, v254, 8
	v_readlane_b32 s49, v254, 25
	v_readlane_b32 s62, v254, 18
	v_readlane_b32 s63, v254, 19
	v_readlane_b32 s66, v254, 22
	v_readlane_b32 s67, v254, 23
	s_mov_b64 s[62:63], s[4:5]
	s_cselect_b32 s4, s49, s67
	s_cselect_b32 s5, s48, s66
	v_mov_b32_e32 v130, s5
	v_mov_b32_e32 v131, s4
	v_lshl_add_u64 v[140:141], v[176:177], 2, v[130:131]
	global_load_dwordx4 v[130:133], v[140:141], off offset:16
	global_load_dwordx4 v[134:137], v[140:141], off
	v_cndmask_b32_e64 v138, v216, 1.0, s[70:71]
	v_readlane_b32 s55, v254, 11
	s_lshl_b32 s4, s40, 8
	s_mov_b32 s55, s12
	s_add_i32 s12, s4, 0xfffff800
	s_lshl_b64 s[4:5], s[12:13], 1
	v_readlane_b32 s12, v254, 47
	v_readlane_b32 s58, v254, 14
	s_add_u32 s12, s12, s4
	v_readlane_b32 s4, v254, 48
	v_readlane_b32 s56, v254, 12
	v_readlane_b32 s57, v254, 13
	s_mov_b32 s58, s39
	s_addc_u32 s39, s4, s5
	v_xor_b32_e32 v129, 16, v217
	s_mov_b64 s[56:57], vcc
	s_and_b64 s[4:5], s[70:71], exec
	v_readlane_b32 s4, v254, 49
	v_readlane_b32 s5, v254, 50
	s_cselect_b32 s4, s4, s12
	v_readlane_b32 s12, v254, 63
	v_readlane_b32 s50, v254, 26
	v_readlane_b32 s51, v254, 27
	s_cselect_b32 s5, s5, s39
	s_add_u32 s4, s4, s12
	s_addc_u32 s5, s5, 0
	v_ashrrev_i32_e32 v175, 31, v174
	v_readlane_b32 s50, v254, 57
	v_lshl_add_u64 v[178:179], v[176:177], 1, s[4:5]
	v_cmp_eq_u32_e64 s[4:5], 0, v128
	v_readlane_b32 s51, v254, 58
	v_add_u32_e32 v196, 16, v174
	v_ashrrev_i32_e32 v197, 31, v196
	v_readlane_b32 s53, v254, 9
	v_readlane_b32 s60, v254, 16
	v_readlane_b32 s61, v254, 17
	v_readlane_b32 s64, v254, 20
	v_readlane_b32 s65, v254, 21
	s_mov_b64 s[64:65], 0xc000
	s_mov_b64 s[60:61], 0x4000
	s_mov_b64 s[52:53], s[80:81]
	s_mov_b64 s[66:67], 0x20000
	v_readlane_b32 s54, v254, 10
	v_readlane_b32 s59, v254, 15
	s_waitcnt vmcnt(0)
	v_pk_mul_f32 v[180:181], v[138:139], v[132:133] op_sel_hi:[0,1]
	v_pk_mul_f32 v[184:185], v[138:139], v[136:137] op_sel_hi:[0,1]
	v_pk_mul_f32 v[186:187], v[138:139], v[134:135] op_sel_hi:[0,1]
	v_pk_mul_f32 v[182:183], v[138:139], v[130:131] op_sel_hi:[0,1]
	global_load_dwordx4 v[130:133], v[140:141], off offset:144
	global_load_dwordx4 v[134:137], v[140:141], off offset:128
	s_waitcnt vmcnt(1)
	v_pk_mul_f32 v[190:191], v[138:139], v[130:131] op_sel_hi:[0,1]
	v_and_b32_e32 v130, 64, v217
	v_add_u32_e32 v130, 64, v130
	v_cmp_lt_i32_e32 vcc, v129, v130
	s_waitcnt vmcnt(0)
	v_pk_mul_f32 v[192:193], v[138:139], v[136:137] op_sel_hi:[0,1]
	v_pk_mul_f32 v[194:195], v[138:139], v[134:135] op_sel_hi:[0,1]
	v_cndmask_b32_e32 v129, v217, v129, vcc
	v_lshlrev_b32_e32 v173, 2, v129
	v_xor_b32_e32 v129, 32, v217
	v_cmp_lt_i32_e32 vcc, v129, v130
	v_pk_mul_f32 v[188:189], v[138:139], v[132:133] op_sel_hi:[0,1]
	s_nop 0
	v_cndmask_b32_e32 v129, v217, v129, vcc
	v_lshlrev_b32_e32 v220, 2, v129
	v_cmp_gt_i32_e32 vcc, 2, v128
	v_lshlrev_b64 v[128:129], 6, v[174:175]
	v_lshl_add_u64 v[128:129], s[50:51], 0, v[128:129]
	global_load_dwordx4 v[144:147], v[128:129], off offset:16
	global_load_dwordx4 v[148:151], v[128:129], off offset:48
	global_load_dwordx4 v[152:155], v[128:129], off
	global_load_dwordx4 v[156:159], v[128:129], off offset:32
	v_lshlrev_b64 v[128:129], 6, v[196:197]
	v_lshl_add_u64 v[140:141], s[50:51], 0, v[128:129]
	global_load_dwordx4 v[128:131], v[140:141], off offset:16
	global_load_dwordx4 v[132:135], v[140:141], off offset:48
	global_load_dwordx4 v[136:139], v[140:141], off
	s_nop 0
	global_load_dwordx4 v[140:143], v[140:141], off offset:32
	v_pk_mul_f32 v[198:199], v[126:127], v[126:127]
	v_pk_mul_f32 v[200:201], v[124:125], v[124:125]
	s_and_b64 s[48:49], s[70:71], exec
	v_pk_mov_b32 v[202:203], v[200:201], v[198:199] op_sel:[1,0]
	v_mov_b32_e32 v201, v199
	v_pk_add_f32 v[198:199], v[202:203], v[200:201]
	v_pk_mul_f32 v[200:201], v[122:123], v[122:123]
	v_pk_mul_f32 v[202:203], v[120:121], v[120:121]
	v_pk_add_f32 v[198:199], v[198:199], v[198:199] op_sel:[0,1] op_sel_hi:[1,0]
	v_pk_mov_b32 v[204:205], v[202:203], v[200:201] op_sel:[1,0]
	v_mov_b32_e32 v203, v201
	v_pk_add_f32 v[200:201], v[204:205], v[202:203]
	v_mul_f32_e32 v202, v104, v104
	v_mul_f32_e32 v203, v105, v105
	v_pk_add_f32 v[200:201], v[200:201], v[200:201] op_sel:[0,1] op_sel_hi:[1,0]
	v_mov_b32_e32 v199, v202
	v_mov_b32_e32 v201, v203
	v_pk_add_f32 v[198:199], v[198:199], v[200:201]
	v_mul_f32_e32 v200, v113, v113
	v_mul_f32_e32 v202, v115, v115
	v_mul_f32_e32 v204, v106, v106
	v_mul_f32_e32 v205, v107, v107
	v_pk_fma_f32 v[200:201], v[112:113], v[112:113], v[200:201] op_sel_hi:[1,1,0]
	v_pk_fma_f32 v[202:203], v[114:115], v[114:115], v[202:203] op_sel_hi:[1,1,0]
	v_mov_b32_e32 v201, v204
	v_mov_b32_e32 v203, v205
	v_pk_add_f32 v[200:201], v[200:201], v[202:203]
	s_cselect_b32 s12, 7, 9
	v_pk_add_f32 v[198:199], v[198:199], v[200:201]
	s_nop 0
	v_add_f32_e32 v198, v198, v199
	ds_bpermute_b32 v199, v173, v198
	s_waitcnt lgkmcnt(0)
; __device__ __forceinline__ u32x4 pack8(const f32x4& a, const f32x4& b) { u32x4 w; w.x = cvt_pk_bf16(a[0], a[1]); w.y = cvt_pk_bf16(a[2], a[3]); w.z = cvt_pk_bf16(b[0], b[1]); w.w = cvt_pk_bf16(b[2], b[3]); return w; }
; __device__ __forceinline__ float frsq(float x) { return __builtin_amdgcn_rsqf(x); }
;     __device__ __forceinline__ void operator()(Acc& acc, const Unit& u, int wr, int wc, int fr, int fq) const {
;     ...
;                         const float rstd = frsq(ss * (1.0f / 64.0f) + EPS);
;                         f32x4 y[2][2];
; #pragma unroll
;                         for (int bj = 0; bj < 2; ++bj)
; #pragma unroll
;                             for (int n = 0; n < 2; ++n) y[bj][n] = acc[ai][bj][m][n] * rstd * g[bj][n];
; #pragma unroll
;                         for (int n = 0; n < 2; ++n) {
;                             const f32x4 cs = rc[m2][n], sn = rs[m2][n];
;                             f32x4 o;
; #pragma unroll
;                             for (int i = 0; i < 4; ++i) { const float mine = y[0][n][i], oth = __shfl_xor(mine, 16);
;                                 const float r = (fq == 0) ? (mine * cs[i] - oth * sn[i]) : (mine * cs[i] + oth * sn[i]);
;                                 o[i] = (fq < 2) ? r : mine; }
;                             y[0][n] = o;
;                         }
; #pragma unroll
;                         for (int bj = 0; bj < 2; ++bj) *(u32x4*)(ob + (size_t)row * ld + bj * 32) = pack8(y[bj][0], y[bj][1]);
	v_add_f32_e32 v198, v198, v199
	ds_bpermute_b32 v199, v220, v198
	s_waitcnt lgkmcnt(0)
	v_add_f32_e32 v198, v198, v199
	v_fmamk_f32 v198, v198, 0x3c800000, v215
	v_rsq_f32_e32 v202, v198
	s_nop 0
	v_pk_mul_f32 v[198:199], v[124:125], v[202:203] op_sel_hi:[1,0]
	s_nop 0
	v_pk_mul_f32 v[224:225], v[186:187], v[198:199]
	ds_bpermute_b32 v221, v173, v224
	v_pk_mul_f32 v[200:201], v[126:127], v[202:203] op_sel_hi:[1,0]
	v_pk_mul_f32 v[198:199], v[120:121], v[202:203] op_sel_hi:[1,0]
	v_pk_mul_f32 v[222:223], v[184:185], v[200:201]
	v_pk_mul_f32 v[226:227], v[182:183], v[198:199]
	s_waitcnt vmcnt(4) lgkmcnt(0)
	v_mul_f32_e32 v156, v156, v221
	v_cndmask_b32_e64 v156, v156, -v156, s[4:5]
	v_fmac_f32_e32 v156, v152, v224
	v_cndmask_b32_e32 v152, v224, v156, vcc
	ds_bpermute_b32 v156, v173, v225
	v_pk_mul_f32 v[200:201], v[122:123], v[202:203] op_sel_hi:[1,0]
	v_pk_mul_f32 v[198:199], v[114:115], v[202:203] op_sel_hi:[1,0]
	v_pk_mul_f32 v[206:207], v[180:181], v[200:201]
	v_pk_mul_f32 v[200:201], v[112:113], v[202:203] op_sel_hi:[1,0]
	s_waitcnt lgkmcnt(0)
	v_mul_f32_e32 v156, v157, v156
	v_cndmask_b32_e64 v156, v156, -v156, s[4:5]
	v_fmac_f32_e32 v156, v153, v225
	v_cndmask_b32_e32 v153, v225, v156, vcc
	ds_bpermute_b32 v156, v173, v222
	v_pk_mul_f32 v[204:205], v[104:105], v[202:203] op_sel_hi:[1,0]
	v_pk_mul_f32 v[202:203], v[106:107], v[202:203] op_sel_hi:[1,0]
	v_pk_mul_f32 v[198:199], v[192:193], v[198:199]
	v_pk_mul_f32 v[200:201], v[194:195], v[200:201]
	s_waitcnt lgkmcnt(0)
	v_mul_f32_e32 v156, v158, v156
	v_cndmask_b32_e64 v156, v156, -v156, s[4:5]
	v_fmac_f32_e32 v156, v154, v222
	v_cndmask_b32_e32 v154, v222, v156, vcc
	ds_bpermute_b32 v156, v173, v223
	v_pk_mul_f32 v[202:203], v[188:189], v[202:203]
	v_pk_mul_f32 v[204:205], v[190:191], v[204:205]
	s_waitcnt lgkmcnt(0)
	v_mul_f32_e32 v156, v159, v156
	v_cndmask_b32_e64 v156, v156, -v156, s[4:5]
	v_fmac_f32_e32 v156, v155, v223
	v_cndmask_b32_e32 v155, v223, v156, vcc
	ds_bpermute_b32 v156, v173, v226
	s_waitcnt lgkmcnt(0)
	v_mul_f32_e32 v148, v148, v156
	v_cndmask_b32_e64 v148, v148, -v148, s[4:5]
	v_fmac_f32_e32 v148, v144, v226
	ds_bpermute_b32 v144, v173, v227
	v_cndmask_b32_e32 v156, v226, v148, vcc
	s_waitcnt lgkmcnt(0)
	v_mul_f32_e32 v144, v149, v144
	v_cndmask_b32_e64 v144, v144, -v144, s[4:5]
	v_fmac_f32_e32 v144, v145, v227
	v_cndmask_b32_e32 v157, v227, v144, vcc
	ds_bpermute_b32 v144, v173, v206
	s_waitcnt lgkmcnt(0)
	v_mul_f32_e32 v144, v150, v144
	v_cndmask_b32_e64 v144, v144, -v144, s[4:5]
	v_fmac_f32_e32 v144, v146, v206
	v_cndmask_b32_e32 v150, v206, v144, vcc
	ds_bpermute_b32 v144, v173, v207
	s_waitcnt lgkmcnt(0)
	v_mul_f32_e32 v144, v151, v144
	v_cndmask_b32_e64 v144, v144, -v144, s[4:5]
	v_fmac_f32_e32 v144, v147, v207
	v_cndmask_b32_e32 v147, v207, v144, vcc
	v_lshlrev_b64 v[144:145], s12, v[174:175]
	v_lshl_add_u64 v[148:149], v[144:145], 1, v[178:179]
	v_cvt_pk_bf16_f32 v144, v152, v153
	v_cvt_pk_bf16_f32 v145, v154, v155
	v_cvt_pk_bf16_f32 v146, v156, v157
	v_cvt_pk_bf16_f32 v147, v150, v147
	global_store_dwordx4 v[148:149], v[144:147], off sc1
	s_nop 1
	v_cvt_pk_bf16_f32 v144, v200, v201
	v_cvt_pk_bf16_f32 v145, v198, v199
	v_cvt_pk_bf16_f32 v146, v204, v205
	v_cvt_pk_bf16_f32 v147, v202, v203
	global_store_dwordx4 v[148:149], v[144:147], off offset:64 sc1
	s_nop 1
	v_pk_mul_f32 v[144:145], v[118:119], v[118:119]
	v_pk_mul_f32 v[146:147], v[116:117], v[116:117]
	s_nop 0
	v_pk_mov_b32 v[148:149], v[146:147], v[144:145] op_sel:[1,0]
	v_mov_b32_e32 v147, v145
	v_pk_add_f32 v[144:145], v[148:149], v[146:147]
	v_pk_mul_f32 v[146:147], v[110:111], v[110:111]
	v_pk_mul_f32 v[148:149], v[108:109], v[108:109]
	v_pk_add_f32 v[144:145], v[144:145], v[144:145] op_sel:[0,1] op_sel_hi:[1,0]
	v_pk_mov_b32 v[150:151], v[148:149], v[146:147] op_sel:[1,0]
	v_mov_b32_e32 v149, v147
	v_pk_add_f32 v[146:147], v[150:151], v[148:149]
	v_mul_f32_e32 v148, v88, v88
	v_mul_f32_e32 v149, v89, v89
	v_pk_add_f32 v[146:147], v[146:147], v[146:147] op_sel:[0,1] op_sel_hi:[1,0]
	v_mov_b32_e32 v145, v148
	v_mov_b32_e32 v147, v149
	v_pk_add_f32 v[144:145], v[144:145], v[146:147]
	v_mul_f32_e32 v146, v97, v97
	v_mul_f32_e32 v148, v99, v99
	v_mul_f32_e32 v150, v90, v90
	v_mul_f32_e32 v151, v91, v91
	v_pk_fma_f32 v[146:147], v[96:97], v[96:97], v[146:147] op_sel_hi:[1,1,0]
	v_pk_fma_f32 v[148:149], v[98:99], v[98:99], v[148:149] op_sel_hi:[1,1,0]
	v_mov_b32_e32 v147, v150
	v_mov_b32_e32 v149, v151
	v_pk_add_f32 v[146:147], v[146:147], v[148:149]
	s_nop 0
	v_pk_add_f32 v[144:145], v[144:145], v[146:147]
	s_nop 0
	v_add_f32_e32 v144, v144, v145
	ds_bpermute_b32 v145, v173, v144
	s_waitcnt lgkmcnt(0)
	v_add_f32_e32 v144, v144, v145
	ds_bpermute_b32 v145, v220, v144
	s_waitcnt lgkmcnt(0)
	v_add_f32_e32 v144, v144, v145
	v_fmamk_f32 v144, v144, 0x3c800000, v215
	v_rsq_f32_e32 v144, v144
	s_nop 0
	v_pk_mul_f32 v[146:147], v[116:117], v[144:145] op_sel_hi:[1,0]
	s_nop 0
	v_pk_mul_f32 v[156:157], v[186:187], v[146:147]
	ds_bpermute_b32 v175, v173, v156
	v_pk_mul_f32 v[148:149], v[118:119], v[144:145] op_sel_hi:[1,0]
	v_pk_mul_f32 v[146:147], v[108:109], v[144:145] op_sel_hi:[1,0]
	v_pk_mul_f32 v[154:155], v[184:185], v[148:149]
	v_pk_mul_f32 v[158:159], v[182:183], v[146:147]
	s_waitcnt vmcnt(2) lgkmcnt(0)
	v_mul_f32_e32 v140, v140, v175
	v_cndmask_b32_e64 v140, v140, -v140, s[4:5]
	v_fmac_f32_e32 v140, v136, v156
	v_cndmask_b32_e32 v136, v156, v140, vcc
	ds_bpermute_b32 v140, v173, v157
	v_pk_mul_f32 v[148:149], v[110:111], v[144:145] op_sel_hi:[1,0]
	v_pk_mul_f32 v[146:147], v[98:99], v[144:145] op_sel_hi:[1,0]
	v_pk_mul_f32 v[152:153], v[180:181], v[148:149]
	v_pk_mul_f32 v[148:149], v[96:97], v[144:145] op_sel_hi:[1,0]
	s_waitcnt lgkmcnt(0)
; __device__ __forceinline__ u32x4 pack8(const f32x4& a, const f32x4& b) { u32x4 w; w.x = cvt_pk_bf16(a[0], a[1]); w.y = cvt_pk_bf16(a[2], a[3]); w.z = cvt_pk_bf16(b[0], b[1]); w.w = cvt_pk_bf16(b[2], b[3]); return w; }
;     __device__ __forceinline__ void operator()(Acc& acc, const Unit& u, int wr, int wc, int fr, int fq) const {
;     ...
;                   for (int mh = 0; mh < 2; ++mh) {
;                     f32x4 rc[2][2], rs[2][2];
; #pragma unroll
;                     for (int m2 = 0; m2 < 2; ++m2) { const float* rp = rope + (size_t)(row0 + ai * HALF + (2 * mh + m2) * 16) * 16;
; #pragma unroll
;                         for (int n = 0; n < 2; ++n) { rc[m2][n] = *(const f32x4*)(rp + 4 * n); rs[m2][n] = *(const f32x4*)(rp + 8 + 4 * n); } }
;                     __builtin_amdgcn_sched_barrier(0);
; #pragma unroll
;                     for (int m2 = 0; m2 < 2; ++m2) { const int m = 2 * mh + m2;
;                         const int row = row0 + ai * HALF + m * 16;
;                         float ss = 0.f;
; #pragma unroll
;                         for (int bj = 0; bj < 2; ++bj)
; #pragma unroll
;                             for (int n = 0; n < 2; ++n) { const f32x4 v = acc[ai][bj][m][n]; ss += (v[0] * v[0] + v[1] * v[1]) + (v[2] * v[2] + v[3] * v[3]); }
;                         ss += __shfl_xor(ss, 16); ss += __shfl_xor(ss, 32);
;                         const float rstd = frsq(ss * (1.0f / 64.0f) + EPS);
;                         f32x4 y[2][2];
; #pragma unroll
;                         for (int bj = 0; bj < 2; ++bj)
; #pragma unroll
;                             for (int n = 0; n < 2; ++n) y[bj][n] = acc[ai][bj][m][n] * rstd * g[bj][n];
; #pragma unroll
;                         for (int n = 0; n < 2; ++n) {
;                             const f32x4 cs = rc[m2][n], sn = rs[m2][n];
;                             f32x4 o;
; #pragma unroll
;                             for (int i = 0; i < 4; ++i) { const float mine = y[0][n][i], oth = __shfl_xor(mine, 16);
;                                 const float r = (fq == 0) ? (mine * cs[i] - oth * sn[i]) : (mine * cs[i] + oth * sn[i]);
;                                 o[i] = (fq < 2) ? r : mine; }
;                             y[0][n] = o;
;                         }
; #pragma unroll
;                         for (int bj = 0; bj < 2; ++bj) *(u32x4*)(ob + (size_t)row * ld + bj * 32) = pack8(y[bj][0], y[bj][1]);
	v_mul_f32_e32 v140, v141, v140
	v_cndmask_b32_e64 v140, v140, -v140, s[4:5]
	v_fmac_f32_e32 v140, v137, v157
	v_cndmask_b32_e32 v137, v157, v140, vcc
	ds_bpermute_b32 v140, v173, v154
	v_pk_mul_f32 v[146:147], v[192:193], v[146:147]
	v_pk_mul_f32 v[150:151], v[194:195], v[148:149]
	v_pk_mul_f32 v[148:149], v[88:89], v[144:145] op_sel_hi:[1,0]
	v_pk_mul_f32 v[144:145], v[90:91], v[144:145] op_sel_hi:[1,0]
	s_waitcnt lgkmcnt(0)
	v_mul_f32_e32 v140, v142, v140
	v_cndmask_b32_e64 v140, v140, -v140, s[4:5]
	v_fmac_f32_e32 v140, v138, v154
	v_cndmask_b32_e32 v138, v154, v140, vcc
	ds_bpermute_b32 v140, v173, v155
	v_add_u32_e32 v154, 32, v174
	v_pk_mul_f32 v[144:145], v[188:189], v[144:145]
	v_pk_mul_f32 v[148:149], v[190:191], v[148:149]
	s_waitcnt lgkmcnt(0)
	v_mul_f32_e32 v140, v143, v140
	v_cndmask_b32_e64 v140, v140, -v140, s[4:5]
	v_fmac_f32_e32 v140, v139, v155
	v_cndmask_b32_e32 v139, v155, v140, vcc
	ds_bpermute_b32 v140, v173, v158
	v_ashrrev_i32_e32 v155, 31, v154
	s_waitcnt lgkmcnt(0)
	v_mul_f32_e32 v132, v132, v140
	v_cndmask_b32_e64 v132, v132, -v132, s[4:5]
	v_fmac_f32_e32 v132, v128, v158
	ds_bpermute_b32 v128, v173, v159
	v_cndmask_b32_e32 v140, v158, v132, vcc
	s_waitcnt lgkmcnt(0)
	v_mul_f32_e32 v128, v133, v128
	v_cndmask_b32_e64 v128, v128, -v128, s[4:5]
	v_fmac_f32_e32 v128, v129, v159
	v_cndmask_b32_e32 v141, v159, v128, vcc
	ds_bpermute_b32 v128, v173, v152
	s_waitcnt lgkmcnt(0)
	v_mul_f32_e32 v128, v134, v128
	v_cndmask_b32_e64 v128, v128, -v128, s[4:5]
	v_fmac_f32_e32 v128, v130, v152
	v_cndmask_b32_e32 v134, v152, v128, vcc
	ds_bpermute_b32 v128, v173, v153
	v_add_u32_e32 v152, 48, v174
	s_waitcnt lgkmcnt(0)
	v_mul_f32_e32 v128, v135, v128
	v_cndmask_b32_e64 v128, v128, -v128, s[4:5]
	v_fmac_f32_e32 v128, v131, v153
	v_cndmask_b32_e32 v131, v153, v128, vcc
	v_lshlrev_b64 v[128:129], s12, v[196:197]
	v_lshl_add_u64 v[132:133], v[128:129], 1, v[178:179]
	v_cvt_pk_bf16_f32 v128, v136, v137
	v_cvt_pk_bf16_f32 v129, v138, v139
	v_cvt_pk_bf16_f32 v130, v140, v141
	v_cvt_pk_bf16_f32 v131, v134, v131
	global_store_dwordx4 v[132:133], v[128:131], off sc1
	v_ashrrev_i32_e32 v153, 31, v152
	s_nop 0
	v_cvt_pk_bf16_f32 v128, v150, v151
	v_cvt_pk_bf16_f32 v129, v146, v147
	v_cvt_pk_bf16_f32 v130, v148, v149
	v_cvt_pk_bf16_f32 v131, v144, v145
	global_store_dwordx4 v[132:133], v[128:131], off offset:64 sc1
	s_nop 1
	v_lshlrev_b64 v[128:129], 6, v[154:155]
	v_lshl_add_u64 v[128:129], s[50:51], 0, v[128:129]
	global_load_dwordx4 v[144:147], v[128:129], off offset:16
	global_load_dwordx4 v[148:151], v[128:129], off offset:48
	global_load_dwordx4 v[202:205], v[128:129], off
	global_load_dwordx4 v[222:225], v[128:129], off offset:32
	v_lshlrev_b64 v[128:129], 6, v[152:153]
	v_lshl_add_u64 v[140:141], s[50:51], 0, v[128:129]
	global_load_dwordx4 v[128:131], v[140:141], off offset:16
	global_load_dwordx4 v[132:135], v[140:141], off offset:48
	global_load_dwordx4 v[136:139], v[140:141], off
	s_nop 0
	global_load_dwordx4 v[140:143], v[140:141], off offset:32
	v_pk_mul_f32 v[156:157], v[102:103], v[102:103]
	v_pk_mul_f32 v[158:159], v[100:101], v[100:101]
	v_mul_f32_e32 v175, v72, v72
	v_pk_mov_b32 v[196:197], v[158:159], v[156:157] op_sel:[1,0]
	v_mov_b32_e32 v159, v157
	v_pk_add_f32 v[156:157], v[196:197], v[158:159]
	v_pk_mul_f32 v[158:159], v[94:95], v[94:95]
	v_pk_mul_f32 v[196:197], v[92:93], v[92:93]
	v_pk_add_f32 v[156:157], v[156:157], v[156:157] op_sel:[0,1] op_sel_hi:[1,0]
	v_pk_mov_b32 v[198:199], v[196:197], v[158:159] op_sel:[1,0]
	v_mov_b32_e32 v197, v159
	v_pk_add_f32 v[158:159], v[198:199], v[196:197]
	v_mul_f32_e32 v196, v73, v73
	v_pk_add_f32 v[158:159], v[158:159], v[158:159] op_sel:[0,1] op_sel_hi:[1,0]
	v_mov_b32_e32 v157, v175
	v_mov_b32_e32 v159, v196
	v_pk_add_f32 v[156:157], v[156:157], v[158:159]
	v_mul_f32_e32 v158, v81, v81
	v_mul_f32_e32 v197, v74, v74
	v_pk_fma_f32 v[158:159], v[80:81], v[80:81], v[158:159] op_sel_hi:[1,1,0]
	v_mul_f32_e32 v196, v83, v83
	v_mul_f32_e32 v198, v75, v75
	v_mov_b32_e32 v159, v197
	v_pk_fma_f32 v[196:197], v[82:83], v[82:83], v[196:197] op_sel_hi:[1,1,0]
	s_nop 0
	v_mov_b32_e32 v197, v198
	v_pk_add_f32 v[158:159], v[158:159], v[196:197]
	s_nop 0
	v_pk_add_f32 v[156:157], v[156:157], v[158:159]
	s_nop 0
	v_add_f32_e32 v156, v156, v157
	ds_bpermute_b32 v157, v173, v156
	s_waitcnt lgkmcnt(0)
	v_add_f32_e32 v156, v156, v157
	ds_bpermute_b32 v157, v220, v156
	s_waitcnt lgkmcnt(0)
	v_add_f32_e32 v156, v156, v157
	v_fmamk_f32 v156, v156, 0x3c800000, v215
	v_rsq_f32_e32 v196, v156
	s_nop 0
	v_pk_mul_f32 v[156:157], v[100:101], v[196:197] op_sel_hi:[1,0]
	s_nop 0
	v_pk_mul_f32 v[226:227], v[186:187], v[156:157]
	ds_bpermute_b32 v175, v173, v226
	v_pk_mul_f32 v[158:159], v[102:103], v[196:197] op_sel_hi:[1,0]
	v_pk_mul_f32 v[156:157], v[92:93], v[196:197] op_sel_hi:[1,0]
	v_pk_mul_f32 v[206:207], v[184:185], v[158:159]
	v_pk_mul_f32 v[230:231], v[182:183], v[156:157]
	s_waitcnt vmcnt(4) lgkmcnt(0)
	v_mul_f32_e32 v175, v222, v175
	v_cndmask_b32_e64 v175, v175, -v175, s[4:5]
	v_fmac_f32_e32 v175, v202, v226
	ds_bpermute_b32 v202, v173, v227
	v_pk_mul_f32 v[158:159], v[94:95], v[196:197] op_sel_hi:[1,0]
	v_pk_mul_f32 v[156:157], v[82:83], v[196:197] op_sel_hi:[1,0]
	v_pk_mul_f32 v[200:201], v[180:181], v[158:159]
	v_pk_mul_f32 v[158:159], v[80:81], v[196:197] op_sel_hi:[1,0]
	s_waitcnt lgkmcnt(0)
	v_mul_f32_e32 v202, v223, v202
	v_cndmask_b32_e64 v202, v202, -v202, s[4:5]
	v_fmac_f32_e32 v202, v203, v227
	ds_bpermute_b32 v203, v173, v206
	v_pk_mul_f32 v[198:199], v[72:73], v[196:197] op_sel_hi:[1,0]
	v_pk_mul_f32 v[196:197], v[74:75], v[196:197] op_sel_hi:[1,0]
	v_cndmask_b32_e32 v175, v226, v175, vcc
	v_cndmask_b32_e32 v202, v227, v202, vcc
	s_waitcnt lgkmcnt(0)
; __device__ __forceinline__ u32x4 pack8(const f32x4& a, const f32x4& b) { u32x4 w; w.x = cvt_pk_bf16(a[0], a[1]); w.y = cvt_pk_bf16(a[2], a[3]); w.z = cvt_pk_bf16(b[0], b[1]); w.w = cvt_pk_bf16(b[2], b[3]); return w; }
; __device__ __forceinline__ float frsq(float x) { return __builtin_amdgcn_rsqf(x); }
;     __device__ __forceinline__ void operator()(Acc& acc, const Unit& u, int wr, int wc, int fr, int fq) const {
;     ...
;                     for (int m2 = 0; m2 < 2; ++m2) { const int m = 2 * mh + m2;
;                         const int row = row0 + ai * HALF + m * 16;
;                         float ss = 0.f;
; #pragma unroll
;                         for (int bj = 0; bj < 2; ++bj)
; #pragma unroll
;                             for (int n = 0; n < 2; ++n) { const f32x4 v = acc[ai][bj][m][n]; ss += (v[0] * v[0] + v[1] * v[1]) + (v[2] * v[2] + v[3] * v[3]); }
;                         ss += __shfl_xor(ss, 16); ss += __shfl_xor(ss, 32);
;                         const float rstd = frsq(ss * (1.0f / 64.0f) + EPS);
;                         f32x4 y[2][2];
; #pragma unroll
;                         for (int bj = 0; bj < 2; ++bj)
; #pragma unroll
;                             for (int n = 0; n < 2; ++n) y[bj][n] = acc[ai][bj][m][n] * rstd * g[bj][n];
; #pragma unroll
;                         for (int n = 0; n < 2; ++n) {
;                             const f32x4 cs = rc[m2][n], sn = rs[m2][n];
;                             f32x4 o;
; #pragma unroll
;                             for (int i = 0; i < 4; ++i) { const float mine = y[0][n][i], oth = __shfl_xor(mine, 16);
;                                 const float r = (fq == 0) ? (mine * cs[i] - oth * sn[i]) : (mine * cs[i] + oth * sn[i]);
;                                 o[i] = (fq < 2) ? r : mine; }
;                             y[0][n] = o;
;                         }
; #pragma unroll
;                         for (int bj = 0; bj < 2; ++bj) *(u32x4*)(ob + (size_t)row * ld + bj * 32) = pack8(y[bj][0], y[bj][1]);
	v_mul_f32_e32 v203, v224, v203
	v_cndmask_b32_e64 v203, v203, -v203, s[4:5]
	v_fmac_f32_e32 v203, v204, v206
	ds_bpermute_b32 v204, v173, v207
	v_cndmask_b32_e32 v203, v206, v203, vcc
	v_pk_mul_f32 v[156:157], v[192:193], v[156:157]
	v_pk_mul_f32 v[158:159], v[194:195], v[158:159]
	v_pk_mul_f32 v[196:197], v[188:189], v[196:197]
	s_waitcnt lgkmcnt(0)
	v_mul_f32_e32 v204, v225, v204
	v_cndmask_b32_e64 v204, v204, -v204, s[4:5]
	v_fmac_f32_e32 v204, v205, v207
	ds_bpermute_b32 v205, v173, v230
	v_cndmask_b32_e32 v204, v207, v204, vcc
	v_pk_mul_f32 v[198:199], v[190:191], v[198:199]
	s_waitcnt lgkmcnt(0)
	v_mul_f32_e32 v148, v148, v205
	v_cndmask_b32_e64 v148, v148, -v148, s[4:5]
	v_fmac_f32_e32 v148, v144, v230
	ds_bpermute_b32 v144, v173, v231
	v_cndmask_b32_e32 v205, v230, v148, vcc
	s_waitcnt lgkmcnt(0)
	v_mul_f32_e32 v144, v149, v144
	v_cndmask_b32_e64 v144, v144, -v144, s[4:5]
	v_fmac_f32_e32 v144, v145, v231
	v_cndmask_b32_e32 v206, v231, v144, vcc
	ds_bpermute_b32 v144, v173, v200
	s_waitcnt lgkmcnt(0)
	v_mul_f32_e32 v144, v150, v144
	v_cndmask_b32_e64 v144, v144, -v144, s[4:5]
	v_fmac_f32_e32 v144, v146, v200
	v_cndmask_b32_e32 v150, v200, v144, vcc
	ds_bpermute_b32 v144, v173, v201
	s_waitcnt lgkmcnt(0)
	v_mul_f32_e32 v144, v151, v144
	v_cndmask_b32_e64 v144, v144, -v144, s[4:5]
	v_fmac_f32_e32 v144, v147, v201
	v_cndmask_b32_e32 v147, v201, v144, vcc
	v_lshlrev_b64 v[144:145], s12, v[154:155]
	v_lshl_add_u64 v[148:149], v[144:145], 1, v[178:179]
	v_cvt_pk_bf16_f32 v144, v175, v202
	v_cvt_pk_bf16_f32 v145, v203, v204
	v_cvt_pk_bf16_f32 v146, v205, v206
	v_cvt_pk_bf16_f32 v147, v150, v147
	global_store_dwordx4 v[148:149], v[144:147], off sc1
	s_nop 1
	v_cvt_pk_bf16_f32 v144, v158, v159
	v_cvt_pk_bf16_f32 v145, v156, v157
	v_cvt_pk_bf16_f32 v146, v198, v199
	v_cvt_pk_bf16_f32 v147, v196, v197
	global_store_dwordx4 v[148:149], v[144:147], off offset:64 sc1
	s_nop 1
	v_pk_mul_f32 v[144:145], v[86:87], v[86:87]
	v_pk_mul_f32 v[146:147], v[84:85], v[84:85]
	s_nop 0
	v_pk_mov_b32 v[148:149], v[146:147], v[144:145] op_sel:[1,0]
	v_mov_b32_e32 v147, v145
	v_pk_add_f32 v[144:145], v[148:149], v[146:147]
	v_pk_mul_f32 v[146:147], v[78:79], v[78:79]
	v_pk_mul_f32 v[148:149], v[76:77], v[76:77]
	v_pk_add_f32 v[144:145], v[144:145], v[144:145] op_sel:[0,1] op_sel_hi:[1,0]
	v_pk_mov_b32 v[150:151], v[148:149], v[146:147] op_sel:[1,0]
	v_mov_b32_e32 v149, v147
	v_pk_add_f32 v[146:147], v[150:151], v[148:149]
	v_mul_f32_e32 v148, v64, v64
	v_mul_f32_e32 v149, v65, v65
	v_pk_add_f32 v[146:147], v[146:147], v[146:147] op_sel:[0,1] op_sel_hi:[1,0]
	v_mov_b32_e32 v145, v148
	v_mov_b32_e32 v147, v149
	v_pk_add_f32 v[144:145], v[144:145], v[146:147]
	v_mul_f32_e32 v146, v69, v69
	v_mul_f32_e32 v148, v71, v71
	v_mul_f32_e32 v150, v66, v66
	v_mul_f32_e32 v151, v67, v67
	v_pk_fma_f32 v[146:147], v[68:69], v[68:69], v[146:147] op_sel_hi:[1,1,0]
	v_pk_fma_f32 v[148:149], v[70:71], v[70:71], v[148:149] op_sel_hi:[1,1,0]
	v_mov_b32_e32 v147, v150
	v_mov_b32_e32 v149, v151
	v_pk_add_f32 v[146:147], v[146:147], v[148:149]
	s_nop 0
	v_pk_add_f32 v[144:145], v[144:145], v[146:147]
	s_nop 0
	v_add_f32_e32 v144, v144, v145
	ds_bpermute_b32 v145, v173, v144
	s_waitcnt lgkmcnt(0)
	v_add_f32_e32 v144, v144, v145
	ds_bpermute_b32 v145, v220, v144
	s_waitcnt lgkmcnt(0)
	v_add_f32_e32 v144, v144, v145
	v_fmamk_f32 v144, v144, 0x3c800000, v215
	v_rsq_f32_e32 v144, v144
	s_nop 0
	v_pk_mul_f32 v[146:147], v[84:85], v[144:145] op_sel_hi:[1,0]
	s_nop 0
	v_pk_mul_f32 v[158:159], v[186:187], v[146:147]
	ds_bpermute_b32 v175, v173, v158
	v_pk_mul_f32 v[148:149], v[86:87], v[144:145] op_sel_hi:[1,0]
	v_pk_mul_f32 v[146:147], v[76:77], v[144:145] op_sel_hi:[1,0]
	v_pk_mul_f32 v[156:157], v[184:185], v[148:149]
	v_pk_mul_f32 v[196:197], v[182:183], v[146:147]
	s_waitcnt vmcnt(2) lgkmcnt(0)
	v_mul_f32_e32 v140, v140, v175
	v_cndmask_b32_e64 v140, v140, -v140, s[4:5]
	v_fmac_f32_e32 v140, v136, v158
	v_cndmask_b32_e32 v136, v158, v140, vcc
	ds_bpermute_b32 v140, v173, v159
	v_pk_mul_f32 v[148:149], v[78:79], v[144:145] op_sel_hi:[1,0]
	v_pk_mul_f32 v[146:147], v[70:71], v[144:145] op_sel_hi:[1,0]
	v_pk_mul_f32 v[154:155], v[180:181], v[148:149]
	v_pk_mul_f32 v[148:149], v[68:69], v[144:145] op_sel_hi:[1,0]
	s_waitcnt lgkmcnt(0)
	v_mul_f32_e32 v140, v141, v140
	v_cndmask_b32_e64 v140, v140, -v140, s[4:5]
	v_fmac_f32_e32 v140, v137, v159
	v_cndmask_b32_e32 v137, v159, v140, vcc
	ds_bpermute_b32 v140, v173, v156
	v_pk_mul_f32 v[146:147], v[192:193], v[146:147]
	v_pk_mul_f32 v[150:151], v[194:195], v[148:149]
	v_pk_mul_f32 v[148:149], v[64:65], v[144:145] op_sel_hi:[1,0]
	v_pk_mul_f32 v[144:145], v[66:67], v[144:145] op_sel_hi:[1,0]
	s_waitcnt lgkmcnt(0)
	v_mul_f32_e32 v140, v142, v140
	v_cndmask_b32_e64 v140, v140, -v140, s[4:5]
	v_fmac_f32_e32 v140, v138, v156
	v_cndmask_b32_e32 v138, v156, v140, vcc
	ds_bpermute_b32 v140, v173, v157
	v_pk_mul_f32 v[144:145], v[188:189], v[144:145]
	v_pk_mul_f32 v[148:149], v[190:191], v[148:149]
	s_waitcnt lgkmcnt(0)
	v_mul_f32_e32 v140, v143, v140
	v_cndmask_b32_e64 v140, v140, -v140, s[4:5]
	v_fmac_f32_e32 v140, v139, v157
	v_cndmask_b32_e32 v139, v157, v140, vcc
	ds_bpermute_b32 v140, v173, v196
	s_waitcnt lgkmcnt(0)
	v_mul_f32_e32 v132, v132, v140
	v_cndmask_b32_e64 v132, v132, -v132, s[4:5]
	v_fmac_f32_e32 v132, v128, v196
	ds_bpermute_b32 v128, v173, v197
	v_cndmask_b32_e32 v140, v196, v132, vcc
	s_waitcnt lgkmcnt(0)
	v_mul_f32_e32 v128, v133, v128
	v_cndmask_b32_e64 v128, v128, -v128, s[4:5]
	v_fmac_f32_e32 v128, v129, v197
	v_cndmask_b32_e32 v141, v197, v128, vcc
	ds_bpermute_b32 v128, v173, v154
	s_waitcnt lgkmcnt(0)
; __device__ __forceinline__ u32x4 pack8(const f32x4& a, const f32x4& b) { u32x4 w; w.x = cvt_pk_bf16(a[0], a[1]); w.y = cvt_pk_bf16(a[2], a[3]); w.z = cvt_pk_bf16(b[0], b[1]); w.w = cvt_pk_bf16(b[2], b[3]); return w; }
;     __device__ __forceinline__ void operator()(Acc& acc, const Unit& u, int wr, int wc, int fr, int fq) const {
;     ...
;                   for (int mh = 0; mh < 2; ++mh) {
;                     f32x4 rc[2][2], rs[2][2];
; #pragma unroll
;                     for (int m2 = 0; m2 < 2; ++m2) { const float* rp = rope + (size_t)(row0 + ai * HALF + (2 * mh + m2) * 16) * 16;
; #pragma unroll
;                         for (int n = 0; n < 2; ++n) { rc[m2][n] = *(const f32x4*)(rp + 4 * n); rs[m2][n] = *(const f32x4*)(rp + 8 + 4 * n); } }
;                     __builtin_amdgcn_sched_barrier(0);
; #pragma unroll
;                     for (int m2 = 0; m2 < 2; ++m2) { const int m = 2 * mh + m2;
;                         const int row = row0 + ai * HALF + m * 16;
;                         float ss = 0.f;
; #pragma unroll
;                         for (int bj = 0; bj < 2; ++bj)
; #pragma unroll
;                             for (int n = 0; n < 2; ++n) { const f32x4 v = acc[ai][bj][m][n]; ss += (v[0] * v[0] + v[1] * v[1]) + (v[2] * v[2] + v[3] * v[3]); }
;                         ss += __shfl_xor(ss, 16); ss += __shfl_xor(ss, 32);
;                         const float rstd = frsq(ss * (1.0f / 64.0f) + EPS);
;                         f32x4 y[2][2];
; #pragma unroll
;                         for (int bj = 0; bj < 2; ++bj)
; #pragma unroll
;                             for (int n = 0; n < 2; ++n) y[bj][n] = acc[ai][bj][m][n] * rstd * g[bj][n];
; #pragma unroll
;                         for (int n = 0; n < 2; ++n) {
;                             const f32x4 cs = rc[m2][n], sn = rs[m2][n];
;                             f32x4 o;
; #pragma unroll
;                             for (int i = 0; i < 4; ++i) { const float mine = y[0][n][i], oth = __shfl_xor(mine, 16);
;                                 const float r = (fq == 0) ? (mine * cs[i] - oth * sn[i]) : (mine * cs[i] + oth * sn[i]);
;                                 o[i] = (fq < 2) ? r : mine; }
;                             y[0][n] = o;
;                         }
; #pragma unroll
;                         for (int bj = 0; bj < 2; ++bj) *(u32x4*)(ob + (size_t)row * ld + bj * 32) = pack8(y[bj][0], y[bj][1]);
	v_mul_f32_e32 v128, v134, v128
	v_cndmask_b32_e64 v128, v128, -v128, s[4:5]
	v_fmac_f32_e32 v128, v130, v154
	v_cndmask_b32_e32 v134, v154, v128, vcc
	ds_bpermute_b32 v128, v173, v155
	v_add_u32_e32 v154, 0x80, v174
	s_waitcnt lgkmcnt(0)
	v_mul_f32_e32 v128, v135, v128
	v_cndmask_b32_e64 v128, v128, -v128, s[4:5]
	v_fmac_f32_e32 v128, v131, v155
	v_cndmask_b32_e32 v131, v155, v128, vcc
	v_lshlrev_b64 v[128:129], s12, v[152:153]
	v_lshl_add_u64 v[132:133], v[128:129], 1, v[178:179]
	v_cvt_pk_bf16_f32 v128, v136, v137
	v_cvt_pk_bf16_f32 v129, v138, v139
	v_cvt_pk_bf16_f32 v130, v140, v141
	v_cvt_pk_bf16_f32 v131, v134, v131
	global_store_dwordx4 v[132:133], v[128:131], off sc1
	v_ashrrev_i32_e32 v155, 31, v154
	v_add_u32_e32 v152, 0x90, v174
	v_cvt_pk_bf16_f32 v128, v150, v151
	v_cvt_pk_bf16_f32 v129, v146, v147
	v_cvt_pk_bf16_f32 v130, v148, v149
	v_cvt_pk_bf16_f32 v131, v144, v145
	global_store_dwordx4 v[132:133], v[128:131], off offset:64 sc1
	v_ashrrev_i32_e32 v153, 31, v152
	s_nop 0
	v_lshlrev_b64 v[128:129], 6, v[154:155]
	v_lshl_add_u64 v[128:129], s[50:51], 0, v[128:129]
	global_load_dwordx4 v[144:147], v[128:129], off offset:16
	global_load_dwordx4 v[148:151], v[128:129], off offset:48
	global_load_dwordx4 v[202:205], v[128:129], off
	global_load_dwordx4 v[222:225], v[128:129], off offset:32
	v_lshlrev_b64 v[128:129], 6, v[152:153]
	v_lshl_add_u64 v[140:141], s[50:51], 0, v[128:129]
	global_load_dwordx4 v[128:131], v[140:141], off offset:16
	global_load_dwordx4 v[132:135], v[140:141], off offset:48
	global_load_dwordx4 v[136:139], v[140:141], off
	s_nop 0
	global_load_dwordx4 v[140:143], v[140:141], off offset:32
	v_pk_mul_f32 v[156:157], v[62:63], v[62:63]
	v_pk_mul_f32 v[158:159], v[60:61], v[60:61]
	v_mul_f32_e32 v175, v40, v40
	v_pk_mov_b32 v[196:197], v[158:159], v[156:157] op_sel:[1,0]
	v_mov_b32_e32 v159, v157
	v_pk_add_f32 v[156:157], v[196:197], v[158:159]
	v_pk_mul_f32 v[158:159], v[58:59], v[58:59]
	v_pk_mul_f32 v[196:197], v[56:57], v[56:57]
	v_pk_add_f32 v[156:157], v[156:157], v[156:157] op_sel:[0,1] op_sel_hi:[1,0]
	v_pk_mov_b32 v[198:199], v[196:197], v[158:159] op_sel:[1,0]
	v_mov_b32_e32 v197, v159
	v_pk_add_f32 v[158:159], v[198:199], v[196:197]
	v_mul_f32_e32 v196, v41, v41
	v_pk_add_f32 v[158:159], v[158:159], v[158:159] op_sel:[0,1] op_sel_hi:[1,0]
	v_mov_b32_e32 v157, v175
	v_mov_b32_e32 v159, v196
	v_pk_add_f32 v[156:157], v[156:157], v[158:159]
	v_mul_f32_e32 v158, v49, v49
	v_mul_f32_e32 v197, v42, v42
	v_pk_fma_f32 v[158:159], v[48:49], v[48:49], v[158:159] op_sel_hi:[1,1,0]
	v_mul_f32_e32 v196, v51, v51
	v_mul_f32_e32 v198, v43, v43
	v_mov_b32_e32 v159, v197
	v_pk_fma_f32 v[196:197], v[50:51], v[50:51], v[196:197] op_sel_hi:[1,1,0]
	s_nop 0
	v_mov_b32_e32 v197, v198
	v_pk_add_f32 v[158:159], v[158:159], v[196:197]
	s_nop 0
	v_pk_add_f32 v[156:157], v[156:157], v[158:159]
	s_nop 0
	v_add_f32_e32 v156, v156, v157
	ds_bpermute_b32 v157, v173, v156
	s_waitcnt lgkmcnt(0)
	v_add_f32_e32 v156, v156, v157
	ds_bpermute_b32 v157, v220, v156
	s_waitcnt lgkmcnt(0)
	v_add_f32_e32 v156, v156, v157
	v_fmamk_f32 v156, v156, 0x3c800000, v215
	v_rsq_f32_e32 v196, v156
	s_nop 0
	v_pk_mul_f32 v[156:157], v[60:61], v[196:197] op_sel_hi:[1,0]
	s_nop 0
	v_pk_mul_f32 v[226:227], v[186:187], v[156:157]
	ds_bpermute_b32 v175, v173, v226
	v_pk_mul_f32 v[158:159], v[62:63], v[196:197] op_sel_hi:[1,0]
	v_pk_mul_f32 v[156:157], v[56:57], v[196:197] op_sel_hi:[1,0]
	v_pk_mul_f32 v[206:207], v[184:185], v[158:159]
	v_pk_mul_f32 v[230:231], v[182:183], v[156:157]
	s_waitcnt vmcnt(4) lgkmcnt(0)
	v_mul_f32_e32 v175, v222, v175
	v_cndmask_b32_e64 v175, v175, -v175, s[4:5]
	v_fmac_f32_e32 v175, v202, v226
	ds_bpermute_b32 v202, v173, v227
	v_pk_mul_f32 v[158:159], v[58:59], v[196:197] op_sel_hi:[1,0]
	v_pk_mul_f32 v[156:157], v[50:51], v[196:197] op_sel_hi:[1,0]
	v_pk_mul_f32 v[200:201], v[180:181], v[158:159]
	v_pk_mul_f32 v[158:159], v[48:49], v[196:197] op_sel_hi:[1,0]
	s_waitcnt lgkmcnt(0)
	v_mul_f32_e32 v202, v223, v202
	v_cndmask_b32_e64 v202, v202, -v202, s[4:5]
	v_fmac_f32_e32 v202, v203, v227
	ds_bpermute_b32 v203, v173, v206
	v_pk_mul_f32 v[198:199], v[40:41], v[196:197] op_sel_hi:[1,0]
	v_pk_mul_f32 v[196:197], v[42:43], v[196:197] op_sel_hi:[1,0]
	v_cndmask_b32_e32 v175, v226, v175, vcc
	v_cndmask_b32_e32 v202, v227, v202, vcc
	s_waitcnt lgkmcnt(0)
	v_mul_f32_e32 v203, v224, v203
	v_cndmask_b32_e64 v203, v203, -v203, s[4:5]
	v_fmac_f32_e32 v203, v204, v206
	ds_bpermute_b32 v204, v173, v207
	v_cndmask_b32_e32 v203, v206, v203, vcc
	v_pk_mul_f32 v[156:157], v[192:193], v[156:157]
	v_pk_mul_f32 v[158:159], v[194:195], v[158:159]
	v_pk_mul_f32 v[196:197], v[188:189], v[196:197]
	s_waitcnt lgkmcnt(0)
	v_mul_f32_e32 v204, v225, v204
	v_cndmask_b32_e64 v204, v204, -v204, s[4:5]
	v_fmac_f32_e32 v204, v205, v207
	ds_bpermute_b32 v205, v173, v230
	v_cndmask_b32_e32 v204, v207, v204, vcc
	v_pk_mul_f32 v[198:199], v[190:191], v[198:199]
	s_waitcnt lgkmcnt(0)
	v_mul_f32_e32 v148, v148, v205
	v_cndmask_b32_e64 v148, v148, -v148, s[4:5]
	v_fmac_f32_e32 v148, v144, v230
	ds_bpermute_b32 v144, v173, v231
	v_cndmask_b32_e32 v205, v230, v148, vcc
	s_waitcnt lgkmcnt(0)
	v_mul_f32_e32 v144, v149, v144
	v_cndmask_b32_e64 v144, v144, -v144, s[4:5]
	v_fmac_f32_e32 v144, v145, v231
	v_cndmask_b32_e32 v206, v231, v144, vcc
	ds_bpermute_b32 v144, v173, v200
	s_waitcnt lgkmcnt(0)
	v_mul_f32_e32 v144, v150, v144
	v_cndmask_b32_e64 v144, v144, -v144, s[4:5]
	v_fmac_f32_e32 v144, v146, v200
	v_cndmask_b32_e32 v150, v200, v144, vcc
	ds_bpermute_b32 v144, v173, v201
	s_waitcnt lgkmcnt(0)
; __device__ __forceinline__ u32x4 pack8(const f32x4& a, const f32x4& b) { u32x4 w; w.x = cvt_pk_bf16(a[0], a[1]); w.y = cvt_pk_bf16(a[2], a[3]); w.z = cvt_pk_bf16(b[0], b[1]); w.w = cvt_pk_bf16(b[2], b[3]); return w; }
; __device__ __forceinline__ float frsq(float x) { return __builtin_amdgcn_rsqf(x); }
;     __device__ __forceinline__ void operator()(Acc& acc, const Unit& u, int wr, int wc, int fr, int fq) const {
;     ...
;                     for (int m2 = 0; m2 < 2; ++m2) { const int m = 2 * mh + m2;
;                         const int row = row0 + ai * HALF + m * 16;
;                         float ss = 0.f;
; #pragma unroll
;                         for (int bj = 0; bj < 2; ++bj)
; #pragma unroll
;                             for (int n = 0; n < 2; ++n) { const f32x4 v = acc[ai][bj][m][n]; ss += (v[0] * v[0] + v[1] * v[1]) + (v[2] * v[2] + v[3] * v[3]); }
;                         ss += __shfl_xor(ss, 16); ss += __shfl_xor(ss, 32);
;                         const float rstd = frsq(ss * (1.0f / 64.0f) + EPS);
;                         f32x4 y[2][2];
; #pragma unroll
;                         for (int bj = 0; bj < 2; ++bj)
; #pragma unroll
;                             for (int n = 0; n < 2; ++n) y[bj][n] = acc[ai][bj][m][n] * rstd * g[bj][n];
; #pragma unroll
;                         for (int n = 0; n < 2; ++n) {
;                             const f32x4 cs = rc[m2][n], sn = rs[m2][n];
;                             f32x4 o;
; #pragma unroll
;                             for (int i = 0; i < 4; ++i) { const float mine = y[0][n][i], oth = __shfl_xor(mine, 16);
;                                 const float r = (fq == 0) ? (mine * cs[i] - oth * sn[i]) : (mine * cs[i] + oth * sn[i]);
;                                 o[i] = (fq < 2) ? r : mine; }
;                             y[0][n] = o;
;                         }
; #pragma unroll
;                         for (int bj = 0; bj < 2; ++bj) *(u32x4*)(ob + (size_t)row * ld + bj * 32) = pack8(y[bj][0], y[bj][1]);
	v_mul_f32_e32 v144, v151, v144
	v_cndmask_b32_e64 v144, v144, -v144, s[4:5]
	v_fmac_f32_e32 v144, v147, v201
	v_cndmask_b32_e32 v147, v201, v144, vcc
	v_lshlrev_b64 v[144:145], s12, v[154:155]
	v_lshl_add_u64 v[148:149], v[144:145], 1, v[178:179]
	v_cvt_pk_bf16_f32 v144, v175, v202
	v_cvt_pk_bf16_f32 v145, v203, v204
	v_cvt_pk_bf16_f32 v146, v205, v206
	v_cvt_pk_bf16_f32 v147, v150, v147
	global_store_dwordx4 v[148:149], v[144:147], off sc1
	s_nop 1
	v_cvt_pk_bf16_f32 v144, v158, v159
	v_cvt_pk_bf16_f32 v145, v156, v157
	v_cvt_pk_bf16_f32 v146, v198, v199
	v_cvt_pk_bf16_f32 v147, v196, v197
	global_store_dwordx4 v[148:149], v[144:147], off offset:64 sc1
	s_nop 1
	v_pk_mul_f32 v[144:145], v[54:55], v[54:55]
	v_pk_mul_f32 v[146:147], v[52:53], v[52:53]
	s_nop 0
	v_pk_mov_b32 v[148:149], v[146:147], v[144:145] op_sel:[1,0]
	v_mov_b32_e32 v147, v145
	v_pk_add_f32 v[144:145], v[148:149], v[146:147]
	v_pk_mul_f32 v[146:147], v[46:47], v[46:47]
	v_pk_mul_f32 v[148:149], v[44:45], v[44:45]
	v_pk_add_f32 v[144:145], v[144:145], v[144:145] op_sel:[0,1] op_sel_hi:[1,0]
	v_pk_mov_b32 v[150:151], v[148:149], v[146:147] op_sel:[1,0]
	v_mov_b32_e32 v149, v147
	v_pk_add_f32 v[146:147], v[150:151], v[148:149]
	v_mul_f32_e32 v148, v24, v24
	v_mul_f32_e32 v149, v25, v25
	v_pk_add_f32 v[146:147], v[146:147], v[146:147] op_sel:[0,1] op_sel_hi:[1,0]
	v_mov_b32_e32 v145, v148
	v_mov_b32_e32 v147, v149
	v_pk_add_f32 v[144:145], v[144:145], v[146:147]
	v_mul_f32_e32 v146, v33, v33
	v_mul_f32_e32 v148, v35, v35
	v_mul_f32_e32 v150, v26, v26
	v_mul_f32_e32 v151, v27, v27
	v_pk_fma_f32 v[146:147], v[32:33], v[32:33], v[146:147] op_sel_hi:[1,1,0]
	v_pk_fma_f32 v[148:149], v[34:35], v[34:35], v[148:149] op_sel_hi:[1,1,0]
	v_mov_b32_e32 v147, v150
	v_mov_b32_e32 v149, v151
	v_pk_add_f32 v[146:147], v[146:147], v[148:149]
	s_nop 0
	v_pk_add_f32 v[144:145], v[144:145], v[146:147]
	s_nop 0
	v_add_f32_e32 v144, v144, v145
	ds_bpermute_b32 v145, v173, v144
	s_waitcnt lgkmcnt(0)
	v_add_f32_e32 v144, v144, v145
	ds_bpermute_b32 v145, v220, v144
	s_waitcnt lgkmcnt(0)
	v_add_f32_e32 v144, v144, v145
	v_fmamk_f32 v144, v144, 0x3c800000, v215
	v_rsq_f32_e32 v144, v144
	s_nop 0
	v_pk_mul_f32 v[146:147], v[52:53], v[144:145] op_sel_hi:[1,0]
	s_nop 0
	v_pk_mul_f32 v[158:159], v[186:187], v[146:147]
	ds_bpermute_b32 v175, v173, v158
	v_pk_mul_f32 v[148:149], v[54:55], v[144:145] op_sel_hi:[1,0]
	v_pk_mul_f32 v[146:147], v[44:45], v[144:145] op_sel_hi:[1,0]
	v_pk_mul_f32 v[156:157], v[184:185], v[148:149]
	v_pk_mul_f32 v[196:197], v[182:183], v[146:147]
	s_waitcnt vmcnt(2) lgkmcnt(0)
	v_mul_f32_e32 v140, v140, v175
	v_cndmask_b32_e64 v140, v140, -v140, s[4:5]
	v_fmac_f32_e32 v140, v136, v158
	v_cndmask_b32_e32 v136, v158, v140, vcc
	ds_bpermute_b32 v140, v173, v159
	v_pk_mul_f32 v[148:149], v[46:47], v[144:145] op_sel_hi:[1,0]
	v_pk_mul_f32 v[146:147], v[34:35], v[144:145] op_sel_hi:[1,0]
	v_pk_mul_f32 v[154:155], v[180:181], v[148:149]
	v_pk_mul_f32 v[148:149], v[32:33], v[144:145] op_sel_hi:[1,0]
	s_waitcnt lgkmcnt(0)
	v_mul_f32_e32 v140, v141, v140
	v_cndmask_b32_e64 v140, v140, -v140, s[4:5]
	v_fmac_f32_e32 v140, v137, v159
	v_cndmask_b32_e32 v137, v159, v140, vcc
	ds_bpermute_b32 v140, v173, v156
	v_pk_mul_f32 v[146:147], v[192:193], v[146:147]
	v_pk_mul_f32 v[150:151], v[194:195], v[148:149]
	v_pk_mul_f32 v[148:149], v[24:25], v[144:145] op_sel_hi:[1,0]
	v_pk_mul_f32 v[144:145], v[26:27], v[144:145] op_sel_hi:[1,0]
	s_waitcnt lgkmcnt(0)
	v_mul_f32_e32 v140, v142, v140
	v_cndmask_b32_e64 v140, v140, -v140, s[4:5]
	v_fmac_f32_e32 v140, v138, v156
	v_cndmask_b32_e32 v138, v156, v140, vcc
	ds_bpermute_b32 v140, v173, v157
	v_pk_mul_f32 v[144:145], v[188:189], v[144:145]
	v_pk_mul_f32 v[148:149], v[190:191], v[148:149]
	s_waitcnt lgkmcnt(0)
	v_mul_f32_e32 v140, v143, v140
	v_cndmask_b32_e64 v140, v140, -v140, s[4:5]
	v_fmac_f32_e32 v140, v139, v157
	v_cndmask_b32_e32 v139, v157, v140, vcc
	ds_bpermute_b32 v140, v173, v196
	s_waitcnt lgkmcnt(0)
	v_mul_f32_e32 v132, v132, v140
	v_cndmask_b32_e64 v132, v132, -v132, s[4:5]
	v_fmac_f32_e32 v132, v128, v196
	ds_bpermute_b32 v128, v173, v197
	v_cndmask_b32_e32 v140, v196, v132, vcc
	s_waitcnt lgkmcnt(0)
	v_mul_f32_e32 v128, v133, v128
	v_cndmask_b32_e64 v128, v128, -v128, s[4:5]
	v_fmac_f32_e32 v128, v129, v197
	v_cndmask_b32_e32 v141, v197, v128, vcc
	ds_bpermute_b32 v128, v173, v154
	s_waitcnt lgkmcnt(0)
	v_mul_f32_e32 v128, v134, v128
	v_cndmask_b32_e64 v128, v128, -v128, s[4:5]
	v_fmac_f32_e32 v128, v130, v154
	v_cndmask_b32_e32 v134, v154, v128, vcc
	ds_bpermute_b32 v128, v173, v155
	v_add_u32_e32 v154, 0xa0, v174
	s_waitcnt lgkmcnt(0)
; __device__ __forceinline__ u32x4 pack8(const f32x4& a, const f32x4& b) { u32x4 w; w.x = cvt_pk_bf16(a[0], a[1]); w.y = cvt_pk_bf16(a[2], a[3]); w.z = cvt_pk_bf16(b[0], b[1]); w.w = cvt_pk_bf16(b[2], b[3]); return w; }
; __device__ __forceinline__ float frsq(float x) { return __builtin_amdgcn_rsqf(x); }
;     __device__ __forceinline__ void operator()(Acc& acc, const Unit& u, int wr, int wc, int fr, int fq) const {
;     ...
;                     for (int m2 = 0; m2 < 2; ++m2) { const float* rp = rope + (size_t)(row0 + ai * HALF + (2 * mh + m2) * 16) * 16;
; #pragma unroll
;                         for (int n = 0; n < 2; ++n) { rc[m2][n] = *(const f32x4*)(rp + 4 * n); rs[m2][n] = *(const f32x4*)(rp + 8 + 4 * n); } }
;                     __builtin_amdgcn_sched_barrier(0);
; #pragma unroll
;                     for (int m2 = 0; m2 < 2; ++m2) { const int m = 2 * mh + m2;
;                         const int row = row0 + ai * HALF + m * 16;
;                         float ss = 0.f;
; #pragma unroll
;                         for (int bj = 0; bj < 2; ++bj)
; #pragma unroll
;                             for (int n = 0; n < 2; ++n) { const f32x4 v = acc[ai][bj][m][n]; ss += (v[0] * v[0] + v[1] * v[1]) + (v[2] * v[2] + v[3] * v[3]); }
;                         ss += __shfl_xor(ss, 16); ss += __shfl_xor(ss, 32);
;                         const float rstd = frsq(ss * (1.0f / 64.0f) + EPS);
;                         f32x4 y[2][2];
; #pragma unroll
;                         for (int bj = 0; bj < 2; ++bj)
; #pragma unroll
;                             for (int n = 0; n < 2; ++n) y[bj][n] = acc[ai][bj][m][n] * rstd * g[bj][n];
; #pragma unroll
;                         for (int n = 0; n < 2; ++n) {
;                             const f32x4 cs = rc[m2][n], sn = rs[m2][n];
;                             f32x4 o;
; #pragma unroll
;                             for (int i = 0; i < 4; ++i) { const float mine = y[0][n][i], oth = __shfl_xor(mine, 16);
;                                 const float r = (fq == 0) ? (mine * cs[i] - oth * sn[i]) : (mine * cs[i] + oth * sn[i]);
;                                 o[i] = (fq < 2) ? r : mine; }
;                             y[0][n] = o;
;                         }
; #pragma unroll
;                         for (int bj = 0; bj < 2; ++bj) *(u32x4*)(ob + (size_t)row * ld + bj * 32) = pack8(y[bj][0], y[bj][1]);
	v_mul_f32_e32 v128, v135, v128
	v_cndmask_b32_e64 v128, v128, -v128, s[4:5]
	v_fmac_f32_e32 v128, v131, v155
	v_cndmask_b32_e32 v131, v155, v128, vcc
	v_lshlrev_b64 v[128:129], s12, v[152:153]
	v_lshl_add_u64 v[132:133], v[128:129], 1, v[178:179]
	v_cvt_pk_bf16_f32 v128, v136, v137
	v_cvt_pk_bf16_f32 v129, v138, v139
	v_cvt_pk_bf16_f32 v130, v140, v141
	v_cvt_pk_bf16_f32 v131, v134, v131
	global_store_dwordx4 v[132:133], v[128:131], off sc1
	v_ashrrev_i32_e32 v155, 31, v154
	v_add_u32_e32 v152, 0xb0, v174
	v_cvt_pk_bf16_f32 v128, v150, v151
	v_cvt_pk_bf16_f32 v129, v146, v147
	v_cvt_pk_bf16_f32 v130, v148, v149
	v_cvt_pk_bf16_f32 v131, v144, v145
	global_store_dwordx4 v[132:133], v[128:131], off offset:64 sc1
	v_ashrrev_i32_e32 v153, 31, v152
	s_nop 0
	v_lshlrev_b64 v[128:129], 6, v[154:155]
	v_lshl_add_u64 v[128:129], s[50:51], 0, v[128:129]
	global_load_dwordx4 v[144:147], v[128:129], off offset:16
	global_load_dwordx4 v[148:151], v[128:129], off offset:48
	global_load_dwordx4 v[202:205], v[128:129], off
	global_load_dwordx4 v[222:225], v[128:129], off offset:32
	v_lshlrev_b64 v[128:129], 6, v[152:153]
	v_lshl_add_u64 v[140:141], s[50:51], 0, v[128:129]
	global_load_dwordx4 v[128:131], v[140:141], off offset:16
	global_load_dwordx4 v[132:135], v[140:141], off offset:48
	global_load_dwordx4 v[136:139], v[140:141], off
	s_nop 0
	global_load_dwordx4 v[140:143], v[140:141], off offset:32
	v_pk_mul_f32 v[156:157], v[38:39], v[38:39]
	v_pk_mul_f32 v[158:159], v[36:37], v[36:37]
	v_mul_f32_e32 v175, v8, v8
	v_pk_mov_b32 v[196:197], v[158:159], v[156:157] op_sel:[1,0]
	v_mov_b32_e32 v159, v157
	v_pk_add_f32 v[156:157], v[196:197], v[158:159]
	v_pk_mul_f32 v[158:159], v[30:31], v[30:31]
	v_pk_mul_f32 v[196:197], v[28:29], v[28:29]
	v_pk_add_f32 v[156:157], v[156:157], v[156:157] op_sel:[0,1] op_sel_hi:[1,0]
	v_pk_mov_b32 v[198:199], v[196:197], v[158:159] op_sel:[1,0]
	v_mov_b32_e32 v197, v159
	v_pk_add_f32 v[158:159], v[198:199], v[196:197]
	v_mul_f32_e32 v196, v9, v9
	v_pk_add_f32 v[158:159], v[158:159], v[158:159] op_sel:[0,1] op_sel_hi:[1,0]
	v_mov_b32_e32 v157, v175
	v_mov_b32_e32 v159, v196
	v_pk_add_f32 v[156:157], v[156:157], v[158:159]
	v_mul_f32_e32 v158, v17, v17
	v_mul_f32_e32 v197, v10, v10
	v_pk_fma_f32 v[158:159], v[16:17], v[16:17], v[158:159] op_sel_hi:[1,1,0]
	v_mul_f32_e32 v196, v19, v19
	v_mul_f32_e32 v198, v11, v11
	v_mov_b32_e32 v159, v197
	v_pk_fma_f32 v[196:197], v[18:19], v[18:19], v[196:197] op_sel_hi:[1,1,0]
	s_nop 0
	v_mov_b32_e32 v197, v198
	v_pk_add_f32 v[158:159], v[158:159], v[196:197]
	s_nop 0
	v_pk_add_f32 v[156:157], v[156:157], v[158:159]
	s_nop 0
	v_add_f32_e32 v156, v156, v157
	ds_bpermute_b32 v157, v173, v156
	s_waitcnt lgkmcnt(0)
	v_add_f32_e32 v156, v156, v157
	ds_bpermute_b32 v157, v220, v156
	s_waitcnt lgkmcnt(0)
	v_add_f32_e32 v156, v156, v157
	v_fmamk_f32 v156, v156, 0x3c800000, v215
	v_rsq_f32_e32 v196, v156
	s_nop 0
	v_pk_mul_f32 v[156:157], v[36:37], v[196:197] op_sel_hi:[1,0]
	s_nop 0
	v_pk_mul_f32 v[226:227], v[186:187], v[156:157]
	ds_bpermute_b32 v175, v173, v226
	v_pk_mul_f32 v[158:159], v[38:39], v[196:197] op_sel_hi:[1,0]
	v_pk_mul_f32 v[156:157], v[28:29], v[196:197] op_sel_hi:[1,0]
	v_pk_mul_f32 v[206:207], v[184:185], v[158:159]
	v_pk_mul_f32 v[230:231], v[182:183], v[156:157]
	s_waitcnt vmcnt(4) lgkmcnt(0)
	v_mul_f32_e32 v175, v222, v175
	v_cndmask_b32_e64 v175, v175, -v175, s[4:5]
	v_fmac_f32_e32 v175, v202, v226
	ds_bpermute_b32 v202, v173, v227
	v_pk_mul_f32 v[158:159], v[30:31], v[196:197] op_sel_hi:[1,0]
	v_pk_mul_f32 v[156:157], v[18:19], v[196:197] op_sel_hi:[1,0]
	v_pk_mul_f32 v[200:201], v[180:181], v[158:159]
	v_pk_mul_f32 v[158:159], v[16:17], v[196:197] op_sel_hi:[1,0]
	s_waitcnt lgkmcnt(0)
	v_mul_f32_e32 v202, v223, v202
	v_cndmask_b32_e64 v202, v202, -v202, s[4:5]
	v_fmac_f32_e32 v202, v203, v227
	ds_bpermute_b32 v203, v173, v206
	v_pk_mul_f32 v[198:199], v[8:9], v[196:197] op_sel_hi:[1,0]
	v_pk_mul_f32 v[196:197], v[10:11], v[196:197] op_sel_hi:[1,0]
	v_cndmask_b32_e32 v175, v226, v175, vcc
	v_cndmask_b32_e32 v202, v227, v202, vcc
	s_waitcnt lgkmcnt(0)
	v_mul_f32_e32 v203, v224, v203
	v_cndmask_b32_e64 v203, v203, -v203, s[4:5]
	v_fmac_f32_e32 v203, v204, v206
	ds_bpermute_b32 v204, v173, v207
	v_cndmask_b32_e32 v203, v206, v203, vcc
	v_pk_mul_f32 v[156:157], v[192:193], v[156:157]
	v_pk_mul_f32 v[158:159], v[194:195], v[158:159]
	v_pk_mul_f32 v[196:197], v[188:189], v[196:197]
	s_waitcnt lgkmcnt(0)
	v_mul_f32_e32 v204, v225, v204
	v_cndmask_b32_e64 v204, v204, -v204, s[4:5]
	v_fmac_f32_e32 v204, v205, v207
	ds_bpermute_b32 v205, v173, v230
	v_cndmask_b32_e32 v204, v207, v204, vcc
	v_pk_mul_f32 v[198:199], v[190:191], v[198:199]
	s_waitcnt lgkmcnt(0)
	v_mul_f32_e32 v148, v148, v205
	v_cndmask_b32_e64 v148, v148, -v148, s[4:5]
	v_fmac_f32_e32 v148, v144, v230
	ds_bpermute_b32 v144, v173, v231
	v_cndmask_b32_e32 v205, v230, v148, vcc
	s_waitcnt lgkmcnt(0)
	v_mul_f32_e32 v144, v149, v144
	v_cndmask_b32_e64 v144, v144, -v144, s[4:5]
	v_fmac_f32_e32 v144, v145, v231
	v_cndmask_b32_e32 v206, v231, v144, vcc
	ds_bpermute_b32 v144, v173, v200
	s_waitcnt lgkmcnt(0)
	v_mul_f32_e32 v144, v150, v144
	v_cndmask_b32_e64 v144, v144, -v144, s[4:5]
	v_fmac_f32_e32 v144, v146, v200
	v_cndmask_b32_e32 v150, v200, v144, vcc
	ds_bpermute_b32 v144, v173, v201
	s_waitcnt lgkmcnt(0)
; __device__ __forceinline__ u32x4 pack8(const f32x4& a, const f32x4& b) { u32x4 w; w.x = cvt_pk_bf16(a[0], a[1]); w.y = cvt_pk_bf16(a[2], a[3]); w.z = cvt_pk_bf16(b[0], b[1]); w.w = cvt_pk_bf16(b[2], b[3]); return w; }
; __device__ __forceinline__ float frsq(float x) { return __builtin_amdgcn_rsqf(x); }
;     __device__ __forceinline__ void operator()(Acc& acc, const Unit& u, int wr, int wc, int fr, int fq) const {
;     ...
;                     for (int m2 = 0; m2 < 2; ++m2) { const int m = 2 * mh + m2;
;                         const int row = row0 + ai * HALF + m * 16;
;                         float ss = 0.f;
; #pragma unroll
;                         for (int bj = 0; bj < 2; ++bj)
; #pragma unroll
;                             for (int n = 0; n < 2; ++n) { const f32x4 v = acc[ai][bj][m][n]; ss += (v[0] * v[0] + v[1] * v[1]) + (v[2] * v[2] + v[3] * v[3]); }
;                         ss += __shfl_xor(ss, 16); ss += __shfl_xor(ss, 32);
;                         const float rstd = frsq(ss * (1.0f / 64.0f) + EPS);
;                         f32x4 y[2][2];
; #pragma unroll
;                         for (int bj = 0; bj < 2; ++bj)
; #pragma unroll
;                             for (int n = 0; n < 2; ++n) y[bj][n] = acc[ai][bj][m][n] * rstd * g[bj][n];
; #pragma unroll
;                         for (int n = 0; n < 2; ++n) {
;                             const f32x4 cs = rc[m2][n], sn = rs[m2][n];
;                             f32x4 o;
; #pragma unroll
;                             for (int i = 0; i < 4; ++i) { const float mine = y[0][n][i], oth = __shfl_xor(mine, 16);
;                                 const float r = (fq == 0) ? (mine * cs[i] - oth * sn[i]) : (mine * cs[i] + oth * sn[i]);
;                                 o[i] = (fq < 2) ? r : mine; }
;                             y[0][n] = o;
;                         }
; #pragma unroll
;                         for (int bj = 0; bj < 2; ++bj) *(u32x4*)(ob + (size_t)row * ld + bj * 32) = pack8(y[bj][0], y[bj][1]);
	v_mul_f32_e32 v144, v151, v144
	v_cndmask_b32_e64 v144, v144, -v144, s[4:5]
	v_fmac_f32_e32 v144, v147, v201
	v_cndmask_b32_e32 v147, v201, v144, vcc
	v_lshlrev_b64 v[144:145], s12, v[154:155]
	v_lshl_add_u64 v[148:149], v[144:145], 1, v[178:179]
	v_cvt_pk_bf16_f32 v144, v175, v202
	v_cvt_pk_bf16_f32 v145, v203, v204
	v_cvt_pk_bf16_f32 v146, v205, v206
	v_cvt_pk_bf16_f32 v147, v150, v147
	global_store_dwordx4 v[148:149], v[144:147], off sc1
	s_nop 1
	v_cvt_pk_bf16_f32 v144, v158, v159
	v_cvt_pk_bf16_f32 v145, v156, v157
	v_cvt_pk_bf16_f32 v146, v198, v199
	v_cvt_pk_bf16_f32 v147, v196, v197
	global_store_dwordx4 v[148:149], v[144:147], off offset:64 sc1
	s_nop 1
	v_pk_mul_f32 v[144:145], v[22:23], v[22:23]
	v_pk_mul_f32 v[146:147], v[20:21], v[20:21]
	s_nop 0
	v_pk_mov_b32 v[148:149], v[146:147], v[144:145] op_sel:[1,0]
	v_mov_b32_e32 v147, v145
	v_pk_add_f32 v[144:145], v[148:149], v[146:147]
	v_pk_mul_f32 v[146:147], v[14:15], v[14:15]
	v_pk_mul_f32 v[148:149], v[12:13], v[12:13]
	v_pk_add_f32 v[144:145], v[144:145], v[144:145] op_sel:[0,1] op_sel_hi:[1,0]
	v_pk_mov_b32 v[150:151], v[148:149], v[146:147] op_sel:[1,0]
	v_mov_b32_e32 v149, v147
	v_pk_add_f32 v[146:147], v[150:151], v[148:149]
	v_mul_f32_e32 v148, v0, v0
	v_mul_f32_e32 v149, v1, v1
	v_pk_add_f32 v[146:147], v[146:147], v[146:147] op_sel:[0,1] op_sel_hi:[1,0]
	v_mov_b32_e32 v145, v148
	v_mov_b32_e32 v147, v149
	v_pk_add_f32 v[144:145], v[144:145], v[146:147]
	v_mul_f32_e32 v146, v5, v5
	v_mul_f32_e32 v148, v7, v7
	v_mul_f32_e32 v150, v2, v2
	v_mul_f32_e32 v151, v3, v3
	v_pk_fma_f32 v[146:147], v[4:5], v[4:5], v[146:147] op_sel_hi:[1,1,0]
	v_pk_fma_f32 v[148:149], v[6:7], v[6:7], v[148:149] op_sel_hi:[1,1,0]
	v_mov_b32_e32 v147, v150
	v_mov_b32_e32 v149, v151
	v_pk_add_f32 v[146:147], v[146:147], v[148:149]
	s_nop 0
	v_pk_add_f32 v[144:145], v[144:145], v[146:147]
	s_nop 0
	v_add_f32_e32 v144, v144, v145
	ds_bpermute_b32 v145, v173, v144
	s_waitcnt lgkmcnt(0)
	v_add_f32_e32 v144, v144, v145
	ds_bpermute_b32 v145, v220, v144
	s_waitcnt lgkmcnt(0)
	v_add_f32_e32 v144, v144, v145
	v_fmamk_f32 v144, v144, 0x3c800000, v215
	v_rsq_f32_e32 v144, v144
	s_nop 0
	v_pk_mul_f32 v[146:147], v[20:21], v[144:145] op_sel_hi:[1,0]
	s_nop 0
	v_pk_mul_f32 v[158:159], v[186:187], v[146:147]
	ds_bpermute_b32 v175, v173, v158
	v_pk_mul_f32 v[148:149], v[22:23], v[144:145] op_sel_hi:[1,0]
	v_pk_mul_f32 v[146:147], v[12:13], v[144:145] op_sel_hi:[1,0]
	v_pk_mul_f32 v[156:157], v[184:185], v[148:149]
	v_pk_mul_f32 v[148:149], v[14:15], v[144:145] op_sel_hi:[1,0]
	s_waitcnt vmcnt(2) lgkmcnt(0)
	v_mul_f32_e32 v140, v140, v175
	v_cndmask_b32_e64 v140, v140, -v140, s[4:5]
	v_fmac_f32_e32 v140, v136, v158
	v_cndmask_b32_e32 v136, v158, v140, vcc
	ds_bpermute_b32 v140, v173, v159
	v_pk_mul_f32 v[154:155], v[180:181], v[148:149]
	v_pk_mul_f32 v[180:181], v[182:183], v[146:147]
	v_pk_mul_f32 v[148:149], v[4:5], v[144:145] op_sel_hi:[1,0]
	v_pk_mul_f32 v[146:147], v[6:7], v[144:145] op_sel_hi:[1,0]
	s_waitcnt lgkmcnt(0)
	v_mul_f32_e32 v140, v141, v140
	v_cndmask_b32_e64 v140, v140, -v140, s[4:5]
	v_fmac_f32_e32 v140, v137, v159
	v_cndmask_b32_e32 v137, v159, v140, vcc
	ds_bpermute_b32 v140, v173, v156
	v_pk_mul_f32 v[150:151], v[194:195], v[148:149]
	v_pk_mul_f32 v[148:149], v[0:1], v[144:145] op_sel_hi:[1,0]
	v_pk_mul_f32 v[144:145], v[2:3], v[144:145] op_sel_hi:[1,0]
	v_pk_mul_f32 v[146:147], v[192:193], v[146:147]
	s_waitcnt lgkmcnt(0)
	v_mul_f32_e32 v140, v142, v140
	v_cndmask_b32_e64 v140, v140, -v140, s[4:5]
	v_fmac_f32_e32 v140, v138, v156
	v_cndmask_b32_e32 v138, v156, v140, vcc
	ds_bpermute_b32 v140, v173, v157
	v_pk_mul_f32 v[144:145], v[188:189], v[144:145]
	v_pk_mul_f32 v[148:149], v[190:191], v[148:149]
	s_waitcnt lgkmcnt(0)
	v_mul_f32_e32 v140, v143, v140
	v_cndmask_b32_e64 v140, v140, -v140, s[4:5]
	v_fmac_f32_e32 v140, v139, v157
	v_cndmask_b32_e32 v139, v157, v140, vcc
	ds_bpermute_b32 v140, v173, v180
	s_waitcnt lgkmcnt(0)
	v_mul_f32_e32 v132, v132, v140
	v_cndmask_b32_e64 v132, v132, -v132, s[4:5]
	v_fmac_f32_e32 v132, v128, v180
	ds_bpermute_b32 v128, v173, v181
	v_cndmask_b32_e32 v140, v180, v132, vcc
	s_waitcnt lgkmcnt(0)
	v_mul_f32_e32 v128, v133, v128
	v_cndmask_b32_e64 v128, v128, -v128, s[4:5]
	v_fmac_f32_e32 v128, v129, v181
	v_cndmask_b32_e32 v141, v181, v128, vcc
	ds_bpermute_b32 v128, v173, v154
	s_waitcnt lgkmcnt(0)
	v_mul_f32_e32 v128, v134, v128
	v_cndmask_b32_e64 v128, v128, -v128, s[4:5]
	v_fmac_f32_e32 v128, v130, v154
	v_cndmask_b32_e32 v134, v154, v128, vcc
	ds_bpermute_b32 v128, v173, v155
	s_waitcnt lgkmcnt(0)
	v_mul_f32_e32 v128, v135, v128
	v_cndmask_b32_e64 v128, v128, -v128, s[4:5]
	v_fmac_f32_e32 v128, v131, v155
	v_cndmask_b32_e32 v131, v155, v128, vcc
	v_lshlrev_b64 v[128:129], s12, v[152:153]
	v_lshl_add_u64 v[132:133], v[128:129], 1, v[178:179]
	v_cvt_pk_bf16_f32 v128, v136, v137
	v_cvt_pk_bf16_f32 v129, v138, v139
	v_cvt_pk_bf16_f32 v130, v140, v141
	v_cvt_pk_bf16_f32 v131, v134, v131
	global_store_dwordx4 v[132:133], v[128:131], off sc1
	s_mov_b64 s[4:5], 0
	s_nop 0
	v_cvt_pk_bf16_f32 v128, v150, v151
	v_cvt_pk_bf16_f32 v129, v146, v147
	v_cvt_pk_bf16_f32 v130, v148, v149
	v_cvt_pk_bf16_f32 v131, v144, v145
	global_store_dwordx4 v[132:133], v[128:131], off offset:64 sc1
; __device__ __forceinline__ u32x4 pack8(const f32x4& a, const f32x4& b) { u32x4 w; w.x = cvt_pk_bf16(a[0], a[1]); w.y = cvt_pk_bf16(a[2], a[3]); w.z = cvt_pk_bf16(b[0], b[1]); w.w = cvt_pk_bf16(b[2], b[3]); return w; }
;     __device__ __forceinline__ void operator()(Acc& acc, const Unit& u, int wr, int wc, int fr, int fq) const {
;     ...
; #pragma unroll
;                 for (int ai = 0; ai < 2; ++ai)
; #pragma unroll
;                     for (int m = 0; m < 4; ++m)
; #pragma unroll
;                         for (int bj = 0; bj < 2; ++bj) *(u32x4*)(SV + (size_t)(row0 + ai * HALF + m * 16) * 128 + (wc - 2) * 64 + bj * 32 + 8 * fq) = pack8(acc[ai][bj][m][0], acc[ai][bj][m][1]);
.LBB0_181:
	s_andn2_b64 vcc, exec, s[4:5]
	s_cbranch_vccnz .LBB0_183
	v_ashrrev_i32_e32 v175, 31, v174
	v_lshlrev_b64 v[132:133], 8, v[174:175]
	v_lshl_add_u64 v[132:133], s[78:79], 0, v[132:133]
	v_cvt_pk_bf16_f32 v128, v124, v125
	v_cvt_pk_bf16_f32 v129, v126, v127
	v_cvt_pk_bf16_f32 v130, v120, v121
	v_cvt_pk_bf16_f32 v131, v122, v123
	v_lshl_add_u64 v[132:133], v[176:177], 1, v[132:133]
	global_store_dwordx4 v[132:133], v[128:131], off offset:-256 sc1
	s_mov_b64 s[4:5], 0x2000
	v_lshl_add_u64 v[134:135], v[132:133], 0, s[4:5]
	v_cvt_pk_bf16_f32 v128, v112, v113
	v_cvt_pk_bf16_f32 v129, v114, v115
	v_cvt_pk_bf16_f32 v130, v104, v105
	v_cvt_pk_bf16_f32 v131, v106, v107
	global_store_dwordx4 v[132:133], v[128:131], off offset:-192 sc1
	s_mov_b64 s[4:5], 0x3000
	s_nop 0
	v_cvt_pk_bf16_f32 v128, v116, v117
	v_cvt_pk_bf16_f32 v129, v118, v119
	v_cvt_pk_bf16_f32 v130, v108, v109
	v_cvt_pk_bf16_f32 v131, v110, v111
	global_store_dwordx4 v[132:133], v[128:131], off offset:3840 sc1
	s_nop 1
	v_cvt_pk_bf16_f32 v128, v96, v97
	v_cvt_pk_bf16_f32 v129, v98, v99
	v_cvt_pk_bf16_f32 v130, v88, v89
	v_cvt_pk_bf16_f32 v131, v90, v91
	global_store_dwordx4 v[132:133], v[128:131], off offset:3904 sc1
	s_nop 1
	v_cvt_pk_bf16_f32 v128, v100, v101
	v_cvt_pk_bf16_f32 v129, v102, v103
	v_cvt_pk_bf16_f32 v130, v92, v93
	v_cvt_pk_bf16_f32 v131, v94, v95
	global_store_dwordx4 v[134:135], v[128:131], off offset:-256 sc1
	s_nop 1
	v_cvt_pk_bf16_f32 v128, v80, v81
	v_cvt_pk_bf16_f32 v129, v82, v83
	v_cvt_pk_bf16_f32 v130, v72, v73
	v_cvt_pk_bf16_f32 v131, v74, v75
	global_store_dwordx4 v[134:135], v[128:131], off offset:-192 sc1
	v_lshl_add_u64 v[134:135], v[132:133], 0, s[4:5]
	s_mov_b64 s[4:5], 0x9000
	v_cvt_pk_bf16_f32 v128, v84, v85
	v_cvt_pk_bf16_f32 v129, v86, v87
	v_cvt_pk_bf16_f32 v130, v76, v77
	v_cvt_pk_bf16_f32 v131, v78, v79
	global_store_dwordx4 v[134:135], v[128:131], off offset:-256 sc1
	s_nop 1
	v_cvt_pk_bf16_f32 v128, v68, v69
	v_cvt_pk_bf16_f32 v129, v70, v71
	v_cvt_pk_bf16_f32 v130, v64, v65
	v_cvt_pk_bf16_f32 v131, v66, v67
	global_store_dwordx4 v[134:135], v[128:131], off offset:-192 sc1
	v_lshl_add_u64 v[134:135], v[132:133], 0, s[24:25]
	s_nop 0
	v_cvt_pk_bf16_f32 v128, v60, v61
	v_cvt_pk_bf16_f32 v129, v62, v63
	v_cvt_pk_bf16_f32 v130, v56, v57
	v_cvt_pk_bf16_f32 v131, v58, v59
	global_store_dwordx4 v[134:135], v[128:131], off offset:-256 sc1
	s_nop 1
	v_cvt_pk_bf16_f32 v128, v48, v49
	v_cvt_pk_bf16_f32 v129, v50, v51
	v_cvt_pk_bf16_f32 v130, v40, v41
	v_cvt_pk_bf16_f32 v131, v42, v43
	global_store_dwordx4 v[134:135], v[128:131], off offset:-192 sc1
	v_lshl_add_u64 v[134:135], v[132:133], 0, s[4:5]
	s_mov_b64 s[4:5], 0xa000
	v_cvt_pk_bf16_f32 v128, v52, v53
	v_cvt_pk_bf16_f32 v129, v54, v55
	v_cvt_pk_bf16_f32 v130, v44, v45
	v_cvt_pk_bf16_f32 v131, v46, v47
	global_store_dwordx4 v[134:135], v[128:131], off offset:-256 sc1
	s_nop 1
	v_cvt_pk_bf16_f32 v128, v32, v33
	v_cvt_pk_bf16_f32 v129, v34, v35
	v_cvt_pk_bf16_f32 v130, v24, v25
	v_cvt_pk_bf16_f32 v131, v26, v27
	global_store_dwordx4 v[134:135], v[128:131], off offset:-192 sc1
	v_lshl_add_u64 v[134:135], v[132:133], 0, s[4:5]
	s_mov_b64 s[4:5], 0xb000
	v_cvt_pk_bf16_f32 v128, v36, v37
	v_cvt_pk_bf16_f32 v129, v38, v39
	v_cvt_pk_bf16_f32 v130, v28, v29
	v_cvt_pk_bf16_f32 v131, v30, v31
	global_store_dwordx4 v[134:135], v[128:131], off offset:-256 sc1
	v_lshl_add_u64 v[132:133], v[132:133], 0, s[4:5]
	s_nop 0
	v_cvt_pk_bf16_f32 v128, v16, v17
	v_cvt_pk_bf16_f32 v129, v18, v19
	v_cvt_pk_bf16_f32 v130, v8, v9
	v_cvt_pk_bf16_f32 v131, v10, v11
	global_store_dwordx4 v[134:135], v[128:131], off offset:-192 sc1
	s_nop 1
	v_cvt_pk_bf16_f32 v128, v20, v21
	v_cvt_pk_bf16_f32 v129, v22, v23
	v_cvt_pk_bf16_f32 v130, v12, v13
	v_cvt_pk_bf16_f32 v131, v14, v15
	global_store_dwordx4 v[132:133], v[128:131], off offset:-256 sc1
	s_nop 1
	v_cvt_pk_bf16_f32 v128, v4, v5
	v_cvt_pk_bf16_f32 v129, v6, v7
	v_cvt_pk_bf16_f32 v130, v0, v1
	v_cvt_pk_bf16_f32 v131, v2, v3
	global_store_dwordx4 v[132:133], v[128:131], off offset:-192 sc1

; __device__ __forceinline__ u32x4 pack8(const f32x4& a, const f32x4& b) { u32x4 w; w.x = cvt_pk_bf16(a[0], a[1]); w.y = cvt_pk_bf16(a[2], a[3]); w.z = cvt_pk_bf16(b[0], b[1]); w.w = cvt_pk_bf16(b[2], b[3]); return w; }
; __device__ __forceinline__ float fexp(float x) { return __builtin_amdgcn_exp2f(x * 1.4426950408889634f); }
; __device__ __forceinline__ float frcp(float x) { return __builtin_amdgcn_rcpf(x); }
;     __device__ __forceinline__ void operator()(Acc& acc, const Unit& u, int wr, int wc, int fr, int fq) const {
;     ...
; #pragma unroll
;             for (int ai = 0; ai < 2; ++ai)
; #pragma unroll
;                 for (int m = 0; m < 4; ++m)
; #pragma unroll
;                     for (int bj = 0; bj < 2; ++bj) { f32x4 a = acc[ai][bj][m][0], b = acc[ai][bj][m][1];
; #pragma unroll
;                         for (int i = 0; i < 4; ++i) { a[i] = a[i] * frcp(1.0f + fexp(-a[i])); b[i] = b[i] * frcp(1.0f + fexp(-b[i])); }
;                         *(u32x4*)(SG + (size_t)(row0 + ai * HALF + m * 16) * 512 + (pn - 6) * 256 + bj * HALF + cw) = pack8(a, b); }
.LBB0_184:
	s_andn2_b64 vcc, exec, s[4:5]
	s_cbranch_vccnz .LBB0_186
	v_mul_f32_e32 v131, 0xbfb8aa3b, v120
	v_mul_f32_e32 v132, 0xbfb8aa3b, v125
	v_exp_f32_e32 v131, v131
	v_exp_f32_e32 v132, v132
	v_mul_f32_e32 v133, 0xbfb8aa3b, v121
	v_exp_f32_e32 v133, v133
	v_add_f32_e32 v131, 1.0, v131
	v_add_f32_e32 v132, 1.0, v132
	v_rcp_f32_e32 v131, v131
	v_rcp_f32_e32 v132, v132
	v_mul_f32_e32 v128, 0xbfb8aa3b, v124
	v_exp_f32_e32 v130, v128
	v_mul_f32_e32 v134, v120, v131
	v_mul_f32_e32 v131, v125, v132
	v_add_f32_e32 v132, 1.0, v133
	v_mul_f32_e32 v133, 0xbfb8aa3b, v126
	v_mul_f32_e32 v136, 0xbfb8aa3b, v127
	v_exp_f32_e32 v133, v133
	v_mul_f32_e32 v135, 0xbfb8aa3b, v122
	v_exp_f32_e32 v136, v136
	v_mul_f32_e32 v137, 0xbfb8aa3b, v123
	v_exp_f32_e32 v135, v135
	v_exp_f32_e32 v137, v137
	v_add_f32_e32 v130, 1.0, v130
	v_rcp_f32_e32 v130, v130
	v_rcp_f32_e32 v132, v132
	v_add_f32_e32 v133, 1.0, v133
	v_add_f32_e32 v136, 1.0, v136
	v_ashrrev_i32_e32 v175, 31, v174
	v_rcp_f32_e32 v133, v133
	v_add_f32_e32 v135, 1.0, v135
	v_rcp_f32_e32 v136, v136
	v_add_f32_e32 v137, 1.0, v137
	v_readlane_b32 s4, v254, 45
	v_lshlrev_b64 v[128:129], 10, v[174:175]
	v_rcp_f32_e32 v135, v135
	v_rcp_f32_e32 v137, v137
	v_readlane_b32 s5, v254, 46
	s_lshl_b32 s12, s40, 9
	v_ashrrev_i32_e32 v173, 31, v172
	v_lshl_add_u64 v[128:129], s[4:5], 0, v[128:129]
	v_mul_f32_e32 v130, v124, v130
	v_mul_f32_e32 v132, v121, v132
	v_lshl_add_u64 v[128:129], v[128:129], 0, s[12:13]
	v_mul_f32_e32 v133, v126, v133
	v_mul_f32_e32 v136, v127, v136
	v_cvt_pk_bf16_f32 v130, v130, v131
	v_cvt_pk_bf16_f32 v131, v133, v136
	v_cvt_pk_bf16_f32 v132, v134, v132
	v_lshl_add_u64 v[128:129], v[172:173], 1, v[128:129]
	v_mul_f32_e32 v135, v122, v135
	v_mul_f32_e32 v137, v123, v137
	v_cvt_pk_bf16_f32 v133, v135, v137
	global_store_dwordx4 v[128:129], v[130:133], off offset:-3072 sc1
	v_mul_f32_e32 v134, 0xbfb8aa3b, v112
	v_exp_f32_e32 v134, v134
	v_mul_f32_e32 v131, 0xbfb8aa3b, v104
	v_mul_f32_e32 v132, 0xbfb8aa3b, v113
	v_exp_f32_e32 v131, v131
	v_exp_f32_e32 v132, v132
	v_mul_f32_e32 v133, 0xbfb8aa3b, v105
	v_exp_f32_e32 v133, v133
	v_add_f32_e32 v131, 1.0, v131
	v_add_f32_e32 v132, 1.0, v132
	v_rcp_f32_e32 v131, v131
	v_rcp_f32_e32 v132, v132
	v_add_f32_e32 v130, 1.0, v134
	v_mul_f32_e32 v136, 0xbfb8aa3b, v115
	v_mul_f32_e32 v134, v104, v131
	v_mul_f32_e32 v131, v113, v132
	v_add_f32_e32 v132, 1.0, v133
	v_mul_f32_e32 v133, 0xbfb8aa3b, v114
	v_exp_f32_e32 v133, v133
	v_mul_f32_e32 v135, 0xbfb8aa3b, v106
	v_exp_f32_e32 v136, v136
	v_mul_f32_e32 v137, 0xbfb8aa3b, v107
	v_exp_f32_e32 v135, v135
	v_exp_f32_e32 v137, v137
	v_add_f32_e32 v133, 1.0, v133
	v_rcp_f32_e32 v130, v130
	v_rcp_f32_e32 v132, v132
	v_rcp_f32_e32 v133, v133
	v_add_f32_e32 v136, 1.0, v136
	v_add_f32_e32 v135, 1.0, v135
	v_rcp_f32_e32 v136, v136
	v_add_f32_e32 v137, 1.0, v137
	v_rcp_f32_e32 v135, v135
	v_rcp_f32_e32 v137, v137
	v_mul_f32_e32 v130, v112, v130
	v_mul_f32_e32 v132, v105, v132
	v_mul_f32_e32 v133, v114, v133
	v_mul_f32_e32 v136, v115, v136
	v_cvt_pk_bf16_f32 v130, v130, v131
	v_cvt_pk_bf16_f32 v131, v133, v136
	v_mul_f32_e32 v133, 0xbfb8aa3b, v116
	v_cvt_pk_bf16_f32 v132, v134, v132
	v_mul_f32_e32 v135, v106, v135
	v_mul_f32_e32 v137, v107, v137
	v_exp_f32_e32 v136, v133
	v_cvt_pk_bf16_f32 v133, v135, v137
	global_store_dwordx4 v[128:129], v[130:133], off offset:-2816 sc1
	v_mul_f32_e32 v135, 0xbfb8aa3b, v110
	v_exp_f32_e32 v135, v135
	v_mul_f32_e32 v131, 0xbfb8aa3b, v108
	v_mul_f32_e32 v132, 0xbfb8aa3b, v117
	v_exp_f32_e32 v131, v131
	v_exp_f32_e32 v132, v132
	v_mul_f32_e32 v133, 0xbfb8aa3b, v109
	v_exp_f32_e32 v133, v133
	v_add_f32_e32 v131, 1.0, v131
	v_add_f32_e32 v132, 1.0, v132
	v_rcp_f32_e32 v131, v131
	v_rcp_f32_e32 v132, v132
	v_add_f32_e32 v130, 1.0, v136
	v_mul_f32_e32 v136, 0xbfb8aa3b, v119
	v_mul_f32_e32 v134, v108, v131
	v_mul_f32_e32 v131, v117, v132
	v_add_f32_e32 v132, 1.0, v133
	v_mul_f32_e32 v133, 0xbfb8aa3b, v118
	v_exp_f32_e32 v133, v133
	v_exp_f32_e32 v136, v136
	v_mul_f32_e32 v137, 0xbfb8aa3b, v111
	v_exp_f32_e32 v137, v137
	v_add_f32_e32 v133, 1.0, v133
	v_rcp_f32_e32 v130, v130
	v_rcp_f32_e32 v133, v133
	v_add_f32_e32 v135, 1.0, v135
	v_add_f32_e32 v136, 1.0, v136
	v_rcp_f32_e32 v132, v132
	v_rcp_f32_e32 v135, v135
	v_rcp_f32_e32 v136, v136
	v_add_f32_e32 v137, 1.0, v137
	v_rcp_f32_e32 v137, v137
	v_mul_f32_e32 v130, v116, v130
	v_mul_f32_e32 v133, v118, v133
	v_mul_f32_e32 v132, v109, v132
	v_mul_f32_e32 v135, v110, v135
	v_mul_f32_e32 v136, v119, v136
	v_cvt_pk_bf16_f32 v130, v130, v131
	v_cvt_pk_bf16_f32 v131, v133, v136
	v_mul_f32_e32 v133, 0xbfb8aa3b, v96
	v_mul_f32_e32 v137, v111, v137
	v_cvt_pk_bf16_f32 v132, v134, v132
	v_exp_f32_e32 v136, v133
	v_cvt_pk_bf16_f32 v133, v135, v137
	v_lshl_add_u64 v[134:135], v[128:129], 0, s[60:61]
	global_store_dwordx4 v[134:135], v[130:133], off offset:-3072 sc1
	v_mul_f32_e32 v138, 0xbfb8aa3b, v99
	v_mul_f32_e32 v137, 0xbfb8aa3b, v90
	v_mul_f32_e32 v131, 0xbfb8aa3b, v88
	v_mul_f32_e32 v132, 0xbfb8aa3b, v97
	v_exp_f32_e32 v131, v131
	v_exp_f32_e32 v132, v132
	v_mul_f32_e32 v133, 0xbfb8aa3b, v89
	v_exp_f32_e32 v133, v133
	v_add_f32_e32 v131, 1.0, v131
	v_add_f32_e32 v132, 1.0, v132
	v_rcp_f32_e32 v131, v131
	v_rcp_f32_e32 v132, v132
	v_add_f32_e32 v130, 1.0, v136
	v_exp_f32_e32 v138, v138
	v_mul_f32_e32 v136, v88, v131
	v_mul_f32_e32 v131, v97, v132
	v_add_f32_e32 v132, 1.0, v133
	v_mul_f32_e32 v133, 0xbfb8aa3b, v98
	v_exp_f32_e32 v133, v133
	v_mul_f32_e32 v139, 0xbfb8aa3b, v91
	v_exp_f32_e32 v137, v137
	v_exp_f32_e32 v139, v139
	v_add_f32_e32 v133, 1.0, v133
	v_rcp_f32_e32 v130, v130
	v_rcp_f32_e32 v132, v132
	v_rcp_f32_e32 v133, v133
; __device__ __forceinline__ u32x4 pack8(const f32x4& a, const f32x4& b) { u32x4 w; w.x = cvt_pk_bf16(a[0], a[1]); w.y = cvt_pk_bf16(a[2], a[3]); w.z = cvt_pk_bf16(b[0], b[1]); w.w = cvt_pk_bf16(b[2], b[3]); return w; }
; __device__ __forceinline__ float fexp(float x) { return __builtin_amdgcn_exp2f(x * 1.4426950408889634f); }
; __device__ __forceinline__ float frcp(float x) { return __builtin_amdgcn_rcpf(x); }
;     __device__ __forceinline__ void operator()(Acc& acc, const Unit& u, int wr, int wc, int fr, int fq) const {
;     ...
; #pragma unroll
;             for (int ai = 0; ai < 2; ++ai)
; #pragma unroll
;                 for (int m = 0; m < 4; ++m)
; #pragma unroll
;                     for (int bj = 0; bj < 2; ++bj) { f32x4 a = acc[ai][bj][m][0], b = acc[ai][bj][m][1];
; #pragma unroll
;                         for (int i = 0; i < 4; ++i) { a[i] = a[i] * frcp(1.0f + fexp(-a[i])); b[i] = b[i] * frcp(1.0f + fexp(-b[i])); }
;                         *(u32x4*)(SG + (size_t)(row0 + ai * HALF + m * 16) * 512 + (pn - 6) * 256 + bj * HALF + cw) = pack8(a, b); }
	v_add_f32_e32 v138, 1.0, v138
	v_add_f32_e32 v137, 1.0, v137
	v_rcp_f32_e32 v138, v138
	v_add_f32_e32 v139, 1.0, v139
	v_rcp_f32_e32 v137, v137
	v_rcp_f32_e32 v139, v139
	v_mul_f32_e32 v130, v96, v130
	v_mul_f32_e32 v132, v89, v132
	v_mul_f32_e32 v133, v98, v133
	v_mul_f32_e32 v138, v99, v138
	v_cvt_pk_bf16_f32 v130, v130, v131
	v_cvt_pk_bf16_f32 v131, v133, v138
	v_mul_f32_e32 v133, 0xbfb8aa3b, v100
	v_cvt_pk_bf16_f32 v132, v136, v132
	v_mul_f32_e32 v137, v90, v137
	v_mul_f32_e32 v139, v91, v139
	v_exp_f32_e32 v138, v133
	v_cvt_pk_bf16_f32 v133, v137, v139
	global_store_dwordx4 v[134:135], v[130:133], off offset:-2816 sc1
	v_mul_f32_e32 v135, 0xbfb8aa3b, v94
	v_mul_f32_e32 v136, 0xbfb8aa3b, v103
	v_mul_f32_e32 v131, 0xbfb8aa3b, v92
	v_mul_f32_e32 v132, 0xbfb8aa3b, v101
	v_exp_f32_e32 v131, v131
	v_exp_f32_e32 v132, v132
	v_mul_f32_e32 v133, 0xbfb8aa3b, v93
	v_exp_f32_e32 v133, v133
	v_add_f32_e32 v131, 1.0, v131
	v_add_f32_e32 v132, 1.0, v132
	v_rcp_f32_e32 v131, v131
	v_rcp_f32_e32 v132, v132
	v_exp_f32_e32 v135, v135
	v_exp_f32_e32 v136, v136
	v_mul_f32_e32 v134, v92, v131
	v_mul_f32_e32 v131, v101, v132
	v_add_f32_e32 v132, 1.0, v133
	v_mul_f32_e32 v133, 0xbfb8aa3b, v102
	v_exp_f32_e32 v133, v133
	v_mul_f32_e32 v137, 0xbfb8aa3b, v95
	v_exp_f32_e32 v137, v137
	v_add_f32_e32 v130, 1.0, v138
	v_add_f32_e32 v133, 1.0, v133
	v_rcp_f32_e32 v130, v130
	v_rcp_f32_e32 v133, v133
	v_add_f32_e32 v135, 1.0, v135
	v_add_f32_e32 v136, 1.0, v136
	v_rcp_f32_e32 v132, v132
	v_rcp_f32_e32 v135, v135
	v_rcp_f32_e32 v136, v136
	v_add_f32_e32 v137, 1.0, v137
	v_rcp_f32_e32 v137, v137
	v_mul_f32_e32 v130, v100, v130
	v_mul_f32_e32 v133, v102, v133
	v_mul_f32_e32 v132, v93, v132
	v_mul_f32_e32 v135, v94, v135
	v_mul_f32_e32 v136, v103, v136
	v_cvt_pk_bf16_f32 v130, v130, v131
	v_cvt_pk_bf16_f32 v131, v133, v136
	v_mul_f32_e32 v133, 0xbfb8aa3b, v80
	v_mul_f32_e32 v137, v95, v137
	v_cvt_pk_bf16_f32 v132, v134, v132
	v_exp_f32_e32 v136, v133
	v_cvt_pk_bf16_f32 v133, v135, v137
	v_lshl_add_u64 v[134:135], v[128:129], 0, s[24:25]
	global_store_dwordx4 v[134:135], v[130:133], off offset:-3072 sc1
	v_mul_f32_e32 v138, 0xbfb8aa3b, v83
	v_mul_f32_e32 v137, 0xbfb8aa3b, v74
	v_mul_f32_e32 v131, 0xbfb8aa3b, v72
	v_mul_f32_e32 v132, 0xbfb8aa3b, v81
	v_exp_f32_e32 v131, v131
	v_exp_f32_e32 v132, v132
	v_mul_f32_e32 v133, 0xbfb8aa3b, v73
	v_exp_f32_e32 v133, v133
	v_add_f32_e32 v131, 1.0, v131
	v_add_f32_e32 v132, 1.0, v132
	v_rcp_f32_e32 v131, v131
	v_rcp_f32_e32 v132, v132
	v_add_f32_e32 v130, 1.0, v136
	v_exp_f32_e32 v138, v138
	v_mul_f32_e32 v136, v72, v131
	v_mul_f32_e32 v131, v81, v132
	v_add_f32_e32 v132, 1.0, v133
	v_mul_f32_e32 v133, 0xbfb8aa3b, v82
	v_exp_f32_e32 v133, v133
	v_mul_f32_e32 v139, 0xbfb8aa3b, v75
	v_exp_f32_e32 v137, v137
	v_exp_f32_e32 v139, v139
	v_add_f32_e32 v133, 1.0, v133
	v_rcp_f32_e32 v130, v130
	v_rcp_f32_e32 v132, v132
	v_rcp_f32_e32 v133, v133
	v_add_f32_e32 v138, 1.0, v138
	v_add_f32_e32 v137, 1.0, v137
	v_rcp_f32_e32 v138, v138
	v_add_f32_e32 v139, 1.0, v139
	v_rcp_f32_e32 v137, v137
	v_rcp_f32_e32 v139, v139
	v_mul_f32_e32 v130, v80, v130
	v_mul_f32_e32 v132, v73, v132
	v_mul_f32_e32 v133, v82, v133
	v_mul_f32_e32 v138, v83, v138
	v_cvt_pk_bf16_f32 v130, v130, v131
	v_cvt_pk_bf16_f32 v131, v133, v138
	v_mul_f32_e32 v133, 0xbfb8aa3b, v84
	v_cvt_pk_bf16_f32 v132, v136, v132
	v_mul_f32_e32 v137, v74, v137
	v_mul_f32_e32 v139, v75, v139
	v_exp_f32_e32 v138, v133
	v_cvt_pk_bf16_f32 v133, v137, v139
	global_store_dwordx4 v[134:135], v[130:133], off offset:-2816 sc1
	v_mul_f32_e32 v135, 0xbfb8aa3b, v78
	v_mul_f32_e32 v136, 0xbfb8aa3b, v87
	v_mul_f32_e32 v131, 0xbfb8aa3b, v76
	v_mul_f32_e32 v132, 0xbfb8aa3b, v85
	v_exp_f32_e32 v131, v131
	v_exp_f32_e32 v132, v132
	v_mul_f32_e32 v133, 0xbfb8aa3b, v77
	v_exp_f32_e32 v133, v133
	v_add_f32_e32 v131, 1.0, v131
	v_add_f32_e32 v132, 1.0, v132
	v_rcp_f32_e32 v131, v131
	v_rcp_f32_e32 v132, v132
	v_exp_f32_e32 v135, v135
	v_exp_f32_e32 v136, v136
	v_mul_f32_e32 v134, v76, v131
	v_mul_f32_e32 v131, v85, v132
	v_add_f32_e32 v132, 1.0, v133
	v_mul_f32_e32 v133, 0xbfb8aa3b, v86
	v_exp_f32_e32 v133, v133
	v_mul_f32_e32 v137, 0xbfb8aa3b, v79
	v_exp_f32_e32 v137, v137
	v_add_f32_e32 v130, 1.0, v138
	v_add_f32_e32 v133, 1.0, v133
	v_rcp_f32_e32 v130, v130
	v_rcp_f32_e32 v133, v133
	v_add_f32_e32 v135, 1.0, v135
	v_add_f32_e32 v136, 1.0, v136
	v_rcp_f32_e32 v132, v132
	v_rcp_f32_e32 v135, v135
	v_rcp_f32_e32 v136, v136
	v_add_f32_e32 v137, 1.0, v137
	v_rcp_f32_e32 v137, v137
	v_mul_f32_e32 v130, v84, v130
	v_mul_f32_e32 v133, v86, v133
	v_mul_f32_e32 v132, v77, v132
	v_mul_f32_e32 v135, v78, v135
	v_mul_f32_e32 v136, v87, v136
	v_cvt_pk_bf16_f32 v130, v130, v131
	v_cvt_pk_bf16_f32 v131, v133, v136
	v_mul_f32_e32 v133, 0xbfb8aa3b, v68
	v_mul_f32_e32 v137, v79, v137
	v_cvt_pk_bf16_f32 v132, v134, v132
	v_exp_f32_e32 v136, v133
	v_cvt_pk_bf16_f32 v133, v135, v137
	v_lshl_add_u64 v[134:135], v[128:129], 0, s[64:65]
	global_store_dwordx4 v[134:135], v[130:133], off offset:-3072 sc1
	v_mul_f32_e32 v138, 0xbfb8aa3b, v71
	v_mul_f32_e32 v137, 0xbfb8aa3b, v66
	v_mul_f32_e32 v131, 0xbfb8aa3b, v64
	v_mul_f32_e32 v132, 0xbfb8aa3b, v69
	v_exp_f32_e32 v131, v131
	v_exp_f32_e32 v132, v132
	v_mul_f32_e32 v133, 0xbfb8aa3b, v65
	v_exp_f32_e32 v133, v133
	v_add_f32_e32 v131, 1.0, v131
	v_add_f32_e32 v132, 1.0, v132
	v_rcp_f32_e32 v131, v131
	v_rcp_f32_e32 v132, v132
	v_add_f32_e32 v130, 1.0, v136
	v_exp_f32_e32 v138, v138
	v_mul_f32_e32 v136, v64, v131
	v_mul_f32_e32 v131, v69, v132
	v_add_f32_e32 v132, 1.0, v133
	v_mul_f32_e32 v133, 0xbfb8aa3b, v70
	v_exp_f32_e32 v133, v133
	v_mul_f32_e32 v139, 0xbfb8aa3b, v67
; __device__ __forceinline__ u32x4 pack8(const f32x4& a, const f32x4& b) { u32x4 w; w.x = cvt_pk_bf16(a[0], a[1]); w.y = cvt_pk_bf16(a[2], a[3]); w.z = cvt_pk_bf16(b[0], b[1]); w.w = cvt_pk_bf16(b[2], b[3]); return w; }
; __device__ __forceinline__ float fexp(float x) { return __builtin_amdgcn_exp2f(x * 1.4426950408889634f); }
; __device__ __forceinline__ float frcp(float x) { return __builtin_amdgcn_rcpf(x); }
;     __device__ __forceinline__ void operator()(Acc& acc, const Unit& u, int wr, int wc, int fr, int fq) const {
;     ...
; #pragma unroll
;             for (int ai = 0; ai < 2; ++ai)
; #pragma unroll
;                 for (int m = 0; m < 4; ++m)
; #pragma unroll
;                     for (int bj = 0; bj < 2; ++bj) { f32x4 a = acc[ai][bj][m][0], b = acc[ai][bj][m][1];
; #pragma unroll
;                         for (int i = 0; i < 4; ++i) { a[i] = a[i] * frcp(1.0f + fexp(-a[i])); b[i] = b[i] * frcp(1.0f + fexp(-b[i])); }
;                         *(u32x4*)(SG + (size_t)(row0 + ai * HALF + m * 16) * 512 + (pn - 6) * 256 + bj * HALF + cw) = pack8(a, b); }
	v_exp_f32_e32 v137, v137
	v_exp_f32_e32 v139, v139
	v_add_f32_e32 v133, 1.0, v133
	v_rcp_f32_e32 v130, v130
	v_rcp_f32_e32 v132, v132
	v_rcp_f32_e32 v133, v133
	v_add_f32_e32 v138, 1.0, v138
	v_add_f32_e32 v137, 1.0, v137
	v_rcp_f32_e32 v138, v138
	v_add_f32_e32 v139, 1.0, v139
	v_rcp_f32_e32 v137, v137
	v_rcp_f32_e32 v139, v139
	v_mul_f32_e32 v130, v68, v130
	v_mul_f32_e32 v132, v65, v132
	v_mul_f32_e32 v133, v70, v133
	v_mul_f32_e32 v138, v71, v138
	v_cvt_pk_bf16_f32 v130, v130, v131
	v_cvt_pk_bf16_f32 v131, v133, v138
	v_mul_f32_e32 v133, 0xbfb8aa3b, v60
	v_cvt_pk_bf16_f32 v132, v136, v132
	v_mul_f32_e32 v137, v66, v137
	v_mul_f32_e32 v139, v67, v139
	v_exp_f32_e32 v138, v133
	v_cvt_pk_bf16_f32 v133, v137, v139
	global_store_dwordx4 v[134:135], v[130:133], off offset:-2816 sc1
	v_mul_f32_e32 v135, 0xbfb8aa3b, v58
	v_mul_f32_e32 v136, 0xbfb8aa3b, v63
	v_mul_f32_e32 v131, 0xbfb8aa3b, v56
	v_mul_f32_e32 v132, 0xbfb8aa3b, v61
	v_exp_f32_e32 v131, v131
	v_exp_f32_e32 v132, v132
	v_mul_f32_e32 v133, 0xbfb8aa3b, v57
	v_exp_f32_e32 v133, v133
	v_add_f32_e32 v131, 1.0, v131
	v_add_f32_e32 v132, 1.0, v132
	v_rcp_f32_e32 v131, v131
	v_rcp_f32_e32 v132, v132
	v_exp_f32_e32 v135, v135
	v_exp_f32_e32 v136, v136
	v_mul_f32_e32 v134, v56, v131
	v_mul_f32_e32 v131, v61, v132
	v_add_f32_e32 v132, 1.0, v133
	v_mul_f32_e32 v133, 0xbfb8aa3b, v62
	v_exp_f32_e32 v133, v133
	v_mul_f32_e32 v137, 0xbfb8aa3b, v59
	v_exp_f32_e32 v137, v137
	v_add_f32_e32 v130, 1.0, v138
	v_add_f32_e32 v133, 1.0, v133
	v_rcp_f32_e32 v130, v130
	v_rcp_f32_e32 v133, v133
	v_add_f32_e32 v135, 1.0, v135
	v_add_f32_e32 v136, 1.0, v136
	v_rcp_f32_e32 v132, v132
	v_rcp_f32_e32 v135, v135
	v_rcp_f32_e32 v136, v136
	v_add_f32_e32 v137, 1.0, v137
	v_rcp_f32_e32 v137, v137
	v_mul_f32_e32 v130, v60, v130
	v_mul_f32_e32 v133, v62, v133
	v_mul_f32_e32 v132, v57, v132
	v_mul_f32_e32 v135, v58, v135
	v_mul_f32_e32 v136, v63, v136
	v_cvt_pk_bf16_f32 v130, v130, v131
	v_cvt_pk_bf16_f32 v131, v133, v136
	v_mul_f32_e32 v133, 0xbfb8aa3b, v48
	v_mul_f32_e32 v137, v59, v137
	v_cvt_pk_bf16_f32 v132, v134, v132
	v_exp_f32_e32 v136, v133
	v_cvt_pk_bf16_f32 v133, v135, v137
	v_lshl_add_u64 v[134:135], v[128:129], 0, s[66:67]
	global_store_dwordx4 v[134:135], v[130:133], off offset:-3072 sc1
	v_mul_f32_e32 v138, 0xbfb8aa3b, v51
	v_mul_f32_e32 v137, 0xbfb8aa3b, v42
	v_mul_f32_e32 v131, 0xbfb8aa3b, v40
	v_mul_f32_e32 v132, 0xbfb8aa3b, v49
	v_exp_f32_e32 v131, v131
	v_exp_f32_e32 v132, v132
	v_mul_f32_e32 v133, 0xbfb8aa3b, v41
	v_exp_f32_e32 v133, v133
	v_add_f32_e32 v131, 1.0, v131
	v_add_f32_e32 v132, 1.0, v132
	v_rcp_f32_e32 v131, v131
	v_rcp_f32_e32 v132, v132
	v_add_f32_e32 v130, 1.0, v136
	v_exp_f32_e32 v138, v138
	v_mul_f32_e32 v136, v40, v131
	v_mul_f32_e32 v131, v49, v132
	v_add_f32_e32 v132, 1.0, v133
	v_mul_f32_e32 v133, 0xbfb8aa3b, v50
	v_exp_f32_e32 v133, v133
	v_mul_f32_e32 v139, 0xbfb8aa3b, v43
	v_exp_f32_e32 v137, v137
	v_exp_f32_e32 v139, v139
	v_add_f32_e32 v133, 1.0, v133
	v_rcp_f32_e32 v130, v130
	v_rcp_f32_e32 v132, v132
	v_rcp_f32_e32 v133, v133
	v_add_f32_e32 v138, 1.0, v138
	v_add_f32_e32 v137, 1.0, v137
	v_rcp_f32_e32 v138, v138
	v_add_f32_e32 v139, 1.0, v139
	v_rcp_f32_e32 v137, v137
	v_rcp_f32_e32 v139, v139
	v_mul_f32_e32 v130, v48, v130
	v_mul_f32_e32 v132, v41, v132
	v_mul_f32_e32 v133, v50, v133
	v_mul_f32_e32 v138, v51, v138
	v_cvt_pk_bf16_f32 v130, v130, v131
	v_cvt_pk_bf16_f32 v131, v133, v138
	v_mul_f32_e32 v133, 0xbfb8aa3b, v52
	v_cvt_pk_bf16_f32 v132, v136, v132
	v_mul_f32_e32 v137, v42, v137
	v_mul_f32_e32 v139, v43, v139
	v_exp_f32_e32 v138, v133
	v_cvt_pk_bf16_f32 v133, v137, v139
	global_store_dwordx4 v[134:135], v[130:133], off offset:-2816 sc1
	v_mul_f32_e32 v135, 0xbfb8aa3b, v46
	v_mul_f32_e32 v136, 0xbfb8aa3b, v55
	v_mul_f32_e32 v131, 0xbfb8aa3b, v44
	v_mul_f32_e32 v132, 0xbfb8aa3b, v53
	v_exp_f32_e32 v131, v131
	v_exp_f32_e32 v132, v132
	v_mul_f32_e32 v133, 0xbfb8aa3b, v45
	v_exp_f32_e32 v133, v133
	v_add_f32_e32 v131, 1.0, v131
	v_add_f32_e32 v132, 1.0, v132
	v_rcp_f32_e32 v131, v131
	v_rcp_f32_e32 v132, v132
	v_exp_f32_e32 v135, v135
	v_exp_f32_e32 v136, v136
	v_mul_f32_e32 v134, v44, v131
	v_mul_f32_e32 v131, v53, v132
	v_add_f32_e32 v132, 1.0, v133
	v_mul_f32_e32 v133, 0xbfb8aa3b, v54
	v_exp_f32_e32 v133, v133
	v_mul_f32_e32 v137, 0xbfb8aa3b, v47
	v_exp_f32_e32 v137, v137
	v_add_f32_e32 v130, 1.0, v138
	v_add_f32_e32 v133, 1.0, v133
	v_rcp_f32_e32 v130, v130
	v_rcp_f32_e32 v133, v133
	v_add_f32_e32 v135, 1.0, v135
	v_add_f32_e32 v136, 1.0, v136
	v_rcp_f32_e32 v132, v132
	v_rcp_f32_e32 v135, v135
	v_rcp_f32_e32 v136, v136
	v_add_f32_e32 v137, 1.0, v137
	v_rcp_f32_e32 v137, v137
	v_mul_f32_e32 v130, v52, v130
	v_mul_f32_e32 v133, v54, v133
	v_mul_f32_e32 v132, v45, v132
	v_mul_f32_e32 v135, v46, v135
	v_mul_f32_e32 v136, v55, v136
	v_cvt_pk_bf16_f32 v130, v130, v131
	v_cvt_pk_bf16_f32 v131, v133, v136
	v_mul_f32_e32 v133, 0xbfb8aa3b, v32
	s_mov_b64 s[4:5], 0x24000
	v_mul_f32_e32 v137, v47, v137
	v_cvt_pk_bf16_f32 v132, v134, v132
	v_exp_f32_e32 v136, v133
	v_cvt_pk_bf16_f32 v133, v135, v137
	v_lshl_add_u64 v[134:135], v[128:129], 0, s[4:5]
	global_store_dwordx4 v[134:135], v[130:133], off offset:-3072 sc1
	v_mul_f32_e32 v138, 0xbfb8aa3b, v35
	v_mul_f32_e32 v137, 0xbfb8aa3b, v26
	v_mul_f32_e32 v131, 0xbfb8aa3b, v24
	v_mul_f32_e32 v132, 0xbfb8aa3b, v33
	v_exp_f32_e32 v131, v131
	v_exp_f32_e32 v132, v132
	v_mul_f32_e32 v133, 0xbfb8aa3b, v25
	v_exp_f32_e32 v133, v133
	v_add_f32_e32 v131, 1.0, v131
	v_add_f32_e32 v132, 1.0, v132
	v_rcp_f32_e32 v131, v131
	v_rcp_f32_e32 v132, v132
	v_add_f32_e32 v130, 1.0, v136
	v_exp_f32_e32 v138, v138
	v_mul_f32_e32 v136, v24, v131
; __device__ __forceinline__ u32x4 pack8(const f32x4& a, const f32x4& b) { u32x4 w; w.x = cvt_pk_bf16(a[0], a[1]); w.y = cvt_pk_bf16(a[2], a[3]); w.z = cvt_pk_bf16(b[0], b[1]); w.w = cvt_pk_bf16(b[2], b[3]); return w; }
; __device__ __forceinline__ float fexp(float x) { return __builtin_amdgcn_exp2f(x * 1.4426950408889634f); }
; __device__ __forceinline__ float frcp(float x) { return __builtin_amdgcn_rcpf(x); }
;     __device__ __forceinline__ void operator()(Acc& acc, const Unit& u, int wr, int wc, int fr, int fq) const {
;     ...
; #pragma unroll
;             for (int ai = 0; ai < 2; ++ai)
; #pragma unroll
;                 for (int m = 0; m < 4; ++m)
; #pragma unroll
;                     for (int bj = 0; bj < 2; ++bj) { f32x4 a = acc[ai][bj][m][0], b = acc[ai][bj][m][1];
; #pragma unroll
;                         for (int i = 0; i < 4; ++i) { a[i] = a[i] * frcp(1.0f + fexp(-a[i])); b[i] = b[i] * frcp(1.0f + fexp(-b[i])); }
;                         *(u32x4*)(SG + (size_t)(row0 + ai * HALF + m * 16) * 512 + (pn - 6) * 256 + bj * HALF + cw) = pack8(a, b); }
	v_mul_f32_e32 v131, v33, v132
	v_add_f32_e32 v132, 1.0, v133
	v_mul_f32_e32 v133, 0xbfb8aa3b, v34
	v_exp_f32_e32 v133, v133
	v_mul_f32_e32 v139, 0xbfb8aa3b, v27
	v_exp_f32_e32 v137, v137
	v_exp_f32_e32 v139, v139
	v_add_f32_e32 v133, 1.0, v133
	v_rcp_f32_e32 v130, v130
	v_rcp_f32_e32 v132, v132
	v_rcp_f32_e32 v133, v133
	v_add_f32_e32 v138, 1.0, v138
	v_add_f32_e32 v137, 1.0, v137
	v_rcp_f32_e32 v138, v138
	v_add_f32_e32 v139, 1.0, v139
	v_rcp_f32_e32 v137, v137
	v_rcp_f32_e32 v139, v139
	v_mul_f32_e32 v130, v32, v130
	v_mul_f32_e32 v132, v25, v132
	v_mul_f32_e32 v133, v34, v133
	v_mul_f32_e32 v138, v35, v138
	v_cvt_pk_bf16_f32 v130, v130, v131
	v_cvt_pk_bf16_f32 v131, v133, v138
	v_mul_f32_e32 v133, 0xbfb8aa3b, v36
	v_cvt_pk_bf16_f32 v132, v136, v132
	v_mul_f32_e32 v137, v26, v137
	v_mul_f32_e32 v139, v27, v139
	v_exp_f32_e32 v138, v133
	v_cvt_pk_bf16_f32 v133, v137, v139
	global_store_dwordx4 v[134:135], v[130:133], off offset:-2816 sc1
	v_mul_f32_e32 v135, 0xbfb8aa3b, v30
	v_mul_f32_e32 v136, 0xbfb8aa3b, v39
	v_mul_f32_e32 v131, 0xbfb8aa3b, v28
	v_mul_f32_e32 v132, 0xbfb8aa3b, v37
	v_exp_f32_e32 v131, v131
	v_exp_f32_e32 v132, v132
	v_mul_f32_e32 v133, 0xbfb8aa3b, v29
	v_exp_f32_e32 v133, v133
	v_add_f32_e32 v131, 1.0, v131
	v_add_f32_e32 v132, 1.0, v132
	v_rcp_f32_e32 v131, v131
	v_rcp_f32_e32 v132, v132
	v_exp_f32_e32 v135, v135
	v_exp_f32_e32 v136, v136
	v_mul_f32_e32 v134, v28, v131
	v_mul_f32_e32 v131, v37, v132
	v_add_f32_e32 v132, 1.0, v133
	v_mul_f32_e32 v133, 0xbfb8aa3b, v38
	v_exp_f32_e32 v133, v133
	v_mul_f32_e32 v137, 0xbfb8aa3b, v31
	v_exp_f32_e32 v137, v137
	v_add_f32_e32 v130, 1.0, v138
	v_add_f32_e32 v133, 1.0, v133
	v_rcp_f32_e32 v130, v130
	v_rcp_f32_e32 v133, v133
	v_add_f32_e32 v135, 1.0, v135
	v_add_f32_e32 v136, 1.0, v136
	v_rcp_f32_e32 v132, v132
	v_rcp_f32_e32 v135, v135
	v_rcp_f32_e32 v136, v136
	v_add_f32_e32 v137, 1.0, v137
	v_rcp_f32_e32 v137, v137
	v_mul_f32_e32 v130, v36, v130
	v_mul_f32_e32 v133, v38, v133
	v_mul_f32_e32 v132, v29, v132
	v_mul_f32_e32 v135, v30, v135
	v_mul_f32_e32 v136, v39, v136
	v_cvt_pk_bf16_f32 v130, v130, v131
	v_cvt_pk_bf16_f32 v131, v133, v136
	v_mul_f32_e32 v133, 0xbfb8aa3b, v16
	s_mov_b64 s[4:5], 0x28000
	v_mul_f32_e32 v137, v31, v137
	v_cvt_pk_bf16_f32 v132, v134, v132
	v_exp_f32_e32 v136, v133
	v_cvt_pk_bf16_f32 v133, v135, v137
	v_lshl_add_u64 v[134:135], v[128:129], 0, s[4:5]
	global_store_dwordx4 v[134:135], v[130:133], off offset:-3072 sc1
	v_mul_f32_e32 v138, 0xbfb8aa3b, v19
	v_mul_f32_e32 v137, 0xbfb8aa3b, v10
	v_mul_f32_e32 v131, 0xbfb8aa3b, v8
	v_mul_f32_e32 v132, 0xbfb8aa3b, v17
	v_exp_f32_e32 v131, v131
	v_exp_f32_e32 v132, v132
	v_mul_f32_e32 v133, 0xbfb8aa3b, v9
	v_exp_f32_e32 v133, v133
	v_add_f32_e32 v131, 1.0, v131
	v_add_f32_e32 v132, 1.0, v132
	v_rcp_f32_e32 v131, v131
	v_rcp_f32_e32 v132, v132
	v_add_f32_e32 v130, 1.0, v136
	v_exp_f32_e32 v138, v138
	v_mul_f32_e32 v136, v8, v131
	v_mul_f32_e32 v131, v17, v132
	v_add_f32_e32 v132, 1.0, v133
	v_mul_f32_e32 v133, 0xbfb8aa3b, v18
	v_exp_f32_e32 v133, v133
	v_mul_f32_e32 v139, 0xbfb8aa3b, v11
	v_exp_f32_e32 v137, v137
	v_exp_f32_e32 v139, v139
	v_add_f32_e32 v133, 1.0, v133
	v_rcp_f32_e32 v130, v130
	v_rcp_f32_e32 v132, v132
	v_rcp_f32_e32 v133, v133
	v_add_f32_e32 v138, 1.0, v138
	v_add_f32_e32 v137, 1.0, v137
	v_rcp_f32_e32 v138, v138
	v_add_f32_e32 v139, 1.0, v139
	v_rcp_f32_e32 v137, v137
	v_rcp_f32_e32 v139, v139
	v_mul_f32_e32 v130, v16, v130
	v_mul_f32_e32 v132, v9, v132
	v_mul_f32_e32 v133, v18, v133
	v_mul_f32_e32 v138, v19, v138
	v_cvt_pk_bf16_f32 v130, v130, v131
	v_cvt_pk_bf16_f32 v131, v133, v138
	v_mul_f32_e32 v133, 0xbfb8aa3b, v20
	v_cvt_pk_bf16_f32 v132, v136, v132
	v_mul_f32_e32 v137, v10, v137
	v_mul_f32_e32 v139, v11, v139
	v_exp_f32_e32 v138, v133
	v_cvt_pk_bf16_f32 v133, v137, v139
	global_store_dwordx4 v[134:135], v[130:133], off offset:-2816 sc1
	v_mul_f32_e32 v135, 0xbfb8aa3b, v14
	v_mul_f32_e32 v136, 0xbfb8aa3b, v23
	v_mul_f32_e32 v131, 0xbfb8aa3b, v12
	v_mul_f32_e32 v132, 0xbfb8aa3b, v21
	v_exp_f32_e32 v131, v131
	v_exp_f32_e32 v132, v132
	v_mul_f32_e32 v133, 0xbfb8aa3b, v13
	v_exp_f32_e32 v133, v133
	v_add_f32_e32 v131, 1.0, v131
	v_add_f32_e32 v132, 1.0, v132
	v_rcp_f32_e32 v131, v131
	v_rcp_f32_e32 v132, v132
	v_exp_f32_e32 v135, v135
	v_exp_f32_e32 v136, v136
	v_mul_f32_e32 v134, v12, v131
	v_mul_f32_e32 v131, v21, v132
	v_add_f32_e32 v132, 1.0, v133
	v_mul_f32_e32 v133, 0xbfb8aa3b, v22
	v_exp_f32_e32 v133, v133
	v_mul_f32_e32 v137, 0xbfb8aa3b, v15
	v_exp_f32_e32 v137, v137
	v_add_f32_e32 v130, 1.0, v138
	v_add_f32_e32 v133, 1.0, v133
	v_rcp_f32_e32 v130, v130
	v_rcp_f32_e32 v133, v133
	v_add_f32_e32 v135, 1.0, v135
	v_add_f32_e32 v136, 1.0, v136
	v_rcp_f32_e32 v132, v132
	v_rcp_f32_e32 v135, v135
	v_rcp_f32_e32 v136, v136
	v_add_f32_e32 v137, 1.0, v137
	v_rcp_f32_e32 v137, v137
	v_mul_f32_e32 v130, v20, v130
	v_mul_f32_e32 v133, v22, v133
	v_mul_f32_e32 v132, v13, v132
	v_mul_f32_e32 v135, v14, v135
	v_mul_f32_e32 v136, v23, v136
	v_cvt_pk_bf16_f32 v130, v130, v131
	v_cvt_pk_bf16_f32 v131, v133, v136
	v_mul_f32_e32 v133, 0xbfb8aa3b, v4
	s_mov_b64 s[4:5], 0x2c000
	v_mul_f32_e32 v137, v15, v137
	v_cvt_pk_bf16_f32 v132, v134, v132
	v_exp_f32_e32 v136, v133
	v_cvt_pk_bf16_f32 v133, v135, v137
	v_lshl_add_u64 v[134:135], v[128:129], 0, s[4:5]
	global_store_dwordx4 v[134:135], v[130:133], off offset:-3072 sc1
	v_mul_f32_e32 v129, 0xbfb8aa3b, v0
	v_exp_f32_e32 v129, v129
	v_mul_f32_e32 v130, 0xbfb8aa3b, v5
	v_exp_f32_e32 v130, v130
	v_mul_f32_e32 v131, 0xbfb8aa3b, v1
	v_add_f32_e32 v129, 1.0, v129
	v_rcp_f32_e32 v129, v129
	v_add_f32_e32 v130, 1.0, v130
	v_rcp_f32_e32 v130, v130
	v_exp_f32_e32 v131, v131
	v_mul_f32_e32 v132, v0, v129
	v_add_f32_e32 v128, 1.0, v136
	v_mul_f32_e32 v129, v5, v130
	v_add_f32_e32 v130, 1.0, v131
	v_mul_f32_e32 v131, 0xbfb8aa3b, v6
	v_exp_f32_e32 v131, v131
	v_mul_f32_e32 v133, 0xbfb8aa3b, v2
	v_mul_f32_e32 v136, 0xbfb8aa3b, v7
	v_mul_f32_e32 v137, 0xbfb8aa3b, v3
	v_exp_f32_e32 v133, v133
	v_exp_f32_e32 v136, v136
	v_exp_f32_e32 v137, v137
	v_add_f32_e32 v131, 1.0, v131
	v_rcp_f32_e32 v128, v128
	v_rcp_f32_e32 v130, v130
	v_rcp_f32_e32 v131, v131
	v_add_f32_e32 v133, 1.0, v133
	v_add_f32_e32 v136, 1.0, v136
	v_add_f32_e32 v137, 1.0, v137
	v_rcp_f32_e32 v133, v133
	v_rcp_f32_e32 v136, v136
	v_rcp_f32_e32 v137, v137
	v_mul_f32_e32 v128, v4, v128
	v_mul_f32_e32 v130, v1, v130
	v_mul_f32_e32 v131, v6, v131
	v_mul_f32_e32 v133, v2, v133
	v_mul_f32_e32 v136, v7, v136
	v_mul_f32_e32 v137, v3, v137
	v_cvt_pk_bf16_f32 v128, v128, v129
	v_cvt_pk_bf16_f32 v129, v131, v136
	v_cvt_pk_bf16_f32 v130, v132, v130
	v_cvt_pk_bf16_f32 v131, v133, v137
	global_store_dwordx4 v[134:135], v[128:131], off offset:-2816 sc1

; __device__ __forceinline__ u32x4 pack8(const f32x4& a, const f32x4& b) { u32x4 w; w.x = cvt_pk_bf16(a[0], a[1]); w.y = cvt_pk_bf16(a[2], a[3]); w.z = cvt_pk_bf16(b[0], b[1]); w.w = cvt_pk_bf16(b[2], b[3]); return w; }
;     __device__ __forceinline__ void operator()(Acc& acc, const Unit& u, int wr, int wc, int fr, int fq) const {
;     ...
; #pragma unroll
;             for (int ai = 0; ai < 2; ++ai)
; #pragma unroll
;                 for (int m = 0; m < 4; ++m)
; #pragma unroll
;                     for (int bj = 0; bj < 2; ++bj) *(u32x4*)(V + (size_t)(row0 + ai * HALF + m * 16) * 512 + (pn - 4) * 256 + bj * HALF + cw) = pack8(acc[ai][bj][m][0], acc[ai][bj][m][1]);
.LBB0_187:
	s_andn2_b64 vcc, exec, s[4:5]
	s_cbranch_vccnz .LBB0_189
	v_ashrrev_i32_e32 v175, 31, v174
	v_lshlrev_b64 v[132:133], 10, v[174:175]
	v_lshl_add_u64 v[132:133], s[62:63], 0, v[132:133]
	s_lshl_b32 s12, s40, 9
	v_ashrrev_i32_e32 v173, 31, v172
	v_lshl_add_u64 v[132:133], v[132:133], 0, s[12:13]
	v_cvt_pk_bf16_f32 v128, v124, v125
	v_cvt_pk_bf16_f32 v129, v126, v127
	v_cvt_pk_bf16_f32 v130, v120, v121
	v_cvt_pk_bf16_f32 v131, v122, v123
	v_lshl_add_u64 v[132:133], v[172:173], 1, v[132:133]
	global_store_dwordx4 v[132:133], v[128:131], off offset:-2048 sc1
	v_lshl_add_u64 v[134:135], v[132:133], 0, s[60:61]
	s_mov_b64 s[4:5], 0x24000
	v_cvt_pk_bf16_f32 v128, v112, v113
	v_cvt_pk_bf16_f32 v129, v114, v115
	v_cvt_pk_bf16_f32 v130, v104, v105
	v_cvt_pk_bf16_f32 v131, v106, v107
	global_store_dwordx4 v[132:133], v[128:131], off offset:-1792 sc1
	s_nop 1
	v_cvt_pk_bf16_f32 v128, v116, v117
	v_cvt_pk_bf16_f32 v129, v118, v119
	v_cvt_pk_bf16_f32 v130, v108, v109
	v_cvt_pk_bf16_f32 v131, v110, v111
	global_store_dwordx4 v[134:135], v[128:131], off offset:-2048 sc1
	s_nop 1
	v_cvt_pk_bf16_f32 v128, v96, v97
	v_cvt_pk_bf16_f32 v129, v98, v99
	v_cvt_pk_bf16_f32 v130, v88, v89
	v_cvt_pk_bf16_f32 v131, v90, v91
	global_store_dwordx4 v[134:135], v[128:131], off offset:-1792 sc1
	v_lshl_add_u64 v[134:135], v[132:133], 0, s[24:25]
	s_nop 0
	v_cvt_pk_bf16_f32 v128, v100, v101
	v_cvt_pk_bf16_f32 v129, v102, v103
	v_cvt_pk_bf16_f32 v130, v92, v93
	v_cvt_pk_bf16_f32 v131, v94, v95
	global_store_dwordx4 v[134:135], v[128:131], off offset:-2048 sc1
	s_nop 1
	v_cvt_pk_bf16_f32 v128, v80, v81
	v_cvt_pk_bf16_f32 v129, v82, v83
	v_cvt_pk_bf16_f32 v130, v72, v73
	v_cvt_pk_bf16_f32 v131, v74, v75
	global_store_dwordx4 v[134:135], v[128:131], off offset:-1792 sc1
	v_lshl_add_u64 v[134:135], v[132:133], 0, s[64:65]
	s_nop 0
	v_cvt_pk_bf16_f32 v128, v84, v85
	v_cvt_pk_bf16_f32 v129, v86, v87
	v_cvt_pk_bf16_f32 v130, v76, v77
	v_cvt_pk_bf16_f32 v131, v78, v79
	global_store_dwordx4 v[134:135], v[128:131], off offset:-2048 sc1
	s_nop 1
	v_cvt_pk_bf16_f32 v128, v68, v69
	v_cvt_pk_bf16_f32 v129, v70, v71
	v_cvt_pk_bf16_f32 v130, v64, v65
	v_cvt_pk_bf16_f32 v131, v66, v67
	global_store_dwordx4 v[134:135], v[128:131], off offset:-1792 sc1
	v_lshl_add_u64 v[134:135], v[132:133], 0, s[66:67]
	s_nop 0
	v_cvt_pk_bf16_f32 v128, v60, v61
	v_cvt_pk_bf16_f32 v129, v62, v63
	v_cvt_pk_bf16_f32 v130, v56, v57
	v_cvt_pk_bf16_f32 v131, v58, v59
	global_store_dwordx4 v[134:135], v[128:131], off offset:-2048 sc1
	s_nop 1
	v_cvt_pk_bf16_f32 v128, v48, v49
	v_cvt_pk_bf16_f32 v129, v50, v51
	v_cvt_pk_bf16_f32 v130, v40, v41
	v_cvt_pk_bf16_f32 v131, v42, v43
	global_store_dwordx4 v[134:135], v[128:131], off offset:-1792 sc1
	v_lshl_add_u64 v[134:135], v[132:133], 0, s[4:5]
	s_mov_b64 s[4:5], 0x28000
	v_cvt_pk_bf16_f32 v128, v52, v53
	v_cvt_pk_bf16_f32 v129, v54, v55
	v_cvt_pk_bf16_f32 v130, v44, v45
	v_cvt_pk_bf16_f32 v131, v46, v47
	global_store_dwordx4 v[134:135], v[128:131], off offset:-2048 sc1
	s_nop 1
	v_cvt_pk_bf16_f32 v128, v32, v33
	v_cvt_pk_bf16_f32 v129, v34, v35
	v_cvt_pk_bf16_f32 v130, v24, v25
	v_cvt_pk_bf16_f32 v131, v26, v27
	global_store_dwordx4 v[134:135], v[128:131], off offset:-1792 sc1
	v_lshl_add_u64 v[134:135], v[132:133], 0, s[4:5]
	s_mov_b64 s[4:5], 0x2c000
	v_cvt_pk_bf16_f32 v128, v36, v37
	v_cvt_pk_bf16_f32 v129, v38, v39
	v_cvt_pk_bf16_f32 v130, v28, v29
	v_cvt_pk_bf16_f32 v131, v30, v31
	global_store_dwordx4 v[134:135], v[128:131], off offset:-2048 sc1
	v_lshl_add_u64 v[132:133], v[132:133], 0, s[4:5]
	s_nop 0
	v_cvt_pk_bf16_f32 v128, v16, v17
	v_cvt_pk_bf16_f32 v129, v18, v19
	v_cvt_pk_bf16_f32 v130, v8, v9
	v_cvt_pk_bf16_f32 v131, v10, v11
	global_store_dwordx4 v[134:135], v[128:131], off offset:-1792 sc1
	s_nop 1
	v_cvt_pk_bf16_f32 v128, v20, v21
	v_cvt_pk_bf16_f32 v129, v22, v23
	v_cvt_pk_bf16_f32 v130, v12, v13
	v_cvt_pk_bf16_f32 v131, v14, v15
	global_store_dwordx4 v[132:133], v[128:131], off offset:-2048 sc1
	s_nop 1
	v_cvt_pk_bf16_f32 v128, v4, v5
	v_cvt_pk_bf16_f32 v129, v6, v7
	v_cvt_pk_bf16_f32 v130, v0, v1
	v_cvt_pk_bf16_f32 v131, v2, v3
	global_store_dwordx4 v[132:133], v[128:131], off offset:-1792 sc1

; __device__ __forceinline__ float fexp(float x) { return __builtin_amdgcn_exp2f(x * 1.4426950408889634f); }
; __device__ __forceinline__ float frcp(float x) { return __builtin_amdgcn_rcpf(x); }
;     __device__ __forceinline__ void operator()(Acc& acc, const Unit& u, int wr, int wc, int fr, int fq) const {
;     ...
;         if (pn < 4 && !(DIS_MASK & 1)) {
;             const int hk0 = pn * 128 + cw;
;             const f32x4 lb4[2] = {*(const f32x4*)(LB + hk0), *(const f32x4*)(LB + hk0 + 4)};
; #pragma unroll
;             for (int ai = 0; ai < 2; ++ai) {
;                 f32x4 el[2];
; #pragma unroll
;                 for (int n = 0; n < 2; ++n)
; #pragma unroll
;                     for (int i = 0; i < 4; ++i) {
;                         const float lbv = lb4[n][i], oml = 1.0f - lbv;
;                         float carry = 1.f;
; #pragma unroll
;                         for (int m = 0; m < 4; ++m) {
;                             float x = acc[ai][1][m][n][i]; x = fminf(fmaxf(x, -30.f), 30.f);
;                             const float ex = fexp(-x), s = frcp(1.0f + ex);
;                             const float f = lbv + oml * s, kk = oml * ex * s;
;                             const float p = row16_prefix_mul(f);
;                             const float eb = carry * p;
;                             carry *= __shfl(p, 15, 16);
;                             float qv = acc[ai][0][m][n][i] * eb, kv = kk * frcp(eb);
;                             asm volatile("" : "+v"(qv), "+v"(kv));
;                             acc[ai][0][m][n][i] = qv; acc[ai][1][m][n][i] = kv;
;                         }
;                         el[n][i] = carry;
;                         __builtin_amdgcn_sched_barrier(0);
;                     }
.LBB0_190:
	s_andn2_b64 vcc, exec, s[4:5]
	s_cbranch_vccnz .LBB0_196
	v_lshl_add_u32 v136, s40, 7, v172
	v_readlane_b32 s4, v254, 55
	v_ashrrev_i32_e32 v137, 31, v136
	v_readlane_b32 s5, v254, 56
	v_max_f32_e32 v138, v112, v112
	v_med3_f32 v138, v138, s36, v218
	v_lshl_add_u64 v[132:133], v[136:137], 2, s[4:5]
	global_load_dwordx4 v[128:131], v[132:133], off offset:16
	s_nop 0
	global_load_dwordx4 v[132:135], v[132:133], off
	v_mul_f32_e32 v138, 0xbfb8aa3b, v138
	v_exp_f32_e32 v138, v138
	v_lshl_or_b32 v154, v217, 2, 60
	v_max_f32_e32 v143, v113, v113
	v_med3_f32 v143, v143, s36, v218
	v_add_f32_e32 v139, 1.0, v138
	v_rcp_f32_e32 v139, v139
	v_mul_f32_e32 v143, 0xbfb8aa3b, v143
	v_exp_f32_e32 v143, v143
	v_cmp_eq_u32_e32 vcc, 0, v219
	v_add_f32_e32 v144, 1.0, v143
	v_rcp_f32_e32 v144, v144
	s_waitcnt vmcnt(0)
	v_sub_f32_e32 v155, 1.0, v132
	v_mul_f32_e32 v138, v138, v155
	v_fma_f32 v140, v139, v155, v132
	v_mul_f32_e32 v138, v139, v138
	v_mov_b32_e32 v139, 1.0
	v_sub_f32_e32 v173, 1.0, v133
	v_mul_f32_e32 v143, v143, v173
	v_mov_b32_dpp v139, v140 row_shr:1 row_mask:0xf bank_mask:0xf
	v_mul_f32_e32 v139, v140, v139
	v_mov_b32_e32 v140, 1.0
	v_fma_f32 v145, v144, v173, v133
	v_mul_f32_e32 v143, v144, v143
	v_mov_b32_dpp v140, v139 row_shr:2 row_mask:0xf bank_mask:0xf
	v_mul_f32_e32 v139, v139, v140
	v_mov_b32_e32 v140, 1.0
	v_max_f32_e32 v144, v97, v97
	v_med3_f32 v144, v144, s36, v218
	v_mov_b32_dpp v140, v139 row_shr:4 row_mask:0xf bank_mask:0xf
	v_mul_f32_e32 v139, v139, v140
	v_mov_b32_e32 v140, 1.0
	v_mul_f32_e32 v144, 0xbfb8aa3b, v144
	v_exp_f32_e32 v144, v144
	v_mov_b32_dpp v140, v139 row_shr:8 row_mask:0xf bank_mask:0xf
	v_mul_f32_e32 v139, v139, v140
	ds_bpermute_b32 v140, v154, v139
	v_mul_f32_e32 v157, v124, v139
	v_rcp_f32_e32 v139, v139
	v_add_f32_e32 v146, 1.0, v144
	v_rcp_f32_e32 v146, v146
	v_mul_f32_e32 v144, v144, v173
	v_mul_f32_e32 v156, v138, v139
	v_max_f32_e32 v138, v96, v96
	v_med3_f32 v138, v138, s36, v218
	v_mul_f32_e32 v138, 0xbfb8aa3b, v138
	v_exp_f32_e32 v138, v138
	v_fma_f32 v147, v146, v173, v133
	v_mul_f32_e32 v144, v146, v144
	v_max_f32_e32 v146, v81, v81
	v_add_f32_e32 v139, 1.0, v138
	v_rcp_f32_e32 v139, v139
	v_mul_f32_e32 v138, v138, v155
	v_med3_f32 v146, v146, s36, v218
	v_mul_f32_e32 v146, 0xbfb8aa3b, v146
	v_fma_f32 v141, v139, v155, v132
	v_mul_f32_e32 v138, v139, v138
	v_mov_b32_e32 v139, 1.0
	v_exp_f32_e32 v146, v146
	s_nop 0
	v_mov_b32_dpp v139, v141 row_shr:1 row_mask:0xf bank_mask:0xf
	v_mul_f32_e32 v139, v141, v139
	v_mov_b32_e32 v141, 1.0
	v_add_f32_e32 v148, 1.0, v146
	v_rcp_f32_e32 v148, v148
	v_mov_b32_dpp v141, v139 row_shr:2 row_mask:0xf bank_mask:0xf
	v_mul_f32_e32 v139, v139, v141
	v_mov_b32_e32 v141, 1.0
	v_mul_f32_e32 v146, v146, v173
	v_fma_f32 v149, v148, v173, v133
	v_mov_b32_dpp v141, v139 row_shr:4 row_mask:0xf bank_mask:0xf
	v_mul_f32_e32 v139, v139, v141
	v_mov_b32_e32 v141, 1.0
	v_mul_f32_e32 v146, v148, v146
	s_nop 0
	v_mov_b32_dpp v141, v139 row_shr:8 row_mask:0xf bank_mask:0xf
	v_mul_f32_e32 v139, v139, v141
	s_waitcnt lgkmcnt(0)
	v_mul_f32_e32 v141, v139, v140
	ds_bpermute_b32 v139, v154, v139
	v_mul_f32_e32 v159, v116, v141
	s_waitcnt lgkmcnt(0)
	v_mul_f32_e32 v139, v140, v139
	v_rcp_f32_e32 v140, v141
	s_nop 0
	v_mul_f32_e32 v158, v138, v140
	v_max_f32_e32 v138, v80, v80
	v_med3_f32 v138, v138, s36, v218
	v_mul_f32_e32 v138, 0xbfb8aa3b, v138
	v_exp_f32_e32 v138, v138
	s_nop 0
	v_add_f32_e32 v140, 1.0, v138
	v_rcp_f32_e32 v140, v140
	v_mul_f32_e32 v138, v138, v155
	v_fma_f32 v141, v140, v155, v132
	v_mul_f32_e32 v138, v140, v138
	v_mov_b32_e32 v140, 1.0
	s_nop 1
	v_mov_b32_dpp v140, v141 row_shr:1 row_mask:0xf bank_mask:0xf
	v_mul_f32_e32 v140, v141, v140
	v_mov_b32_e32 v141, 1.0
	s_nop 1
	v_mov_b32_dpp v141, v140 row_shr:2 row_mask:0xf bank_mask:0xf
	v_mul_f32_e32 v140, v140, v141
	v_mov_b32_e32 v141, 1.0
	s_nop 1
	v_mov_b32_dpp v141, v140 row_shr:4 row_mask:0xf bank_mask:0xf
	v_mul_f32_e32 v140, v140, v141
	v_mov_b32_e32 v141, 1.0
	s_nop 1
	v_mov_b32_dpp v141, v140 row_shr:8 row_mask:0xf bank_mask:0xf
	v_mul_f32_e32 v140, v140, v141
	v_mul_f32_e32 v141, v139, v140
	v_mul_f32_e32 v177, v100, v141
	v_rcp_f32_e32 v141, v141
	ds_bpermute_b32 v140, v154, v140
	v_mul_f32_e32 v176, v138, v141
	v_max_f32_e32 v138, v68, v68
	v_med3_f32 v138, v138, s36, v218
	v_mul_f32_e32 v138, 0xbfb8aa3b, v138
	v_exp_f32_e32 v138, v138
	s_waitcnt lgkmcnt(0)
	v_mul_f32_e32 v140, v139, v140
	v_add_f32_e32 v141, 1.0, v138
	v_rcp_f32_e32 v141, v141
	v_mul_f32_e32 v138, v138, v155
	v_fma_f32 v142, v141, v155, v132
	v_mul_f32_e32 v141, v141, v138
	v_mov_b32_e32 v138, 1.0
	s_nop 1
	v_mov_b32_dpp v138, v142 row_shr:1 row_mask:0xf bank_mask:0xf
	v_mul_f32_e32 v138, v142, v138
	v_mov_b32_e32 v142, 1.0
	s_nop 1
	v_mov_b32_dpp v142, v138 row_shr:2 row_mask:0xf bank_mask:0xf
	v_mul_f32_e32 v138, v138, v142
	v_mov_b32_e32 v142, 1.0
	s_nop 1
	v_mov_b32_dpp v142, v138 row_shr:4 row_mask:0xf bank_mask:0xf
	v_mul_f32_e32 v138, v138, v142
	v_mov_b32_e32 v142, 1.0
	s_nop 1
	v_mov_b32_dpp v142, v138 row_shr:8 row_mask:0xf bank_mask:0xf
	v_mul_f32_e32 v142, v138, v142
	v_mul_f32_e32 v139, v140, v142
	ds_bpermute_b32 v138, v154, v142
	v_mul_f32_e32 v185, v84, v139
	v_rcp_f32_e32 v139, v139
	s_nop 0
	v_mul_f32_e32 v184, v141, v139
	v_mov_b32_e32 v139, 1.0
	v_mov_b32_e32 v141, 1.0
	v_mov_b32_e32 v142, 1.0
	v_mov_b32_dpp v139, v145 row_shr:1 row_mask:0xf bank_mask:0xf
	v_mul_f32_e32 v139, v145, v139
	s_nop 1
	v_mov_b32_dpp v141, v139 row_shr:2 row_mask:0xf bank_mask:0xf
	v_mul_f32_e32 v139, v139, v141
	v_mov_b32_e32 v141, 1.0
	s_nop 1
	v_mov_b32_dpp v141, v139 row_shr:4 row_mask:0xf bank_mask:0xf
	v_mul_f32_e32 v139, v139, v141
	v_mov_b32_e32 v141, 1.0
	s_nop 1
	v_mov_b32_dpp v141, v139 row_shr:8 row_mask:0xf bank_mask:0xf
	v_mul_f32_e32 v139, v139, v141
	ds_bpermute_b32 v141, v154, v139
	v_mul_f32_e32 v187, v125, v139
	v_rcp_f32_e32 v139, v139
	s_nop 0
	v_mul_f32_e32 v186, v143, v139
	v_mov_b32_e32 v139, 1.0
	s_nop 1
	v_mov_b32_dpp v139, v147 row_shr:1 row_mask:0xf bank_mask:0xf
	v_mul_f32_e32 v139, v147, v139
	s_nop 1
	v_mov_b32_dpp v142, v139 row_shr:2 row_mask:0xf bank_mask:0xf
	v_mul_f32_e32 v139, v139, v142
	v_mov_b32_e32 v142, 1.0
	s_nop 1
	v_mov_b32_dpp v142, v139 row_shr:4 row_mask:0xf bank_mask:0xf
	v_mul_f32_e32 v139, v139, v142
	v_mov_b32_e32 v142, 1.0
	s_nop 1
	v_mov_b32_dpp v142, v139 row_shr:8 row_mask:0xf bank_mask:0xf
	v_mul_f32_e32 v139, v139, v142
	s_waitcnt lgkmcnt(0)
; __device__ __forceinline__ float fexp(float x) { return __builtin_amdgcn_exp2f(x * 1.4426950408889634f); }
; __device__ __forceinline__ float frcp(float x) { return __builtin_amdgcn_rcpf(x); }
;     __device__ __forceinline__ void operator()(Acc& acc, const Unit& u, int wr, int wc, int fr, int fq) const {
;     ...
;                 f32x4 el[2];
; #pragma unroll
;                 for (int n = 0; n < 2; ++n)
; #pragma unroll
;                     for (int i = 0; i < 4; ++i) {
;                         const float lbv = lb4[n][i], oml = 1.0f - lbv;
;                         float carry = 1.f;
; #pragma unroll
;                         for (int m = 0; m < 4; ++m) {
;                             float x = acc[ai][1][m][n][i]; x = fminf(fmaxf(x, -30.f), 30.f);
;                             const float ex = fexp(-x), s = frcp(1.0f + ex);
;                             const float f = lbv + oml * s, kk = oml * ex * s;
;                             const float p = row16_prefix_mul(f);
;                             const float eb = carry * p;
;                             carry *= __shfl(p, 15, 16);
;                             float qv = acc[ai][0][m][n][i] * eb, kv = kk * frcp(eb);
;                             asm volatile("" : "+v"(qv), "+v"(kv));
;                             acc[ai][0][m][n][i] = qv; acc[ai][1][m][n][i] = kv;
;                         }
;                         el[n][i] = carry;
;                         __builtin_amdgcn_sched_barrier(0);
;                     }
	v_mul_f32_e32 v142, v139, v141
	ds_bpermute_b32 v139, v154, v139
	v_mul_f32_e32 v188, v117, v142
	s_waitcnt lgkmcnt(0)
	v_mul_f32_e32 v139, v141, v139
	v_rcp_f32_e32 v141, v142
	v_mov_b32_e32 v142, 1.0
	v_mul_f32_e32 v189, v144, v141
	v_mov_b32_e32 v141, 1.0
	s_nop 1
	v_mov_b32_dpp v141, v149 row_shr:1 row_mask:0xf bank_mask:0xf
	v_mul_f32_e32 v141, v149, v141
	s_nop 1
	v_mov_b32_dpp v142, v141 row_shr:2 row_mask:0xf bank_mask:0xf
	v_mul_f32_e32 v141, v141, v142
	v_mov_b32_e32 v142, 1.0
	s_nop 1
	v_mov_b32_dpp v142, v141 row_shr:4 row_mask:0xf bank_mask:0xf
	v_mul_f32_e32 v141, v141, v142
	v_mov_b32_e32 v142, 1.0
	s_nop 1
	v_mov_b32_dpp v142, v141 row_shr:8 row_mask:0xf bank_mask:0xf
	v_mul_f32_e32 v141, v141, v142
	v_mul_f32_e32 v142, v139, v141
	ds_bpermute_b32 v141, v154, v141
	v_mul_f32_e32 v191, v101, v142
	s_waitcnt lgkmcnt(0)
	v_mul_f32_e32 v141, v139, v141
	v_rcp_f32_e32 v139, v142
	s_nop 0
	v_mul_f32_e32 v190, v146, v139
	v_max_f32_e32 v139, v69, v69
	v_med3_f32 v139, v139, s36, v218
	v_mul_f32_e32 v139, 0xbfb8aa3b, v139
	v_exp_f32_e32 v139, v139
	s_nop 0
	v_add_f32_e32 v142, 1.0, v139
	v_rcp_f32_e32 v142, v142
	v_mul_f32_e32 v139, v139, v173
	v_fma_f32 v143, v142, v173, v133
	v_mul_f32_e32 v142, v142, v139
	v_mov_b32_e32 v139, 1.0
	s_nop 1
	v_mov_b32_dpp v139, v143 row_shr:1 row_mask:0xf bank_mask:0xf
	v_mul_f32_e32 v139, v143, v139
	v_mov_b32_e32 v143, 1.0
	s_nop 1
	v_mov_b32_dpp v143, v139 row_shr:2 row_mask:0xf bank_mask:0xf
	v_mul_f32_e32 v139, v139, v143
	v_mov_b32_e32 v143, 1.0
	s_nop 1
	v_mov_b32_dpp v143, v139 row_shr:4 row_mask:0xf bank_mask:0xf
	v_mul_f32_e32 v139, v139, v143
	v_mov_b32_e32 v143, 1.0
	s_nop 1
	v_mov_b32_dpp v143, v139 row_shr:8 row_mask:0xf bank_mask:0xf
	v_mul_f32_e32 v139, v139, v143
	v_mul_f32_e32 v143, v141, v139
	ds_bpermute_b32 v139, v154, v139
	v_mul_f32_e32 v193, v85, v143
	v_rcp_f32_e32 v143, v143
	s_nop 0
	v_mul_f32_e32 v192, v142, v143
	v_max_f32_e32 v142, v114, v114
	v_med3_f32 v142, v142, s36, v218
	v_mul_f32_e32 v142, 0xbfb8aa3b, v142
	v_exp_f32_e32 v142, v142
	v_sub_f32_e32 v181, 1.0, v134
	v_mov_b32_e32 v143, 1.0
	v_mov_b32_e32 v145, 1.0
	v_add_f32_e32 v144, 1.0, v142
	v_rcp_f32_e32 v144, v144
	v_mov_b32_e32 v146, 1.0
	v_mul_f32_e32 v142, v142, v181
	v_max_f32_e32 v150, v99, v99
	v_fma_f32 v147, v144, v181, v134
	v_mul_f32_e32 v142, v144, v142
	v_mov_b32_e32 v144, 1.0
	v_mov_b32_dpp v143, v147 row_shr:1 row_mask:0xf bank_mask:0xf
	v_mul_f32_e32 v143, v147, v143
	v_max_f32_e32 v151, v83, v83
	v_med3_f32 v150, v150, s36, v218
	v_mov_b32_dpp v145, v143 row_shr:2 row_mask:0xf bank_mask:0xf
	v_mul_f32_e32 v143, v143, v145
	v_max_f32_e32 v145, v98, v98
	v_med3_f32 v145, v145, s36, v218
	v_mul_f32_e32 v145, 0xbfb8aa3b, v145
	v_exp_f32_e32 v145, v145
	v_mov_b32_dpp v146, v143 row_shr:4 row_mask:0xf bank_mask:0xf
	v_mul_f32_e32 v143, v143, v146
	v_med3_f32 v151, v151, s36, v218
	v_add_f32_e32 v147, 1.0, v145
	v_mov_b32_dpp v144, v143 row_shr:8 row_mask:0xf bank_mask:0xf
	v_mul_f32_e32 v143, v143, v144
	v_rcp_f32_e32 v146, v143
	v_rcp_f32_e32 v147, v147
	ds_bpermute_b32 v144, v154, v143
	v_mul_f32_e32 v195, v126, v143
	v_mul_f32_e32 v194, v142, v146
	v_fma_f32 v142, v147, v181, v134
	v_mul_f32_e32 v143, v145, v181
	v_mov_b32_e32 v145, 1.0
	v_max_f32_e32 v146, v82, v82
	v_med3_f32 v146, v146, s36, v218
	v_mov_b32_dpp v145, v142 row_shr:1 row_mask:0xf bank_mask:0xf
	v_mul_f32_e32 v142, v142, v145
	v_mov_b32_e32 v145, 1.0
	v_mul_f32_e32 v146, 0xbfb8aa3b, v146
	v_exp_f32_e32 v146, v146
	v_mov_b32_dpp v145, v142 row_shr:2 row_mask:0xf bank_mask:0xf
	v_mul_f32_e32 v142, v142, v145
	v_mov_b32_e32 v145, 1.0
	v_mul_f32_e32 v143, v147, v143
	v_add_f32_e32 v147, 1.0, v146
	v_mov_b32_dpp v145, v142 row_shr:4 row_mask:0xf bank_mask:0xf
	v_mul_f32_e32 v142, v142, v145
	v_mov_b32_e32 v145, 1.0
	v_rcp_f32_e32 v147, v147
	v_mul_f32_e32 v150, 0xbfb8aa3b, v150
	v_mov_b32_dpp v145, v142 row_shr:8 row_mask:0xf bank_mask:0xf
	v_mul_f32_e32 v142, v142, v145
	ds_bpermute_b32 v145, v154, v142
	s_waitcnt lgkmcnt(1)
	v_mul_f32_e32 v142, v142, v144
	v_mul_f32_e32 v197, v118, v142
	v_mul_f32_e32 v151, 0xbfb8aa3b, v151
	v_exp_f32_e32 v150, v150
	s_waitcnt lgkmcnt(0)
	v_mul_f32_e32 v144, v144, v145
	v_rcp_f32_e32 v145, v142
	v_fma_f32 v142, v147, v181, v134
	v_exp_f32_e32 v151, v151
	v_sub_f32_e32 v178, 1.0, v135
	v_mul_f32_e32 v196, v143, v145
	v_mov_b32_e32 v145, 1.0
	v_mul_f32_e32 v143, v146, v181
	v_mul_f32_e32 v143, v147, v143
	v_mov_b32_dpp v145, v142 row_shr:1 row_mask:0xf bank_mask:0xf
	v_mul_f32_e32 v142, v142, v145
	v_mov_b32_e32 v145, 1.0
	v_add_f32_e32 v152, 1.0, v150
	v_rcp_f32_e32 v152, v152
	v_mov_b32_dpp v145, v142 row_shr:2 row_mask:0xf bank_mask:0xf
	v_mul_f32_e32 v142, v142, v145
	v_mov_b32_e32 v145, 1.0
	v_mul_f32_e32 v150, v150, v178
	v_fma_f32 v153, v152, v178, v135
	v_mov_b32_dpp v145, v142 row_shr:4 row_mask:0xf bank_mask:0xf
	v_mul_f32_e32 v142, v142, v145
	v_mov_b32_e32 v145, 1.0
	v_mul_f32_e32 v150, v152, v150
	s_nop 0
	v_mov_b32_dpp v145, v142 row_shr:8 row_mask:0xf bank_mask:0xf
	v_mul_f32_e32 v142, v142, v145
	v_max_f32_e32 v145, v70, v70
	v_med3_f32 v145, v145, s36, v218
	v_mul_f32_e32 v145, 0xbfb8aa3b, v145
	v_exp_f32_e32 v145, v145
	v_mul_f32_e32 v146, v144, v142
	ds_bpermute_b32 v147, v154, v142
	v_rcp_f32_e32 v142, v146
	v_add_f32_e32 v148, 1.0, v145
	v_rcp_f32_e32 v148, v148
	v_mul_f32_e32 v199, v102, v146
	v_max_f32_e32 v146, v115, v115
	v_med3_f32 v146, v146, s36, v218
	v_mul_f32_e32 v146, 0xbfb8aa3b, v146
	v_mul_f32_e32 v198, v143, v142
	v_fma_f32 v142, v148, v181, v134
	v_mul_f32_e32 v143, v145, v181
	v_mov_b32_e32 v145, 1.0
	v_exp_f32_e32 v146, v146
	v_mul_f32_e32 v143, v148, v143
	v_mov_b32_dpp v145, v142 row_shr:1 row_mask:0xf bank_mask:0xf
	v_mul_f32_e32 v142, v142, v145
	v_mov_b32_e32 v145, 1.0
	v_add_f32_e32 v148, 1.0, v146
	v_rcp_f32_e32 v148, v148
	v_mov_b32_dpp v145, v142 row_shr:2 row_mask:0xf bank_mask:0xf
	v_mul_f32_e32 v142, v142, v145
	v_mov_b32_e32 v145, 1.0
	v_mul_f32_e32 v146, v146, v178
	s_waitcnt lgkmcnt(0)
; __device__ __forceinline__ float fexp(float x) { return __builtin_amdgcn_exp2f(x * 1.4426950408889634f); }
; __device__ __forceinline__ float frcp(float x) { return __builtin_amdgcn_rcpf(x); }
;     __device__ __forceinline__ void operator()(Acc& acc, const Unit& u, int wr, int wc, int fr, int fq) const {
;     ...
;                 f32x4 el[2];
; #pragma unroll
;                 for (int n = 0; n < 2; ++n)
; #pragma unroll
;                     for (int i = 0; i < 4; ++i) {
;                         const float lbv = lb4[n][i], oml = 1.0f - lbv;
;                         float carry = 1.f;
; #pragma unroll
;                         for (int m = 0; m < 4; ++m) {
;                             float x = acc[ai][1][m][n][i]; x = fminf(fmaxf(x, -30.f), 30.f);
;                             const float ex = fexp(-x), s = frcp(1.0f + ex);
;                             const float f = lbv + oml * s, kk = oml * ex * s;
;                             const float p = row16_prefix_mul(f);
;                             const float eb = carry * p;
;                             carry *= __shfl(p, 15, 16);
;                             float qv = acc[ai][0][m][n][i] * eb, kv = kk * frcp(eb);
;                             asm volatile("" : "+v"(qv), "+v"(kv));
;                             acc[ai][0][m][n][i] = qv; acc[ai][1][m][n][i] = kv;
;                         }
;                         el[n][i] = carry;
;                         __builtin_amdgcn_sched_barrier(0);
;                     }
	v_mul_f32_e32 v144, v144, v147
	v_mov_b32_dpp v145, v142 row_shr:4 row_mask:0xf bank_mask:0xf
	v_mul_f32_e32 v142, v142, v145
	v_mov_b32_e32 v145, 1.0
	v_fma_f32 v149, v148, v178, v135
	v_mul_f32_e32 v146, v148, v146
	v_mov_b32_dpp v145, v142 row_shr:8 row_mask:0xf bank_mask:0xf
	v_mul_f32_e32 v145, v142, v145
	ds_bpermute_b32 v142, v154, v145
	v_add_f32_e32 v148, 1.0, v151
	v_mul_f32_e32 v145, v144, v145
	v_rcp_f32_e32 v148, v148
	v_rcp_f32_e32 v147, v145
	v_mul_f32_e32 v151, v151, v178
	v_mul_f32_e32 v201, v86, v145
	v_fma_f32 v152, v148, v178, v135
	v_mul_f32_e32 v148, v148, v151
	v_mul_f32_e32 v200, v143, v147
	v_mov_b32_e32 v143, 1.0
	v_mov_b32_e32 v145, 1.0
	s_nop 0
	v_mov_b32_dpp v143, v149 row_shr:1 row_mask:0xf bank_mask:0xf
	v_mul_f32_e32 v143, v149, v143
	s_nop 1
	v_mov_b32_dpp v145, v143 row_shr:2 row_mask:0xf bank_mask:0xf
	v_mul_f32_e32 v143, v143, v145
	v_mov_b32_e32 v145, 1.0
	s_nop 1
	v_mov_b32_dpp v145, v143 row_shr:4 row_mask:0xf bank_mask:0xf
	v_mul_f32_e32 v143, v143, v145
	v_mov_b32_e32 v145, 1.0
	s_nop 1
	v_mov_b32_dpp v145, v143 row_shr:8 row_mask:0xf bank_mask:0xf
	v_mul_f32_e32 v143, v143, v145
	ds_bpermute_b32 v145, v154, v143
	v_mul_f32_e32 v203, v127, v143
	v_rcp_f32_e32 v143, v143
	s_nop 0
	v_mul_f32_e32 v202, v146, v143
	v_mov_b32_e32 v143, 1.0
	v_mov_b32_e32 v146, 1.0
	s_nop 0
	v_mov_b32_dpp v143, v153 row_shr:1 row_mask:0xf bank_mask:0xf
	v_mul_f32_e32 v143, v153, v143
	s_nop 1
	v_mov_b32_dpp v146, v143 row_shr:2 row_mask:0xf bank_mask:0xf
	v_mul_f32_e32 v143, v143, v146
	v_mov_b32_e32 v146, 1.0
	s_nop 1
	v_mov_b32_dpp v146, v143 row_shr:4 row_mask:0xf bank_mask:0xf
	v_mul_f32_e32 v143, v143, v146
	v_mov_b32_e32 v146, 1.0
	s_nop 1
	v_mov_b32_dpp v146, v143 row_shr:8 row_mask:0xf bank_mask:0xf
	v_mul_f32_e32 v143, v143, v146
	s_waitcnt lgkmcnt(0)
	v_mul_f32_e32 v146, v143, v145
	ds_bpermute_b32 v143, v154, v143
	v_mul_f32_e32 v204, v119, v146
	s_waitcnt lgkmcnt(0)
	v_mul_f32_e32 v143, v145, v143
	v_rcp_f32_e32 v145, v146
	v_mov_b32_e32 v146, 1.0
	v_mul_f32_e32 v205, v150, v145
	v_mov_b32_e32 v145, 1.0
	s_nop 1
	v_mov_b32_dpp v145, v152 row_shr:1 row_mask:0xf bank_mask:0xf
	v_mul_f32_e32 v145, v152, v145
	s_nop 1
	v_mov_b32_dpp v146, v145 row_shr:2 row_mask:0xf bank_mask:0xf
	v_mul_f32_e32 v145, v145, v146
	v_mov_b32_e32 v146, 1.0
	s_nop 1
	v_mov_b32_dpp v146, v145 row_shr:4 row_mask:0xf bank_mask:0xf
	v_mul_f32_e32 v145, v145, v146
	v_mov_b32_e32 v146, 1.0
	s_nop 1
	v_mov_b32_dpp v146, v145 row_shr:8 row_mask:0xf bank_mask:0xf
	v_mul_f32_e32 v145, v145, v146
	v_mul_f32_e32 v146, v143, v145
	ds_bpermute_b32 v145, v154, v145
	v_mul_f32_e32 v207, v103, v146
	s_waitcnt lgkmcnt(0)
	v_mul_f32_e32 v145, v143, v145
	v_rcp_f32_e32 v143, v146
	s_nop 0
	v_mul_f32_e32 v206, v148, v143
	v_max_f32_e32 v143, v71, v71
	v_med3_f32 v143, v143, s36, v218
	v_mul_f32_e32 v143, 0xbfb8aa3b, v143
	v_exp_f32_e32 v143, v143
	s_nop 0
	v_add_f32_e32 v146, 1.0, v143
	v_rcp_f32_e32 v146, v146
	v_mul_f32_e32 v143, v143, v178
	v_fma_f32 v147, v146, v178, v135
	v_mul_f32_e32 v146, v146, v143
	v_mov_b32_e32 v143, 1.0
	s_nop 1
	v_mov_b32_dpp v143, v147 row_shr:1 row_mask:0xf bank_mask:0xf
	v_mul_f32_e32 v143, v147, v143
	v_mov_b32_e32 v147, 1.0
	s_nop 1
	v_mov_b32_dpp v147, v143 row_shr:2 row_mask:0xf bank_mask:0xf
	v_mul_f32_e32 v143, v143, v147
	v_mov_b32_e32 v147, 1.0
	s_nop 1
	v_mov_b32_dpp v147, v143 row_shr:4 row_mask:0xf bank_mask:0xf
	v_mul_f32_e32 v143, v143, v147
	v_mov_b32_e32 v147, 1.0
	s_nop 1
	v_mov_b32_dpp v147, v143 row_shr:8 row_mask:0xf bank_mask:0xf
	v_mul_f32_e32 v143, v143, v147
	v_mul_f32_e32 v147, v145, v143
	ds_bpermute_b32 v143, v154, v143
	v_mul_f32_e32 v220, v87, v147
	v_rcp_f32_e32 v147, v147
	s_nop 0
	v_mul_f32_e32 v219, v146, v147
	v_max_f32_e32 v146, v104, v104
	v_med3_f32 v146, v146, s36, v218
	v_mul_f32_e32 v146, 0xbfb8aa3b, v146
	v_exp_f32_e32 v146, v146
	v_sub_f32_e32 v182, 1.0, v128
	v_mov_b32_e32 v147, 1.0
	v_mov_b32_e32 v149, 1.0
	v_add_f32_e32 v148, 1.0, v146
	v_rcp_f32_e32 v148, v148
	v_mov_b32_e32 v150, 1.0
	v_mul_f32_e32 v146, v146, v182
	v_max_f32_e32 v175, v89, v89
	v_fma_f32 v151, v148, v182, v128
	v_mul_f32_e32 v146, v148, v146
	v_mov_b32_e32 v148, 1.0
	v_mov_b32_dpp v147, v151 row_shr:1 row_mask:0xf bank_mask:0xf
	v_mul_f32_e32 v147, v151, v147
	v_max_f32_e32 v180, v73, v73
	v_med3_f32 v175, v175, s36, v218
	v_mov_b32_dpp v149, v147 row_shr:2 row_mask:0xf bank_mask:0xf
	v_mul_f32_e32 v147, v147, v149
	v_max_f32_e32 v149, v88, v88
	v_med3_f32 v149, v149, s36, v218
	v_mul_f32_e32 v149, 0xbfb8aa3b, v149
	v_exp_f32_e32 v149, v149
	v_mov_b32_dpp v150, v147 row_shr:4 row_mask:0xf bank_mask:0xf
	v_mul_f32_e32 v147, v147, v150
	v_med3_f32 v180, v180, s36, v218
	v_add_f32_e32 v151, 1.0, v149
	v_mov_b32_dpp v148, v147 row_shr:8 row_mask:0xf bank_mask:0xf
	v_mul_f32_e32 v147, v147, v148
	v_rcp_f32_e32 v150, v147
	v_rcp_f32_e32 v151, v151
	ds_bpermute_b32 v148, v154, v147
	v_mul_f32_e32 v222, v120, v147
	v_mul_f32_e32 v221, v146, v150
	v_fma_f32 v146, v151, v182, v128
	v_mul_f32_e32 v147, v149, v182
	v_mov_b32_e32 v149, 1.0
	v_max_f32_e32 v150, v72, v72
	v_med3_f32 v150, v150, s36, v218
	v_mov_b32_dpp v149, v146 row_shr:1 row_mask:0xf bank_mask:0xf
	v_mul_f32_e32 v146, v146, v149
	v_mov_b32_e32 v149, 1.0
	v_mul_f32_e32 v150, 0xbfb8aa3b, v150
	v_exp_f32_e32 v150, v150
	v_mov_b32_dpp v149, v146 row_shr:2 row_mask:0xf bank_mask:0xf
	v_mul_f32_e32 v146, v146, v149
	v_mov_b32_e32 v149, 1.0
	v_mul_f32_e32 v147, v151, v147
	v_add_f32_e32 v151, 1.0, v150
	v_mov_b32_dpp v149, v146 row_shr:4 row_mask:0xf bank_mask:0xf
	v_mul_f32_e32 v146, v146, v149
	v_mov_b32_e32 v149, 1.0
	v_rcp_f32_e32 v151, v151
	v_mul_f32_e32 v175, 0xbfb8aa3b, v175
	v_mov_b32_dpp v149, v146 row_shr:8 row_mask:0xf bank_mask:0xf
	v_mul_f32_e32 v146, v146, v149
	ds_bpermute_b32 v149, v154, v146
	s_waitcnt lgkmcnt(1)
; __device__ __forceinline__ float fexp(float x) { return __builtin_amdgcn_exp2f(x * 1.4426950408889634f); }
; __device__ __forceinline__ float frcp(float x) { return __builtin_amdgcn_rcpf(x); }
;     __device__ __forceinline__ void operator()(Acc& acc, const Unit& u, int wr, int wc, int fr, int fq) const {
;     ...
;                 f32x4 el[2];
; #pragma unroll
;                 for (int n = 0; n < 2; ++n)
; #pragma unroll
;                     for (int i = 0; i < 4; ++i) {
;                         const float lbv = lb4[n][i], oml = 1.0f - lbv;
;                         float carry = 1.f;
; #pragma unroll
;                         for (int m = 0; m < 4; ++m) {
;                             float x = acc[ai][1][m][n][i]; x = fminf(fmaxf(x, -30.f), 30.f);
;                             const float ex = fexp(-x), s = frcp(1.0f + ex);
;                             const float f = lbv + oml * s, kk = oml * ex * s;
;                             const float p = row16_prefix_mul(f);
;                             const float eb = carry * p;
;                             carry *= __shfl(p, 15, 16);
;                             float qv = acc[ai][0][m][n][i] * eb, kv = kk * frcp(eb);
;                             asm volatile("" : "+v"(qv), "+v"(kv));
;                             acc[ai][0][m][n][i] = qv; acc[ai][1][m][n][i] = kv;
;                         }
;                         el[n][i] = carry;
;                         __builtin_amdgcn_sched_barrier(0);
;                     }
	v_mul_f32_e32 v146, v146, v148
	v_mul_f32_e32 v224, v108, v146
	v_mul_f32_e32 v180, 0xbfb8aa3b, v180
	v_exp_f32_e32 v175, v175
	s_waitcnt lgkmcnt(0)
	v_mul_f32_e32 v148, v148, v149
	v_rcp_f32_e32 v149, v146
	v_fma_f32 v146, v151, v182, v128
	v_exp_f32_e32 v180, v180
	v_sub_f32_e32 v179, 1.0, v129
	v_mul_f32_e32 v223, v147, v149
	v_mov_b32_e32 v149, 1.0
	v_mul_f32_e32 v147, v150, v182
	v_mul_f32_e32 v147, v151, v147
	v_mov_b32_dpp v149, v146 row_shr:1 row_mask:0xf bank_mask:0xf
	v_mul_f32_e32 v146, v146, v149
	v_mov_b32_e32 v149, 1.0
	v_add_f32_e32 v183, 1.0, v175
	v_rcp_f32_e32 v183, v183
	v_mov_b32_dpp v149, v146 row_shr:2 row_mask:0xf bank_mask:0xf
	v_mul_f32_e32 v146, v146, v149
	v_mov_b32_e32 v149, 1.0
	v_mul_f32_e32 v175, v175, v179
	v_fma_f32 v232, v183, v179, v129
	v_mov_b32_dpp v149, v146 row_shr:4 row_mask:0xf bank_mask:0xf
	v_mul_f32_e32 v146, v146, v149
	v_mov_b32_e32 v149, 1.0
	v_mul_f32_e32 v175, v183, v175
	s_nop 0
	v_mov_b32_dpp v149, v146 row_shr:8 row_mask:0xf bank_mask:0xf
	v_mul_f32_e32 v146, v146, v149
	v_max_f32_e32 v149, v64, v64
	v_med3_f32 v149, v149, s36, v218
	v_mul_f32_e32 v149, 0xbfb8aa3b, v149
	v_exp_f32_e32 v149, v149
	v_mul_f32_e32 v150, v148, v146
	ds_bpermute_b32 v151, v154, v146
	v_rcp_f32_e32 v146, v150
	v_add_f32_e32 v152, 1.0, v149
	v_rcp_f32_e32 v152, v152
	v_mul_f32_e32 v226, v92, v150
	v_max_f32_e32 v150, v105, v105
	v_med3_f32 v150, v150, s36, v218
	v_mul_f32_e32 v150, 0xbfb8aa3b, v150
	v_mul_f32_e32 v225, v147, v146
	v_fma_f32 v146, v152, v182, v128
	v_mul_f32_e32 v147, v149, v182
	v_mov_b32_e32 v149, 1.0
	v_exp_f32_e32 v150, v150
	v_mul_f32_e32 v147, v152, v147
	v_mov_b32_dpp v149, v146 row_shr:1 row_mask:0xf bank_mask:0xf
	v_mul_f32_e32 v146, v146, v149
	v_mov_b32_e32 v149, 1.0
	v_add_f32_e32 v152, 1.0, v150
	v_rcp_f32_e32 v152, v152
	v_mov_b32_dpp v149, v146 row_shr:2 row_mask:0xf bank_mask:0xf
	v_mul_f32_e32 v146, v146, v149
	v_mov_b32_e32 v149, 1.0
	v_mul_f32_e32 v150, v150, v179
	s_waitcnt lgkmcnt(0)
	v_mul_f32_e32 v148, v148, v151
	v_mov_b32_dpp v149, v146 row_shr:4 row_mask:0xf bank_mask:0xf
	v_mul_f32_e32 v146, v146, v149
	v_mov_b32_e32 v149, 1.0
	v_fma_f32 v153, v152, v179, v129
	v_mul_f32_e32 v150, v152, v150
	v_mov_b32_dpp v149, v146 row_shr:8 row_mask:0xf bank_mask:0xf
	v_mul_f32_e32 v149, v146, v149
	ds_bpermute_b32 v146, v154, v149
	v_add_f32_e32 v152, 1.0, v180
	v_mul_f32_e32 v149, v148, v149
	v_rcp_f32_e32 v152, v152
	v_rcp_f32_e32 v151, v149
	v_mul_f32_e32 v180, v180, v179
	v_mul_f32_e32 v229, v76, v149
	v_fma_f32 v183, v152, v179, v129
	v_mul_f32_e32 v152, v152, v180
	v_mul_f32_e32 v227, v147, v151
	v_mov_b32_e32 v147, 1.0
	v_mov_b32_e32 v149, 1.0
	s_nop 0
	v_mov_b32_dpp v147, v153 row_shr:1 row_mask:0xf bank_mask:0xf
	v_mul_f32_e32 v147, v153, v147
	s_nop 1
	v_mov_b32_dpp v149, v147 row_shr:2 row_mask:0xf bank_mask:0xf
	v_mul_f32_e32 v147, v147, v149
	v_mov_b32_e32 v149, 1.0
	s_nop 1
	v_mov_b32_dpp v149, v147 row_shr:4 row_mask:0xf bank_mask:0xf
	v_mul_f32_e32 v147, v147, v149
	v_mov_b32_e32 v149, 1.0
	s_nop 1
	v_mov_b32_dpp v149, v147 row_shr:8 row_mask:0xf bank_mask:0xf
	v_mul_f32_e32 v147, v147, v149
	ds_bpermute_b32 v149, v154, v147
	v_mul_f32_e32 v231, v121, v147
	v_rcp_f32_e32 v147, v147
	s_nop 0
	v_mul_f32_e32 v230, v150, v147
	v_mov_b32_e32 v147, 1.0
	v_mov_b32_e32 v150, 1.0
	s_nop 0
	v_mov_b32_dpp v147, v232 row_shr:1 row_mask:0xf bank_mask:0xf
	v_mul_f32_e32 v147, v232, v147
	s_nop 1
	v_mov_b32_dpp v150, v147 row_shr:2 row_mask:0xf bank_mask:0xf
	v_mul_f32_e32 v147, v147, v150
	v_mov_b32_e32 v150, 1.0
	s_nop 1
	v_mov_b32_dpp v150, v147 row_shr:4 row_mask:0xf bank_mask:0xf
	v_mul_f32_e32 v147, v147, v150
	v_mov_b32_e32 v150, 1.0
	s_nop 1
	v_mov_b32_dpp v150, v147 row_shr:8 row_mask:0xf bank_mask:0xf
	v_mul_f32_e32 v147, v147, v150
	s_waitcnt lgkmcnt(0)
	v_mul_f32_e32 v150, v147, v149
	ds_bpermute_b32 v147, v154, v147
	v_mul_f32_e32 v232, v109, v150
	s_waitcnt lgkmcnt(0)
	v_mul_f32_e32 v147, v149, v147
	v_rcp_f32_e32 v149, v150
	v_mov_b32_e32 v150, 1.0
	v_mul_f32_e32 v233, v175, v149
	v_mov_b32_e32 v149, 1.0
	s_nop 1
	v_mov_b32_dpp v149, v183 row_shr:1 row_mask:0xf bank_mask:0xf
	v_mul_f32_e32 v149, v183, v149
	s_nop 1
	v_mov_b32_dpp v150, v149 row_shr:2 row_mask:0xf bank_mask:0xf
	v_mul_f32_e32 v149, v149, v150
	v_mov_b32_e32 v150, 1.0
	s_nop 1
	v_mov_b32_dpp v150, v149 row_shr:4 row_mask:0xf bank_mask:0xf
	v_mul_f32_e32 v149, v149, v150
	v_mov_b32_e32 v150, 1.0
	s_nop 1
	v_mov_b32_dpp v150, v149 row_shr:8 row_mask:0xf bank_mask:0xf
	v_mul_f32_e32 v149, v149, v150
	v_mul_f32_e32 v150, v147, v149
	ds_bpermute_b32 v149, v154, v149
	v_mul_f32_e32 v235, v93, v150
	s_waitcnt lgkmcnt(0)
; __device__ __forceinline__ float fexp(float x) { return __builtin_amdgcn_exp2f(x * 1.4426950408889634f); }
; __device__ __forceinline__ float frcp(float x) { return __builtin_amdgcn_rcpf(x); }
;     __device__ __forceinline__ void operator()(Acc& acc, const Unit& u, int wr, int wc, int fr, int fq) const {
;     ...
;                 f32x4 el[2];
; #pragma unroll
;                 for (int n = 0; n < 2; ++n)
; #pragma unroll
;                     for (int i = 0; i < 4; ++i) {
;                         const float lbv = lb4[n][i], oml = 1.0f - lbv;
;                         float carry = 1.f;
; #pragma unroll
;                         for (int m = 0; m < 4; ++m) {
;                             float x = acc[ai][1][m][n][i]; x = fminf(fmaxf(x, -30.f), 30.f);
;                             const float ex = fexp(-x), s = frcp(1.0f + ex);
;                             const float f = lbv + oml * s, kk = oml * ex * s;
;                             const float p = row16_prefix_mul(f);
;                             const float eb = carry * p;
;                             carry *= __shfl(p, 15, 16);
;                             float qv = acc[ai][0][m][n][i] * eb, kv = kk * frcp(eb);
;                             asm volatile("" : "+v"(qv), "+v"(kv));
;                             acc[ai][0][m][n][i] = qv; acc[ai][1][m][n][i] = kv;
;                         }
;                         el[n][i] = carry;
;                         __builtin_amdgcn_sched_barrier(0);
;                     }
	v_mul_f32_e32 v149, v147, v149
	v_rcp_f32_e32 v147, v150
	s_nop 0
	v_mul_f32_e32 v234, v152, v147
	v_max_f32_e32 v147, v65, v65
	v_med3_f32 v147, v147, s36, v218
	v_mul_f32_e32 v147, 0xbfb8aa3b, v147
	v_exp_f32_e32 v147, v147
	s_nop 0
	v_add_f32_e32 v150, 1.0, v147
	v_rcp_f32_e32 v150, v150
	v_mul_f32_e32 v147, v147, v179
	v_fma_f32 v151, v150, v179, v129
	v_mul_f32_e32 v150, v150, v147
	v_mov_b32_e32 v147, 1.0
	s_nop 1
	v_mov_b32_dpp v147, v151 row_shr:1 row_mask:0xf bank_mask:0xf
	v_mul_f32_e32 v147, v151, v147
	v_mov_b32_e32 v151, 1.0
	s_nop 1
	v_mov_b32_dpp v151, v147 row_shr:2 row_mask:0xf bank_mask:0xf
	v_mul_f32_e32 v147, v147, v151
	v_mov_b32_e32 v151, 1.0
	s_nop 1
	v_mov_b32_dpp v151, v147 row_shr:4 row_mask:0xf bank_mask:0xf
	v_mul_f32_e32 v147, v147, v151
	v_mov_b32_e32 v151, 1.0
	s_nop 1
	v_mov_b32_dpp v151, v147 row_shr:8 row_mask:0xf bank_mask:0xf
	v_mul_f32_e32 v147, v147, v151
	v_mul_f32_e32 v151, v149, v147
	ds_bpermute_b32 v147, v154, v147
	v_mul_f32_e32 v237, v77, v151
	v_rcp_f32_e32 v151, v151
	s_nop 0
	v_mul_f32_e32 v236, v150, v151
	v_max_f32_e32 v150, v106, v106
	v_med3_f32 v150, v150, s36, v218
	v_mul_f32_e32 v150, 0xbfb8aa3b, v150
	v_exp_f32_e32 v150, v150
	v_sub_f32_e32 v183, 1.0, v130
	v_mov_b32_e32 v151, 1.0
	v_mov_b32_e32 v153, 1.0
	v_add_f32_e32 v152, 1.0, v150
	v_rcp_f32_e32 v152, v152
	v_mov_b32_e32 v175, 1.0
	v_mul_f32_e32 v150, v150, v183
	v_max_f32_e32 v247, v91, v91
	v_fma_f32 v180, v152, v183, v130
	v_mul_f32_e32 v150, v152, v150
	v_mov_b32_e32 v152, 1.0
	v_mov_b32_dpp v151, v180 row_shr:1 row_mask:0xf bank_mask:0xf
	v_mul_f32_e32 v151, v180, v151
	v_med3_f32 v247, v247, s36, v218
	v_max_f32_e32 v248, v75, v75
	v_mov_b32_dpp v153, v151 row_shr:2 row_mask:0xf bank_mask:0xf
	v_mul_f32_e32 v151, v151, v153
	v_max_f32_e32 v153, v90, v90
	v_med3_f32 v153, v153, s36, v218
	v_mul_f32_e32 v153, 0xbfb8aa3b, v153
	v_exp_f32_e32 v153, v153
	v_mov_b32_dpp v175, v151 row_shr:4 row_mask:0xf bank_mask:0xf
	v_mul_f32_e32 v151, v151, v175
	v_mul_f32_e32 v247, 0xbfb8aa3b, v247
	v_add_f32_e32 v180, 1.0, v153
	v_mov_b32_dpp v152, v151 row_shr:8 row_mask:0xf bank_mask:0xf
	v_mul_f32_e32 v151, v151, v152
	v_rcp_f32_e32 v175, v151
	v_rcp_f32_e32 v180, v180
	ds_bpermute_b32 v152, v154, v151
	v_mul_f32_e32 v239, v122, v151
	v_mul_f32_e32 v238, v150, v175
	v_fma_f32 v150, v180, v183, v130
	v_mul_f32_e32 v151, v153, v183
	v_mov_b32_e32 v153, 1.0
	v_max_f32_e32 v175, v74, v74
	v_med3_f32 v175, v175, s36, v218
	v_mov_b32_dpp v153, v150 row_shr:1 row_mask:0xf bank_mask:0xf
	v_mul_f32_e32 v150, v150, v153
	v_mov_b32_e32 v153, 1.0
	v_mul_f32_e32 v175, 0xbfb8aa3b, v175
	v_exp_f32_e32 v175, v175
	v_mov_b32_dpp v153, v150 row_shr:2 row_mask:0xf bank_mask:0xf
	v_mul_f32_e32 v150, v150, v153
	v_mov_b32_e32 v153, 1.0
	v_mul_f32_e32 v151, v180, v151
	v_add_f32_e32 v180, 1.0, v175
	v_mov_b32_dpp v153, v150 row_shr:4 row_mask:0xf bank_mask:0xf
	v_mul_f32_e32 v150, v150, v153
	v_mov_b32_e32 v153, 1.0
	v_rcp_f32_e32 v180, v180
	v_med3_f32 v248, v248, s36, v218
	v_mov_b32_dpp v153, v150 row_shr:8 row_mask:0xf bank_mask:0xf
	v_mul_f32_e32 v150, v150, v153
	ds_bpermute_b32 v153, v154, v150
	s_waitcnt lgkmcnt(1)
	v_mul_f32_e32 v150, v150, v152
	v_mul_f32_e32 v241, v110, v150
	v_exp_f32_e32 v247, v247
	v_mul_f32_e32 v248, 0xbfb8aa3b, v248
	s_waitcnt lgkmcnt(0)
	v_mul_f32_e32 v152, v152, v153
	v_rcp_f32_e32 v153, v150
	v_fma_f32 v150, v180, v183, v130
	v_exp_f32_e32 v248, v248
	v_add_f32_e32 v249, 1.0, v247
	v_mul_f32_e32 v240, v151, v153
	v_mov_b32_e32 v153, 1.0
	v_mul_f32_e32 v151, v175, v183
	v_mul_f32_e32 v151, v180, v151
	v_mov_b32_dpp v153, v150 row_shr:1 row_mask:0xf bank_mask:0xf
	v_mul_f32_e32 v150, v150, v153
	v_mov_b32_e32 v153, 1.0
	v_rcp_f32_e32 v249, v249
	s_nop 0
	v_mov_b32_dpp v153, v150 row_shr:2 row_mask:0xf bank_mask:0xf
	v_mul_f32_e32 v150, v150, v153
	v_mov_b32_e32 v153, 1.0
	s_nop 1
	v_mov_b32_dpp v153, v150 row_shr:4 row_mask:0xf bank_mask:0xf
	v_mul_f32_e32 v150, v150, v153
	v_mov_b32_e32 v153, 1.0
	s_nop 1
	v_mov_b32_dpp v153, v150 row_shr:8 row_mask:0xf bank_mask:0xf
	v_mul_f32_e32 v150, v150, v153
	v_max_f32_e32 v153, v66, v66
	v_med3_f32 v153, v153, s36, v218
	v_mul_f32_e32 v153, 0xbfb8aa3b, v153
	v_exp_f32_e32 v153, v153
	v_mul_f32_e32 v175, v152, v150
	ds_bpermute_b32 v244, v154, v150
	v_rcp_f32_e32 v150, v175
	v_add_f32_e32 v180, 1.0, v153
	v_rcp_f32_e32 v180, v180
	v_mul_f32_e32 v243, v94, v175
	v_max_f32_e32 v175, v107, v107
	v_med3_f32 v175, v175, s36, v218
	v_mul_f32_e32 v175, 0xbfb8aa3b, v175
	v_mul_f32_e32 v242, v151, v150
	v_fma_f32 v150, v180, v183, v130
	v_mul_f32_e32 v151, v153, v183
	v_mov_b32_e32 v153, 1.0
	v_exp_f32_e32 v175, v175
	v_mul_f32_e32 v151, v180, v151
	v_mov_b32_dpp v153, v150 row_shr:1 row_mask:0xf bank_mask:0xf
	v_mul_f32_e32 v150, v150, v153
	v_mov_b32_e32 v153, 1.0
	v_add_f32_e32 v180, 1.0, v175
	v_rcp_f32_e32 v245, v180
	v_mov_b32_dpp v153, v150 row_shr:2 row_mask:0xf bank_mask:0xf
	v_mul_f32_e32 v150, v150, v153
	v_mov_b32_e32 v153, 1.0
	v_sub_f32_e32 v180, 1.0, v131
	v_mul_f32_e32 v175, v175, v180
	v_mov_b32_dpp v153, v150 row_shr:4 row_mask:0xf bank_mask:0xf
	v_mul_f32_e32 v150, v150, v153
	v_mov_b32_e32 v153, 1.0
	s_waitcnt lgkmcnt(0)
; __device__ __forceinline__ float fexp(float x) { return __builtin_amdgcn_exp2f(x * 1.4426950408889634f); }
; __device__ __forceinline__ float frcp(float x) { return __builtin_amdgcn_rcpf(x); }
;     __device__ __forceinline__ void operator()(Acc& acc, const Unit& u, int wr, int wc, int fr, int fq) const {
;     ...
;                     for (int i = 0; i < 4; ++i) {
;                         const float lbv = lb4[n][i], oml = 1.0f - lbv;
;                         float carry = 1.f;
; #pragma unroll
;                         for (int m = 0; m < 4; ++m) {
;                             float x = acc[ai][1][m][n][i]; x = fminf(fmaxf(x, -30.f), 30.f);
;                             const float ex = fexp(-x), s = frcp(1.0f + ex);
;                             const float f = lbv + oml * s, kk = oml * ex * s;
;                             const float p = row16_prefix_mul(f);
;                             const float eb = carry * p;
;                             carry *= __shfl(p, 15, 16);
;                             float qv = acc[ai][0][m][n][i] * eb, kv = kk * frcp(eb);
;                             asm volatile("" : "+v"(qv), "+v"(kv));
;                             acc[ai][0][m][n][i] = qv; acc[ai][1][m][n][i] = kv;
;                         }
;                         el[n][i] = carry;
;                         __builtin_amdgcn_sched_barrier(0);
;                     }
;                 if (fr == 0) { float* ep = ELAST + (size_t)(u.pm * 4 + ai * 2 + wr) * 512 + hk0; *(f32x4*)ep = el[0]; *(f32x4*)(ep + 4) = el[1]; }
	v_mul_f32_e32 v152, v152, v244
	v_fma_f32 v246, v245, v180, v131
	v_mov_b32_dpp v153, v150 row_shr:8 row_mask:0xf bank_mask:0xf
	v_mul_f32_e32 v153, v150, v153
	ds_bpermute_b32 v150, v154, v153
	v_mul_f32_e32 v175, v245, v175
	v_add_f32_e32 v245, 1.0, v248
	v_mul_f32_e32 v153, v152, v153
	v_rcp_f32_e32 v245, v245
	v_rcp_f32_e32 v244, v153
	v_mul_f32_e32 v247, v247, v180
	v_fma_f32 v250, v249, v180, v131
	v_mul_f32_e32 v249, v249, v247
	v_mul_f32_e32 v247, v248, v180
	v_fma_f32 v251, v245, v180, v131
	v_mul_f32_e32 v252, v245, v247
	v_mul_f32_e32 v245, v78, v153
	v_mul_f32_e32 v244, v151, v244
	v_mov_b32_e32 v151, 1.0
	v_mov_b32_e32 v153, 1.0
	s_nop 0
	v_mov_b32_dpp v151, v246 row_shr:1 row_mask:0xf bank_mask:0xf
	v_mul_f32_e32 v151, v246, v151
	s_nop 1
	v_mov_b32_dpp v153, v151 row_shr:2 row_mask:0xf bank_mask:0xf
	v_mul_f32_e32 v151, v151, v153
	v_mov_b32_e32 v153, 1.0
	s_nop 1
	v_mov_b32_dpp v153, v151 row_shr:4 row_mask:0xf bank_mask:0xf
	v_mul_f32_e32 v151, v151, v153
	v_mov_b32_e32 v153, 1.0
	s_nop 1
	v_mov_b32_dpp v153, v151 row_shr:8 row_mask:0xf bank_mask:0xf
	v_mul_f32_e32 v151, v151, v153
	ds_bpermute_b32 v153, v154, v151
	v_mul_f32_e32 v247, v123, v151
	v_rcp_f32_e32 v151, v151
	s_nop 0
	v_mul_f32_e32 v246, v175, v151
	v_mov_b32_e32 v151, 1.0
	v_mov_b32_e32 v175, 1.0
	s_nop 0
	v_mov_b32_dpp v151, v250 row_shr:1 row_mask:0xf bank_mask:0xf
	v_mul_f32_e32 v151, v250, v151
	s_nop 1
	v_mov_b32_dpp v175, v151 row_shr:2 row_mask:0xf bank_mask:0xf
	v_mul_f32_e32 v151, v151, v175
	v_mov_b32_e32 v175, 1.0
	s_nop 1
	v_mov_b32_dpp v175, v151 row_shr:4 row_mask:0xf bank_mask:0xf
	v_mul_f32_e32 v151, v151, v175
	v_mov_b32_e32 v175, 1.0
	s_nop 1
	v_mov_b32_dpp v175, v151 row_shr:8 row_mask:0xf bank_mask:0xf
	v_mul_f32_e32 v151, v151, v175
	s_waitcnt lgkmcnt(0)
	v_mul_f32_e32 v175, v151, v153
	ds_bpermute_b32 v151, v154, v151
	v_mul_f32_e32 v248, v111, v175
	s_waitcnt lgkmcnt(0)
	v_mul_f32_e32 v151, v153, v151
	v_rcp_f32_e32 v153, v175
	v_mov_b32_e32 v175, 1.0
	v_mul_f32_e32 v249, v249, v153
	v_mov_b32_e32 v153, 1.0
	s_nop 1
	v_mov_b32_dpp v153, v251 row_shr:1 row_mask:0xf bank_mask:0xf
	v_mul_f32_e32 v153, v251, v153
	s_nop 1
	v_mov_b32_dpp v175, v153 row_shr:2 row_mask:0xf bank_mask:0xf
	v_mul_f32_e32 v153, v153, v175
	v_mov_b32_e32 v175, 1.0
	s_nop 1
	v_mov_b32_dpp v175, v153 row_shr:4 row_mask:0xf bank_mask:0xf
	v_mul_f32_e32 v153, v153, v175
	v_mov_b32_e32 v175, 1.0
	s_nop 1
	v_mov_b32_dpp v175, v153 row_shr:8 row_mask:0xf bank_mask:0xf
	v_mul_f32_e32 v153, v153, v175
	v_mul_f32_e32 v175, v151, v153
	ds_bpermute_b32 v153, v154, v153
	v_mul_f32_e32 v251, v95, v175
	s_waitcnt lgkmcnt(0)
	v_mul_f32_e32 v153, v151, v153
	v_rcp_f32_e32 v151, v175
	s_nop 0
	v_mul_f32_e32 v250, v252, v151
	v_max_f32_e32 v151, v67, v67
	v_med3_f32 v151, v151, s36, v218
	v_mul_f32_e32 v151, 0xbfb8aa3b, v151
	v_exp_f32_e32 v151, v151
	s_nop 0
	v_add_f32_e32 v175, 1.0, v151
	v_rcp_f32_e32 v175, v175
	v_mul_f32_e32 v151, v151, v180
	v_fma_f32 v252, v175, v180, v131
	v_mul_f32_e32 v175, v175, v151
	v_mov_b32_e32 v151, 1.0
	s_nop 1
	v_mov_b32_dpp v151, v252 row_shr:1 row_mask:0xf bank_mask:0xf
	v_mul_f32_e32 v151, v252, v151
	v_mov_b32_e32 v252, 1.0
	s_nop 1
	v_mov_b32_dpp v252, v151 row_shr:2 row_mask:0xf bank_mask:0xf
	v_mul_f32_e32 v151, v151, v252
	v_mov_b32_e32 v252, 1.0
	s_nop 1
	v_mov_b32_dpp v252, v151 row_shr:4 row_mask:0xf bank_mask:0xf
	v_mul_f32_e32 v151, v151, v252
	v_mov_b32_e32 v252, 1.0
	s_nop 1
	v_mov_b32_dpp v252, v151 row_shr:8 row_mask:0xf bank_mask:0xf
	v_mul_f32_e32 v151, v151, v252
	v_mul_f32_e32 v252, v153, v151
	ds_bpermute_b32 v151, v154, v151
	v_mul_f32_e32 v253, v79, v252
	v_rcp_f32_e32 v252, v252
	s_nop 0
	v_mul_f32_e32 v252, v175, v252
	s_and_saveexec_b64 s[4:5], vcc
	s_cbranch_execz .LBB0_193
	s_lshl_b32 s12, s84, 2
	s_add_i32 s48, s12, s23
	s_ashr_i32 s49, s48, 31
	s_lshl_b64 s[48:49], s[48:49], 11
	s_add_u32 s48, s55, s48
	s_addc_u32 s49, s58, s49
	v_pk_mul_f32 v[142:143], v[144:145], v[142:143]
	v_pk_mul_f32 v[140:141], v[140:141], v[138:139]
	v_lshl_add_u64 v[138:139], v[136:137], 2, s[48:49]
	s_waitcnt lgkmcnt(0)
	v_pk_mul_f32 v[150:151], v[152:153], v[150:151]
	v_pk_mul_f32 v[148:149], v[148:149], v[146:147]
	global_store_dwordx4 v[138:139], v[140:143], off sc1
	global_store_dwordx4 v[138:139], v[148:151], off offset:16 sc1
; __device__ __forceinline__ u32x4 pack8(const f32x4& a, const f32x4& b) { u32x4 w; w.x = cvt_pk_bf16(a[0], a[1]); w.y = cvt_pk_bf16(a[2], a[3]); w.z = cvt_pk_bf16(b[0], b[1]); w.w = cvt_pk_bf16(b[2], b[3]); return w; }
; __device__ __forceinline__ float fexp(float x) { return __builtin_amdgcn_exp2f(x * 1.4426950408889634f); }
; __device__ __forceinline__ float frcp(float x) { return __builtin_amdgcn_rcpf(x); }
;     __device__ __forceinline__ void operator()(Acc& acc, const Unit& u, int wr, int wc, int fr, int fq) const {
;     ...
;                     for (int i = 0; i < 4; ++i) {
;                         const float lbv = lb4[n][i], oml = 1.0f - lbv;
;                         float carry = 1.f;
; #pragma unroll
;                         for (int m = 0; m < 4; ++m) {
;                             float x = acc[ai][1][m][n][i]; x = fminf(fmaxf(x, -30.f), 30.f);
;                             const float ex = fexp(-x), s = frcp(1.0f + ex);
;                             const float f = lbv + oml * s, kk = oml * ex * s;
;                             const float p = row16_prefix_mul(f);
;                             const float eb = carry * p;
;                             carry *= __shfl(p, 15, 16);
;                             float qv = acc[ai][0][m][n][i] * eb, kv = kk * frcp(eb);
;                             asm volatile("" : "+v"(qv), "+v"(kv));
;                             acc[ai][0][m][n][i] = qv; acc[ai][1][m][n][i] = kv;
;                         }
;     ...
;                 for (int m = 0; m < 4; ++m) { const size_t o = (size_t)(row0 + ai * HALF + m * 16) * 512 + hk0;
;                     *(u32x4*)(QT + o) = pack8(acc[ai][0][m][0], acc[ai][0][m][1]); *(u32x4*)(KT + o) = pack8(acc[ai][1][m][0], acc[ai][1][m][1]); }
.LBB0_193:
	s_or_b64 exec, exec, s[4:5]
	v_ashrrev_i32_e32 v175, 31, v174
	v_lshlrev_b64 v[138:139], 9, v[174:175]
	v_lshl_add_u64 v[138:139], v[138:139], 0, v[136:137]
	v_lshlrev_b64 v[138:139], 1, v[138:139]
	v_lshl_add_u64 v[144:145], s[74:75], 0, v[138:139]
	v_cvt_pk_bf16_f32 v140, v157, v187
	v_cvt_pk_bf16_f32 v141, v195, v203
	v_cvt_pk_bf16_f32 v142, v222, v231
	v_cvt_pk_bf16_f32 v143, v239, v247
	global_store_dwordx4 v[144:145], v[140:143], off sc1
	v_lshl_add_u64 v[144:145], s[0:1], 0, v[138:139]
	s_nop 0
	v_cvt_pk_bf16_f32 v140, v156, v186
	v_cvt_pk_bf16_f32 v141, v194, v202
	v_cvt_pk_bf16_f32 v142, v221, v230
	v_cvt_pk_bf16_f32 v143, v238, v246
	global_store_dwordx4 v[144:145], v[140:143], off sc1
	v_lshl_add_u64 v[144:145], v[138:139], 0, s[60:61]
	v_lshl_add_u64 v[146:147], s[74:75], 0, v[144:145]
	v_cvt_pk_bf16_f32 v140, v159, v188
	v_cvt_pk_bf16_f32 v141, v197, v204
	v_cvt_pk_bf16_f32 v142, v224, v232
	v_cvt_pk_bf16_f32 v143, v241, v248
	v_lshl_add_u64 v[144:145], s[0:1], 0, v[144:145]
	global_store_dwordx4 v[146:147], v[140:143], off sc1
	s_nop 1
	v_cvt_pk_bf16_f32 v140, v158, v189
	v_cvt_pk_bf16_f32 v141, v196, v205
	v_cvt_pk_bf16_f32 v142, v223, v233
	v_cvt_pk_bf16_f32 v143, v240, v249
	global_store_dwordx4 v[144:145], v[140:143], off sc1
	v_lshl_add_u64 v[144:145], v[138:139], 0, s[24:25]
	v_lshl_add_u64 v[146:147], s[74:75], 0, v[144:145]
	v_cvt_pk_bf16_f32 v140, v177, v191
	v_cvt_pk_bf16_f32 v141, v199, v207
	v_cvt_pk_bf16_f32 v142, v226, v235
	v_cvt_pk_bf16_f32 v143, v243, v251
	v_lshl_add_u64 v[144:145], s[0:1], 0, v[144:145]
	global_store_dwordx4 v[146:147], v[140:143], off sc1
	s_nop 1
	v_cvt_pk_bf16_f32 v140, v176, v190
	v_cvt_pk_bf16_f32 v141, v198, v206
	v_cvt_pk_bf16_f32 v142, v225, v234
	v_cvt_pk_bf16_f32 v143, v242, v250
	global_store_dwordx4 v[144:145], v[140:143], off sc1
	v_lshl_add_u64 v[144:145], v[138:139], 0, s[64:65]
	v_lshl_add_u64 v[146:147], s[74:75], 0, v[144:145]
	v_cvt_pk_bf16_f32 v140, v185, v193
	v_cvt_pk_bf16_f32 v141, v201, v220
	v_cvt_pk_bf16_f32 v142, v229, v237
	v_cvt_pk_bf16_f32 v143, v245, v253
	global_store_dwordx4 v[146:147], v[140:143], off sc1
	v_lshl_add_u64 v[144:145], s[0:1], 0, v[144:145]
	s_nop 0
	v_max_f32_e32 v140, v48, v48
	v_med3_f32 v140, v140, s36, v218
	v_mul_f32_e32 v140, 0xbfb8aa3b, v140
	v_exp_f32_e32 v146, v140
	v_cvt_pk_bf16_f32 v140, v184, v192
	v_cvt_pk_bf16_f32 v141, v200, v219
	v_cvt_pk_bf16_f32 v142, v227, v236
	s_nop 0
	v_add_f32_e32 v143, 1.0, v146
	v_rcp_f32_e32 v147, v143
	v_cvt_pk_bf16_f32 v143, v244, v252
	global_store_dwordx4 v[144:145], v[140:143], off sc1
	s_nop 1
	v_fma_f32 v140, v147, v155, v132
	v_mov_b32_e32 v142, 1.0
	v_max_f32_e32 v143, v32, v32
	v_med3_f32 v143, v143, s36, v218
	v_mov_b32_dpp v142, v140 row_shr:1 row_mask:0xf bank_mask:0xf
	v_mul_f32_e32 v140, v140, v142
	v_mov_b32_e32 v142, 1.0
	v_mul_f32_e32 v143, 0xbfb8aa3b, v143
	v_exp_f32_e32 v143, v143
	v_mov_b32_dpp v142, v140 row_shr:2 row_mask:0xf bank_mask:0xf
	v_mul_f32_e32 v140, v140, v142
	v_mov_b32_e32 v142, 1.0
	v_add_f32_e32 v145, 1.0, v143
	v_rcp_f32_e32 v145, v145
	v_mov_b32_dpp v142, v140 row_shr:4 row_mask:0xf bank_mask:0xf
	v_mul_f32_e32 v140, v140, v142
	v_mov_b32_e32 v142, 1.0
	v_mul_f32_e32 v141, v146, v155
	v_mul_f32_e32 v141, v147, v141
	v_mov_b32_dpp v142, v140 row_shr:8 row_mask:0xf bank_mask:0xf
	v_mul_f32_e32 v140, v140, v142
	v_rcp_f32_e32 v144, v140
	ds_bpermute_b32 v142, v154, v140
	v_mul_f32_e32 v153, v60, v140
	v_fma_f32 v140, v145, v155, v132
	v_mul_f32_e32 v150, v141, v144
	v_mul_f32_e32 v141, v143, v155
	v_mov_b32_e32 v143, 1.0
	v_max_f32_e32 v144, v16, v16
	v_med3_f32 v144, v144, s36, v218
	v_mov_b32_dpp v143, v140 row_shr:1 row_mask:0xf bank_mask:0xf
	v_mul_f32_e32 v140, v140, v143
	v_mov_b32_e32 v143, 1.0
	v_mul_f32_e32 v144, 0xbfb8aa3b, v144
	v_exp_f32_e32 v144, v144
	v_mov_b32_dpp v143, v140 row_shr:2 row_mask:0xf bank_mask:0xf
	v_mul_f32_e32 v140, v140, v143
	v_mov_b32_e32 v143, 1.0
	v_mul_f32_e32 v141, v145, v141
	v_add_f32_e32 v145, 1.0, v144
	v_mov_b32_dpp v143, v140 row_shr:4 row_mask:0xf bank_mask:0xf
	v_mul_f32_e32 v140, v140, v143
	v_mov_b32_e32 v143, 1.0
	v_rcp_f32_e32 v145, v145
	v_max_f32_e32 v147, v33, v33
	v_mov_b32_dpp v143, v140 row_shr:8 row_mask:0xf bank_mask:0xf
	v_mul_f32_e32 v140, v140, v143
	ds_bpermute_b32 v143, v154, v140
	s_waitcnt lgkmcnt(1)
	v_mul_f32_e32 v140, v140, v142
	v_mul_f32_e32 v152, v52, v140
	v_med3_f32 v147, v147, s36, v218
	v_mul_f32_e32 v147, 0xbfb8aa3b, v147
	s_waitcnt lgkmcnt(0)
	v_mul_f32_e32 v142, v142, v143
	v_rcp_f32_e32 v143, v140
	v_fma_f32 v140, v145, v155, v132
	v_exp_f32_e32 v147, v147
	v_mul_f32_e32 v149, v141, v143
	v_mov_b32_e32 v143, 1.0
	v_mul_f32_e32 v141, v144, v155
	v_mul_f32_e32 v141, v145, v141
	v_mov_b32_dpp v143, v140 row_shr:1 row_mask:0xf bank_mask:0xf
	v_mul_f32_e32 v140, v140, v143
	v_mov_b32_e32 v143, 1.0
	v_add_f32_e32 v156, 1.0, v147
	v_rcp_f32_e32 v156, v156
	v_mov_b32_dpp v143, v140 row_shr:2 row_mask:0xf bank_mask:0xf
	v_mul_f32_e32 v140, v140, v143
	v_mov_b32_e32 v143, 1.0
	v_mul_f32_e32 v147, v147, v173
	v_fma_f32 v158, v156, v173, v133
	v_mov_b32_dpp v143, v140 row_shr:4 row_mask:0xf bank_mask:0xf
	v_mul_f32_e32 v140, v140, v143
	v_mov_b32_e32 v143, 1.0
	v_mul_f32_e32 v147, v156, v147
	s_nop 0
	v_mov_b32_dpp v143, v140 row_shr:8 row_mask:0xf bank_mask:0xf
	v_mul_f32_e32 v140, v140, v143
	v_max_f32_e32 v143, v4, v4
	v_med3_f32 v143, v143, s36, v218
	v_mul_f32_e32 v143, 0xbfb8aa3b, v143
	v_exp_f32_e32 v143, v143
	v_mul_f32_e32 v144, v142, v140
	v_rcp_f32_e32 v145, v144
	v_mul_f32_e32 v151, v36, v144
	v_add_f32_e32 v146, 1.0, v143
	v_rcp_f32_e32 v146, v146
	v_max_f32_e32 v144, v49, v49
	v_med3_f32 v144, v144, s36, v218
	v_mul_f32_e32 v144, 0xbfb8aa3b, v144
	v_mul_f32_e32 v148, v141, v145
	v_fma_f32 v132, v146, v155, v132
	v_mul_f32_e32 v141, v143, v155
	v_mov_b32_e32 v143, 1.0
	v_exp_f32_e32 v144, v144
	v_max_f32_e32 v155, v17, v17
	v_mov_b32_dpp v143, v132 row_shr:1 row_mask:0xf bank_mask:0xf
	v_mul_f32_e32 v132, v132, v143
	v_mov_b32_e32 v143, 1.0
	ds_bpermute_b32 v140, v154, v140
	v_med3_f32 v155, v155, s36, v218
	v_mov_b32_dpp v143, v132 row_shr:2 row_mask:0xf bank_mask:0xf
	v_mul_f32_e32 v132, v132, v143
	v_mov_b32_e32 v143, 1.0
	v_add_f32_e32 v145, 1.0, v144
	v_mul_f32_e32 v155, 0xbfb8aa3b, v155
	v_mov_b32_dpp v143, v132 row_shr:4 row_mask:0xf bank_mask:0xf
	v_rcp_f32_e32 v145, v145
	v_exp_f32_e32 v155, v155
	v_mul_f32_e32 v132, v132, v143
	v_mov_b32_e32 v143, 1.0
	v_mul_f32_e32 v144, v144, v173
	s_waitcnt lgkmcnt(0)
; __device__ __forceinline__ float fexp(float x) { return __builtin_amdgcn_exp2f(x * 1.4426950408889634f); }
; __device__ __forceinline__ float frcp(float x) { return __builtin_amdgcn_rcpf(x); }
;     __device__ __forceinline__ void operator()(Acc& acc, const Unit& u, int wr, int wc, int fr, int fq) const {
;     ...
;                     for (int i = 0; i < 4; ++i) {
;                         const float lbv = lb4[n][i], oml = 1.0f - lbv;
;                         float carry = 1.f;
; #pragma unroll
;                         for (int m = 0; m < 4; ++m) {
;                             float x = acc[ai][1][m][n][i]; x = fminf(fmaxf(x, -30.f), 30.f);
;                             const float ex = fexp(-x), s = frcp(1.0f + ex);
;                             const float f = lbv + oml * s, kk = oml * ex * s;
;                             const float p = row16_prefix_mul(f);
;                             const float eb = carry * p;
;                             carry *= __shfl(p, 15, 16);
;                             float qv = acc[ai][0][m][n][i] * eb, kv = kk * frcp(eb);
;                             asm volatile("" : "+v"(qv), "+v"(kv));
;                             acc[ai][0][m][n][i] = qv; acc[ai][1][m][n][i] = kv;
;                         }
	v_mul_f32_e32 v140, v142, v140
	v_mov_b32_dpp v143, v132 row_shr:8 row_mask:0xf bank_mask:0xf
	v_mul_f32_e32 v143, v132, v143
	v_mul_f32_e32 v141, v146, v141
	v_fma_f32 v146, v145, v173, v133
	v_mul_f32_e32 v144, v145, v144
	v_add_f32_e32 v145, 1.0, v155
	v_mul_f32_e32 v142, v140, v143
	ds_bpermute_b32 v132, v154, v143
	v_rcp_f32_e32 v145, v145
	v_rcp_f32_e32 v143, v142
	v_mul_f32_e32 v155, v155, v173
	v_mul_f32_e32 v156, v20, v142
	v_fma_f32 v177, v145, v173, v133
	v_mul_f32_e32 v145, v145, v155
	v_mul_f32_e32 v155, v141, v143
	v_mov_b32_e32 v141, 1.0
	v_mov_b32_e32 v142, 1.0
	v_mov_b32_e32 v143, 1.0
	v_mov_b32_dpp v141, v146 row_shr:1 row_mask:0xf bank_mask:0xf
	v_mul_f32_e32 v141, v146, v141
	s_nop 1
	v_mov_b32_dpp v142, v141 row_shr:2 row_mask:0xf bank_mask:0xf
	v_mul_f32_e32 v141, v141, v142
	v_mov_b32_e32 v142, 1.0
	s_nop 1
	v_mov_b32_dpp v142, v141 row_shr:4 row_mask:0xf bank_mask:0xf
	v_mul_f32_e32 v141, v141, v142
	v_mov_b32_e32 v142, 1.0
	s_nop 1
	v_mov_b32_dpp v142, v141 row_shr:8 row_mask:0xf bank_mask:0xf
	v_mul_f32_e32 v141, v141, v142
	ds_bpermute_b32 v142, v154, v141
	v_mul_f32_e32 v175, v61, v141
	v_rcp_f32_e32 v141, v141
	s_nop 0
	v_mul_f32_e32 v157, v144, v141
	v_mov_b32_e32 v141, 1.0
	s_nop 1
	v_mov_b32_dpp v141, v158 row_shr:1 row_mask:0xf bank_mask:0xf
	v_mul_f32_e32 v141, v158, v141
	s_nop 1
	v_mov_b32_dpp v143, v141 row_shr:2 row_mask:0xf bank_mask:0xf
	v_mul_f32_e32 v141, v141, v143
	v_mov_b32_e32 v143, 1.0
	s_nop 1
	v_mov_b32_dpp v143, v141 row_shr:4 row_mask:0xf bank_mask:0xf
	v_mul_f32_e32 v141, v141, v143
	v_mov_b32_e32 v143, 1.0
	s_nop 1
	v_mov_b32_dpp v143, v141 row_shr:8 row_mask:0xf bank_mask:0xf
	v_mul_f32_e32 v141, v141, v143
	s_waitcnt lgkmcnt(0)
	v_mul_f32_e32 v143, v141, v142
	ds_bpermute_b32 v141, v154, v141
	v_mul_f32_e32 v159, v53, v143
	s_waitcnt lgkmcnt(0)
	v_mul_f32_e32 v141, v142, v141
	v_rcp_f32_e32 v142, v143
	v_mov_b32_e32 v143, 1.0
	v_mul_f32_e32 v176, v147, v142
	v_mov_b32_e32 v142, 1.0
	s_nop 1
	v_mov_b32_dpp v142, v177 row_shr:1 row_mask:0xf bank_mask:0xf
	v_mul_f32_e32 v142, v177, v142
	s_nop 1
	v_mov_b32_dpp v143, v142 row_shr:2 row_mask:0xf bank_mask:0xf
	v_mul_f32_e32 v142, v142, v143
	v_mov_b32_e32 v143, 1.0
	s_nop 1
	v_mov_b32_dpp v143, v142 row_shr:4 row_mask:0xf bank_mask:0xf
	v_mul_f32_e32 v142, v142, v143
	v_mov_b32_e32 v143, 1.0
	s_nop 1
	v_mov_b32_dpp v143, v142 row_shr:8 row_mask:0xf bank_mask:0xf
	v_mul_f32_e32 v142, v142, v143
	v_mul_f32_e32 v143, v141, v142
	ds_bpermute_b32 v142, v154, v142
	v_mul_f32_e32 v177, v37, v143
	s_waitcnt lgkmcnt(0)
	v_mul_f32_e32 v141, v141, v142
	v_rcp_f32_e32 v142, v143
	s_nop 0
	v_mul_f32_e32 v158, v145, v142
	v_max_f32_e32 v142, v5, v5
	v_med3_f32 v142, v142, s36, v218
	v_mul_f32_e32 v142, 0xbfb8aa3b, v142
	v_exp_f32_e32 v142, v142
	s_nop 0
	v_add_f32_e32 v143, 1.0, v142
	v_rcp_f32_e32 v143, v143
	v_mul_f32_e32 v142, v142, v173
	v_fma_f32 v133, v143, v173, v133
	v_mul_f32_e32 v142, v143, v142
	v_mov_b32_e32 v143, 1.0
	s_nop 1
	v_mov_b32_dpp v143, v133 row_shr:1 row_mask:0xf bank_mask:0xf
	v_mul_f32_e32 v133, v133, v143
	v_mov_b32_e32 v143, 1.0
	s_nop 1
	v_mov_b32_dpp v143, v133 row_shr:2 row_mask:0xf bank_mask:0xf
	v_mul_f32_e32 v133, v133, v143
	v_mov_b32_e32 v143, 1.0
	s_nop 1
	v_mov_b32_dpp v143, v133 row_shr:4 row_mask:0xf bank_mask:0xf
	v_mul_f32_e32 v133, v133, v143
	v_mov_b32_e32 v143, 1.0
	s_nop 1
	v_mov_b32_dpp v143, v133 row_shr:8 row_mask:0xf bank_mask:0xf
	v_mul_f32_e32 v133, v133, v143
	v_mul_f32_e32 v143, v141, v133
	ds_bpermute_b32 v133, v154, v133
	v_mul_f32_e32 v173, v21, v143
	v_rcp_f32_e32 v143, v143
	s_nop 0
	v_mul_f32_e32 v184, v142, v143
	v_max_f32_e32 v142, v50, v50
	v_med3_f32 v142, v142, s36, v218
	v_mul_f32_e32 v142, 0xbfb8aa3b, v142
	v_exp_f32_e32 v142, v142
	v_mov_b32_e32 v143, 1.0
	v_mov_b32_e32 v144, 1.0
	v_mov_b32_e32 v146, 1.0
	v_add_f32_e32 v145, 1.0, v142
	v_rcp_f32_e32 v145, v145
	v_mov_b32_e32 v147, 1.0
	v_mul_f32_e32 v142, v142, v181
	v_fma_f32 v185, v145, v181, v134
	v_mul_f32_e32 v142, v145, v142
	s_nop 0
	v_mov_b32_dpp v143, v185 row_shr:1 row_mask:0xf bank_mask:0xf
	v_mul_f32_e32 v143, v185, v143
	s_nop 1
	v_mov_b32_dpp v144, v143 row_shr:2 row_mask:0xf bank_mask:0xf
	v_mul_f32_e32 v143, v143, v144
	v_max_f32_e32 v144, v34, v34
	v_med3_f32 v144, v144, s36, v218
	v_mul_f32_e32 v144, 0xbfb8aa3b, v144
	v_exp_f32_e32 v144, v144
	v_mov_b32_dpp v146, v143 row_shr:4 row_mask:0xf bank_mask:0xf
	v_mul_f32_e32 v143, v143, v146
	s_nop 1
	v_mov_b32_dpp v147, v143 row_shr:8 row_mask:0xf bank_mask:0xf
	v_mul_f32_e32 v143, v143, v147
	v_add_f32_e32 v147, 1.0, v144
	v_rcp_f32_e32 v146, v143
	v_rcp_f32_e32 v147, v147
	ds_bpermute_b32 v145, v154, v143
	v_mul_f32_e32 v190, v62, v143
	v_mul_f32_e32 v187, v142, v146
	v_fma_f32 v142, v147, v181, v134
	v_mul_f32_e32 v143, v144, v181
	v_mov_b32_e32 v144, 1.0
	v_max_f32_e32 v146, v18, v18
	v_med3_f32 v146, v146, s36, v218
	v_mov_b32_dpp v144, v142 row_shr:1 row_mask:0xf bank_mask:0xf
	v_mul_f32_e32 v142, v142, v144
	v_mov_b32_e32 v144, 1.0
	v_mul_f32_e32 v146, 0xbfb8aa3b, v146
	v_exp_f32_e32 v146, v146
	v_mov_b32_dpp v144, v142 row_shr:2 row_mask:0xf bank_mask:0xf
	v_mul_f32_e32 v142, v142, v144
	v_mov_b32_e32 v144, 1.0
	v_mul_f32_e32 v143, v147, v143
	v_add_f32_e32 v147, 1.0, v146
	v_mov_b32_dpp v144, v142 row_shr:4 row_mask:0xf bank_mask:0xf
	v_mul_f32_e32 v142, v142, v144
	v_mov_b32_e32 v144, 1.0
	v_rcp_f32_e32 v147, v147
	s_nop 0
	v_mov_b32_dpp v144, v142 row_shr:8 row_mask:0xf bank_mask:0xf
	v_mul_f32_e32 v142, v142, v144
	ds_bpermute_b32 v144, v154, v142
	s_waitcnt lgkmcnt(1)
	v_mul_f32_e32 v142, v142, v145
	v_mul_f32_e32 v189, v54, v142
	s_waitcnt lgkmcnt(0)
; __device__ __forceinline__ float fexp(float x) { return __builtin_amdgcn_exp2f(x * 1.4426950408889634f); }
; __device__ __forceinline__ float frcp(float x) { return __builtin_amdgcn_rcpf(x); }
;     __device__ __forceinline__ void operator()(Acc& acc, const Unit& u, int wr, int wc, int fr, int fq) const {
;     ...
;                     for (int i = 0; i < 4; ++i) {
;                         const float lbv = lb4[n][i], oml = 1.0f - lbv;
;                         float carry = 1.f;
; #pragma unroll
;                         for (int m = 0; m < 4; ++m) {
;                             float x = acc[ai][1][m][n][i]; x = fminf(fmaxf(x, -30.f), 30.f);
;                             const float ex = fexp(-x), s = frcp(1.0f + ex);
;                             const float f = lbv + oml * s, kk = oml * ex * s;
;                             const float p = row16_prefix_mul(f);
;                             const float eb = carry * p;
;                             carry *= __shfl(p, 15, 16);
;                             float qv = acc[ai][0][m][n][i] * eb, kv = kk * frcp(eb);
;                             asm volatile("" : "+v"(qv), "+v"(kv));
;                             acc[ai][0][m][n][i] = qv; acc[ai][1][m][n][i] = kv;
;                         }
	v_mul_f32_e32 v144, v145, v144
	v_rcp_f32_e32 v145, v142
	v_fma_f32 v142, v147, v181, v134
	v_mul_f32_e32 v186, v143, v145
	v_mov_b32_e32 v145, 1.0
	v_mul_f32_e32 v143, v146, v181
	v_mul_f32_e32 v143, v147, v143
	v_mov_b32_dpp v145, v142 row_shr:1 row_mask:0xf bank_mask:0xf
	v_mul_f32_e32 v142, v142, v145
	v_mov_b32_e32 v145, 1.0
	s_nop 1
	v_mov_b32_dpp v145, v142 row_shr:2 row_mask:0xf bank_mask:0xf
	v_mul_f32_e32 v142, v142, v145
	v_mov_b32_e32 v145, 1.0
	s_nop 1
	v_mov_b32_dpp v145, v142 row_shr:4 row_mask:0xf bank_mask:0xf
	v_mul_f32_e32 v142, v142, v145
	v_mov_b32_e32 v145, 1.0
	s_nop 1
	v_mov_b32_dpp v145, v142 row_shr:8 row_mask:0xf bank_mask:0xf
	v_mul_f32_e32 v142, v142, v145
	v_max_f32_e32 v145, v6, v6
	v_med3_f32 v145, v145, s36, v218
	v_mul_f32_e32 v145, 0xbfb8aa3b, v145
	v_exp_f32_e32 v145, v145
	v_mul_f32_e32 v146, v144, v142
	v_rcp_f32_e32 v147, v146
	v_mul_f32_e32 v188, v38, v146
	v_add_f32_e32 v185, 1.0, v145
	v_rcp_f32_e32 v191, v185
	v_max_f32_e32 v146, v51, v51
	v_med3_f32 v146, v146, s36, v218
	v_mul_f32_e32 v146, 0xbfb8aa3b, v146
	v_mul_f32_e32 v185, v143, v147
	v_fma_f32 v134, v191, v181, v134
	v_mul_f32_e32 v143, v145, v181
	v_mov_b32_e32 v145, 1.0
	v_exp_f32_e32 v146, v146
	v_max_f32_e32 v181, v35, v35
	v_mov_b32_dpp v145, v134 row_shr:1 row_mask:0xf bank_mask:0xf
	v_mul_f32_e32 v143, v191, v143
	v_mul_f32_e32 v134, v134, v145
	v_mov_b32_e32 v145, 1.0
	v_med3_f32 v181, v181, s36, v218
	v_max_f32_e32 v191, v19, v19
	ds_bpermute_b32 v142, v154, v142
	v_mov_b32_dpp v145, v134 row_shr:2 row_mask:0xf bank_mask:0xf
	v_mul_f32_e32 v181, 0xbfb8aa3b, v181
	v_med3_f32 v191, v191, s36, v218
	v_mul_f32_e32 v134, v134, v145
	v_mov_b32_e32 v145, 1.0
	v_add_f32_e32 v147, 1.0, v146
	v_exp_f32_e32 v181, v181
	v_mul_f32_e32 v191, 0xbfb8aa3b, v191
	v_mov_b32_dpp v145, v134 row_shr:4 row_mask:0xf bank_mask:0xf
	v_rcp_f32_e32 v147, v147
	v_exp_f32_e32 v191, v191
	v_mul_f32_e32 v134, v134, v145
	v_mov_b32_e32 v145, 1.0
	v_mul_f32_e32 v146, v146, v178
	v_add_f32_e32 v193, 1.0, v181
	v_mov_b32_dpp v145, v134 row_shr:8 row_mask:0xf bank_mask:0xf
	v_mul_f32_e32 v145, v134, v145
	s_waitcnt lgkmcnt(0)
	v_mul_f32_e32 v142, v144, v142
	v_fma_f32 v192, v147, v178, v135
	v_rcp_f32_e32 v193, v193
	v_mul_f32_e32 v146, v147, v146
	v_add_f32_e32 v147, 1.0, v191
	v_mul_f32_e32 v144, v142, v145
	ds_bpermute_b32 v134, v154, v145
	v_rcp_f32_e32 v147, v147
	v_rcp_f32_e32 v145, v144
	v_mul_f32_e32 v181, v181, v178
	v_fma_f32 v194, v193, v178, v135
	v_mul_f32_e32 v193, v193, v181
	v_mul_f32_e32 v181, v191, v178
	v_fma_f32 v197, v147, v178, v135
	v_mul_f32_e32 v147, v147, v181
	v_mul_f32_e32 v191, v22, v144
	v_mul_f32_e32 v181, v143, v145
	v_mov_b32_e32 v143, 1.0
	v_mov_b32_e32 v144, 1.0
	v_mov_b32_e32 v145, 1.0
	v_mov_b32_dpp v143, v192 row_shr:1 row_mask:0xf bank_mask:0xf
	v_mul_f32_e32 v143, v192, v143
	s_nop 1
	v_mov_b32_dpp v144, v143 row_shr:2 row_mask:0xf bank_mask:0xf
	v_mul_f32_e32 v143, v143, v144
	v_mov_b32_e32 v144, 1.0
	s_nop 1
	v_mov_b32_dpp v144, v143 row_shr:4 row_mask:0xf bank_mask:0xf
	v_mul_f32_e32 v143, v143, v144
	v_mov_b32_e32 v144, 1.0
	s_nop 1
	v_mov_b32_dpp v144, v143 row_shr:8 row_mask:0xf bank_mask:0xf
	v_mul_f32_e32 v143, v143, v144
	ds_bpermute_b32 v144, v154, v143
	v_mul_f32_e32 v195, v63, v143
	v_rcp_f32_e32 v143, v143
	s_nop 0
	v_mul_f32_e32 v192, v146, v143
	v_mov_b32_e32 v143, 1.0
	s_nop 1
	v_mov_b32_dpp v143, v194 row_shr:1 row_mask:0xf bank_mask:0xf
	v_mul_f32_e32 v143, v194, v143
	s_nop 1
	v_mov_b32_dpp v145, v143 row_shr:2 row_mask:0xf bank_mask:0xf
	v_mul_f32_e32 v143, v143, v145
	v_mov_b32_e32 v145, 1.0
	s_nop 1
	v_mov_b32_dpp v145, v143 row_shr:4 row_mask:0xf bank_mask:0xf
	v_mul_f32_e32 v143, v143, v145
	v_mov_b32_e32 v145, 1.0
	s_nop 1
	v_mov_b32_dpp v145, v143 row_shr:8 row_mask:0xf bank_mask:0xf
	v_mul_f32_e32 v143, v143, v145
	s_waitcnt lgkmcnt(0)
	v_mul_f32_e32 v145, v143, v144
	ds_bpermute_b32 v143, v154, v143
	v_mul_f32_e32 v194, v55, v145
	s_waitcnt lgkmcnt(0)
	v_mul_f32_e32 v143, v144, v143
	v_rcp_f32_e32 v144, v145
	v_mov_b32_e32 v145, 1.0
	v_mul_f32_e32 v196, v193, v144
	v_mov_b32_e32 v144, 1.0
	s_nop 1
	v_mov_b32_dpp v144, v197 row_shr:1 row_mask:0xf bank_mask:0xf
	v_mul_f32_e32 v144, v197, v144
	s_nop 1
	v_mov_b32_dpp v145, v144 row_shr:2 row_mask:0xf bank_mask:0xf
	v_mul_f32_e32 v144, v144, v145
	v_mov_b32_e32 v145, 1.0
	s_nop 1
	v_mov_b32_dpp v145, v144 row_shr:4 row_mask:0xf bank_mask:0xf
	v_mul_f32_e32 v144, v144, v145
	v_mov_b32_e32 v145, 1.0
	s_nop 1
	v_mov_b32_dpp v145, v144 row_shr:8 row_mask:0xf bank_mask:0xf
	v_mul_f32_e32 v144, v144, v145
	v_mul_f32_e32 v145, v143, v144
	ds_bpermute_b32 v144, v154, v144
	v_mul_f32_e32 v197, v39, v145
	s_waitcnt lgkmcnt(0)
; __device__ __forceinline__ float fexp(float x) { return __builtin_amdgcn_exp2f(x * 1.4426950408889634f); }
; __device__ __forceinline__ float frcp(float x) { return __builtin_amdgcn_rcpf(x); }
;     __device__ __forceinline__ void operator()(Acc& acc, const Unit& u, int wr, int wc, int fr, int fq) const {
;     ...
;                     for (int i = 0; i < 4; ++i) {
;                         const float lbv = lb4[n][i], oml = 1.0f - lbv;
;                         float carry = 1.f;
; #pragma unroll
;                         for (int m = 0; m < 4; ++m) {
;                             float x = acc[ai][1][m][n][i]; x = fminf(fmaxf(x, -30.f), 30.f);
;                             const float ex = fexp(-x), s = frcp(1.0f + ex);
;                             const float f = lbv + oml * s, kk = oml * ex * s;
;                             const float p = row16_prefix_mul(f);
;                             const float eb = carry * p;
;                             carry *= __shfl(p, 15, 16);
;                             float qv = acc[ai][0][m][n][i] * eb, kv = kk * frcp(eb);
;                             asm volatile("" : "+v"(qv), "+v"(kv));
;                             acc[ai][0][m][n][i] = qv; acc[ai][1][m][n][i] = kv;
;                         }
	v_mul_f32_e32 v143, v143, v144
	v_rcp_f32_e32 v144, v145
	s_nop 0
	v_mul_f32_e32 v193, v147, v144
	v_max_f32_e32 v144, v7, v7
	v_med3_f32 v144, v144, s36, v218
	v_mul_f32_e32 v144, 0xbfb8aa3b, v144
	v_exp_f32_e32 v144, v144
	s_nop 0
	v_add_f32_e32 v145, 1.0, v144
	v_rcp_f32_e32 v145, v145
	v_mul_f32_e32 v144, v144, v178
	v_fmac_f32_e32 v135, v145, v178
	v_mul_f32_e32 v144, v145, v144
	v_mov_b32_e32 v145, 1.0
	s_nop 1
	v_mov_b32_dpp v145, v135 row_shr:1 row_mask:0xf bank_mask:0xf
	v_mul_f32_e32 v135, v135, v145
	v_mov_b32_e32 v145, 1.0
	s_nop 1
	v_mov_b32_dpp v145, v135 row_shr:2 row_mask:0xf bank_mask:0xf
	v_mul_f32_e32 v135, v135, v145
	v_mov_b32_e32 v145, 1.0
	s_nop 1
	v_mov_b32_dpp v145, v135 row_shr:4 row_mask:0xf bank_mask:0xf
	v_mul_f32_e32 v135, v135, v145
	v_mov_b32_e32 v145, 1.0
	s_nop 1
	v_mov_b32_dpp v145, v135 row_shr:8 row_mask:0xf bank_mask:0xf
	v_mul_f32_e32 v135, v135, v145
	v_mul_f32_e32 v145, v143, v135
	ds_bpermute_b32 v135, v154, v135
	v_mul_f32_e32 v178, v23, v145
	v_rcp_f32_e32 v145, v145
	s_nop 0
	v_mul_f32_e32 v198, v144, v145
	v_max_f32_e32 v144, v40, v40
	v_med3_f32 v144, v144, s36, v218
	v_mul_f32_e32 v144, 0xbfb8aa3b, v144
	v_exp_f32_e32 v144, v144
	v_mov_b32_e32 v145, 1.0
	v_mov_b32_e32 v146, 1.0
	v_mov_b32_e32 v199, 1.0
	v_add_f32_e32 v147, 1.0, v144
	v_rcp_f32_e32 v147, v147
	v_mov_b32_e32 v200, 1.0
	v_mul_f32_e32 v144, v144, v182
	v_max_f32_e32 v207, v25, v25
	v_fma_f32 v201, v147, v182, v128
	v_mul_f32_e32 v144, v147, v144
	v_med3_f32 v207, v207, s36, v218
	v_mov_b32_dpp v145, v201 row_shr:1 row_mask:0xf bank_mask:0xf
	v_mul_f32_e32 v145, v201, v145
	v_max_f32_e32 v219, v9, v9
	v_mul_f32_e32 v207, 0xbfb8aa3b, v207
	v_mov_b32_dpp v146, v145 row_shr:2 row_mask:0xf bank_mask:0xf
	v_mul_f32_e32 v145, v145, v146
	v_max_f32_e32 v146, v24, v24
	v_med3_f32 v146, v146, s36, v218
	v_mul_f32_e32 v146, 0xbfb8aa3b, v146
	v_exp_f32_e32 v146, v146
	v_mov_b32_dpp v199, v145 row_shr:4 row_mask:0xf bank_mask:0xf
	v_mul_f32_e32 v145, v145, v199
	v_med3_f32 v219, v219, s36, v218
	v_exp_f32_e32 v207, v207
	v_mov_b32_dpp v200, v145 row_shr:8 row_mask:0xf bank_mask:0xf
	v_mul_f32_e32 v145, v145, v200
	v_add_f32_e32 v200, 1.0, v146
	v_rcp_f32_e32 v199, v145
	v_rcp_f32_e32 v200, v200
	ds_bpermute_b32 v147, v154, v145
	v_mul_f32_e32 v204, v56, v145
	v_mul_f32_e32 v201, v144, v199
	v_fma_f32 v144, v200, v182, v128
	v_mul_f32_e32 v145, v146, v182
	v_mov_b32_e32 v146, 1.0
	v_max_f32_e32 v199, v8, v8
	v_med3_f32 v199, v199, s36, v218
	v_mov_b32_dpp v146, v144 row_shr:1 row_mask:0xf bank_mask:0xf
	v_mul_f32_e32 v144, v144, v146
	v_mov_b32_e32 v146, 1.0
	v_mul_f32_e32 v199, 0xbfb8aa3b, v199
	v_exp_f32_e32 v199, v199
	v_mov_b32_dpp v146, v144 row_shr:2 row_mask:0xf bank_mask:0xf
	v_mul_f32_e32 v144, v144, v146
	v_mov_b32_e32 v146, 1.0
	v_mul_f32_e32 v145, v200, v145
	v_add_f32_e32 v200, 1.0, v199
	v_mov_b32_dpp v146, v144 row_shr:4 row_mask:0xf bank_mask:0xf
	v_mul_f32_e32 v144, v144, v146
	v_mov_b32_e32 v146, 1.0
	v_rcp_f32_e32 v202, v200
	v_mul_f32_e32 v219, 0xbfb8aa3b, v219
	v_mov_b32_dpp v146, v144 row_shr:8 row_mask:0xf bank_mask:0xf
	v_mul_f32_e32 v144, v144, v146
	ds_bpermute_b32 v146, v154, v144
	s_waitcnt lgkmcnt(1)
	v_mul_f32_e32 v144, v144, v147
	v_mul_f32_e32 v203, v44, v144
	v_exp_f32_e32 v219, v219
	v_add_f32_e32 v220, 1.0, v207
	s_waitcnt lgkmcnt(0)
	v_mul_f32_e32 v146, v147, v146
	v_rcp_f32_e32 v147, v144
	v_fma_f32 v144, v202, v182, v128
	v_rcp_f32_e32 v220, v220
	v_mul_f32_e32 v200, v145, v147
	v_mov_b32_e32 v147, 1.0
	v_mul_f32_e32 v145, v199, v182
	v_mul_f32_e32 v145, v202, v145
	v_mov_b32_dpp v147, v144 row_shr:1 row_mask:0xf bank_mask:0xf
	v_mul_f32_e32 v144, v144, v147
	v_mov_b32_e32 v147, 1.0
	v_fma_f32 v222, v220, v179, v129
	s_nop 0
	v_mov_b32_dpp v147, v144 row_shr:2 row_mask:0xf bank_mask:0xf
	v_mul_f32_e32 v144, v144, v147
	v_mov_b32_e32 v147, 1.0
	s_nop 1
	v_mov_b32_dpp v147, v144 row_shr:4 row_mask:0xf bank_mask:0xf
	v_mul_f32_e32 v144, v144, v147
	v_mov_b32_e32 v147, 1.0
	s_nop 1
	v_mov_b32_dpp v147, v144 row_shr:8 row_mask:0xf bank_mask:0xf
	v_mul_f32_e32 v144, v144, v147
	v_max_f32_e32 v147, v0, v0
	v_med3_f32 v147, v147, s36, v218
	v_mul_f32_e32 v147, 0xbfb8aa3b, v147
	v_exp_f32_e32 v147, v147
	v_mul_f32_e32 v199, v146, v144
	v_rcp_f32_e32 v205, v199
	ds_bpermute_b32 v144, v154, v144
	v_add_f32_e32 v202, 1.0, v147
	v_rcp_f32_e32 v206, v202
	v_mul_f32_e32 v202, v28, v199
	v_mul_f32_e32 v199, v145, v205
	v_mul_f32_e32 v145, v147, v182
	v_fma_f32 v128, v206, v182, v128
	v_max_f32_e32 v182, v41, v41
	v_med3_f32 v182, v182, s36, v218
	v_mul_f32_e32 v182, 0xbfb8aa3b, v182
	v_mov_b32_e32 v147, 1.0
	v_exp_f32_e32 v182, v182
	s_waitcnt lgkmcnt(0)
; __device__ __forceinline__ float fexp(float x) { return __builtin_amdgcn_exp2f(x * 1.4426950408889634f); }
; __device__ __forceinline__ float frcp(float x) { return __builtin_amdgcn_rcpf(x); }
;     __device__ __forceinline__ void operator()(Acc& acc, const Unit& u, int wr, int wc, int fr, int fq) const {
;     ...
;                     for (int i = 0; i < 4; ++i) {
;                         const float lbv = lb4[n][i], oml = 1.0f - lbv;
;                         float carry = 1.f;
; #pragma unroll
;                         for (int m = 0; m < 4; ++m) {
;                             float x = acc[ai][1][m][n][i]; x = fminf(fmaxf(x, -30.f), 30.f);
;                             const float ex = fexp(-x), s = frcp(1.0f + ex);
;                             const float f = lbv + oml * s, kk = oml * ex * s;
;                             const float p = row16_prefix_mul(f);
;                             const float eb = carry * p;
;                             carry *= __shfl(p, 15, 16);
;                             float qv = acc[ai][0][m][n][i] * eb, kv = kk * frcp(eb);
;                             asm volatile("" : "+v"(qv), "+v"(kv));
;                             acc[ai][0][m][n][i] = qv; acc[ai][1][m][n][i] = kv;
;                         }
	v_mul_f32_e32 v144, v146, v144
	v_mov_b32_dpp v147, v128 row_shr:1 row_mask:0xf bank_mask:0xf
	v_mul_f32_e32 v128, v128, v147
	v_mov_b32_e32 v147, 1.0
	v_add_f32_e32 v205, 1.0, v182
	v_rcp_f32_e32 v205, v205
	v_mov_b32_dpp v147, v128 row_shr:2 row_mask:0xf bank_mask:0xf
	v_mul_f32_e32 v128, v128, v147
	v_mov_b32_e32 v147, 1.0
	v_mul_f32_e32 v182, v182, v179
	v_mul_f32_e32 v221, v205, v182
	v_mov_b32_dpp v147, v128 row_shr:4 row_mask:0xf bank_mask:0xf
	v_mul_f32_e32 v128, v128, v147
	v_mov_b32_e32 v147, 1.0
	v_add_f32_e32 v182, 1.0, v219
	v_rcp_f32_e32 v182, v182
	v_mov_b32_dpp v147, v128 row_shr:8 row_mask:0xf bank_mask:0xf
	v_mul_f32_e32 v147, v128, v147
	v_mul_f32_e32 v146, v144, v147
	ds_bpermute_b32 v128, v154, v147
	v_rcp_f32_e32 v147, v146
	v_mul_f32_e32 v145, v206, v145
	v_fma_f32 v206, v205, v179, v129
	v_mul_f32_e32 v205, v207, v179
	v_mul_f32_e32 v207, v220, v205
	v_mul_f32_e32 v205, v219, v179
	v_fma_f32 v223, v182, v179, v129
	v_mul_f32_e32 v224, v182, v205
	v_mul_f32_e32 v205, v12, v146
	v_mul_f32_e32 v182, v145, v147
	v_mov_b32_e32 v145, 1.0
	v_mov_b32_e32 v146, 1.0
	v_mov_b32_e32 v147, 1.0
	v_mov_b32_dpp v145, v206 row_shr:1 row_mask:0xf bank_mask:0xf
	v_mul_f32_e32 v145, v206, v145
	s_nop 1
	v_mov_b32_dpp v146, v145 row_shr:2 row_mask:0xf bank_mask:0xf
	v_mul_f32_e32 v145, v145, v146
	v_mov_b32_e32 v146, 1.0
	s_nop 1
	v_mov_b32_dpp v146, v145 row_shr:4 row_mask:0xf bank_mask:0xf
	v_mul_f32_e32 v145, v145, v146
	v_mov_b32_e32 v146, 1.0
	s_nop 1
	v_mov_b32_dpp v146, v145 row_shr:8 row_mask:0xf bank_mask:0xf
	v_mul_f32_e32 v145, v145, v146
	ds_bpermute_b32 v146, v154, v145
	v_mul_f32_e32 v220, v57, v145
	v_rcp_f32_e32 v145, v145
	s_nop 0
	v_mul_f32_e32 v206, v221, v145
	v_mov_b32_e32 v145, 1.0
	s_nop 1
	v_mov_b32_dpp v145, v222 row_shr:1 row_mask:0xf bank_mask:0xf
	v_mul_f32_e32 v145, v222, v145
	s_nop 1
	v_mov_b32_dpp v147, v145 row_shr:2 row_mask:0xf bank_mask:0xf
	v_mul_f32_e32 v145, v145, v147
	v_mov_b32_e32 v147, 1.0
	s_nop 1
	v_mov_b32_dpp v147, v145 row_shr:4 row_mask:0xf bank_mask:0xf
	v_mul_f32_e32 v145, v145, v147
	v_mov_b32_e32 v147, 1.0
	s_nop 1
	v_mov_b32_dpp v147, v145 row_shr:8 row_mask:0xf bank_mask:0xf
	v_mul_f32_e32 v145, v145, v147
	s_waitcnt lgkmcnt(0)
	v_mul_f32_e32 v147, v145, v146
	ds_bpermute_b32 v145, v154, v145
	v_mul_f32_e32 v219, v45, v147
	s_waitcnt lgkmcnt(0)
	v_mul_f32_e32 v145, v146, v145
	v_rcp_f32_e32 v146, v147
	v_mov_b32_e32 v147, 1.0
	v_mul_f32_e32 v221, v207, v146
	v_mov_b32_e32 v146, 1.0
	s_nop 1
	v_mov_b32_dpp v146, v223 row_shr:1 row_mask:0xf bank_mask:0xf
	v_mul_f32_e32 v146, v223, v146
	s_nop 1
	v_mov_b32_dpp v147, v146 row_shr:2 row_mask:0xf bank_mask:0xf
	v_mul_f32_e32 v146, v146, v147
	v_mov_b32_e32 v147, 1.0
	s_nop 1
	v_mov_b32_dpp v147, v146 row_shr:4 row_mask:0xf bank_mask:0xf
	v_mul_f32_e32 v146, v146, v147
	v_mov_b32_e32 v147, 1.0
	s_nop 1
	v_mov_b32_dpp v147, v146 row_shr:8 row_mask:0xf bank_mask:0xf
	v_mul_f32_e32 v146, v146, v147
	v_mul_f32_e32 v147, v145, v146
	ds_bpermute_b32 v146, v154, v146
	v_mul_f32_e32 v222, v29, v147
	s_waitcnt lgkmcnt(0)
	v_mul_f32_e32 v145, v145, v146
	v_rcp_f32_e32 v146, v147
	s_nop 0
	v_mul_f32_e32 v207, v224, v146
	v_max_f32_e32 v146, v1, v1
	v_med3_f32 v146, v146, s36, v218
	v_mul_f32_e32 v146, 0xbfb8aa3b, v146
	v_exp_f32_e32 v146, v146
	s_nop 0
	v_add_f32_e32 v147, 1.0, v146
	v_rcp_f32_e32 v147, v147
	v_mul_f32_e32 v146, v146, v179
	v_fma_f32 v129, v147, v179, v129
	v_mul_f32_e32 v146, v147, v146
	v_mov_b32_e32 v147, 1.0
	s_nop 1
	v_mov_b32_dpp v147, v129 row_shr:1 row_mask:0xf bank_mask:0xf
	v_mul_f32_e32 v129, v129, v147
	v_mov_b32_e32 v147, 1.0
	s_nop 1
	v_mov_b32_dpp v147, v129 row_shr:2 row_mask:0xf bank_mask:0xf
	v_mul_f32_e32 v129, v129, v147
	v_mov_b32_e32 v147, 1.0
	s_nop 1
	v_mov_b32_dpp v147, v129 row_shr:4 row_mask:0xf bank_mask:0xf
	v_mul_f32_e32 v129, v129, v147
	v_mov_b32_e32 v147, 1.0
	s_nop 1
	v_mov_b32_dpp v147, v129 row_shr:8 row_mask:0xf bank_mask:0xf
	v_mul_f32_e32 v129, v129, v147
	v_mul_f32_e32 v147, v145, v129
	ds_bpermute_b32 v129, v154, v129
	v_mul_f32_e32 v179, v13, v147
	v_rcp_f32_e32 v147, v147
	s_nop 0
	v_mul_f32_e32 v223, v146, v147
	v_max_f32_e32 v146, v42, v42
	v_med3_f32 v146, v146, s36, v218
	v_mul_f32_e32 v146, 0xbfb8aa3b, v146
	v_exp_f32_e32 v146, v146
	v_mov_b32_e32 v147, 1.0
	v_mov_b32_e32 v224, 1.0
	v_mov_b32_e32 v226, 1.0
	v_add_f32_e32 v225, 1.0, v146
	v_rcp_f32_e32 v225, v225
	v_mov_b32_e32 v227, 1.0
	v_mul_f32_e32 v146, v146, v183
	v_max_f32_e32 v235, v27, v27
	v_fma_f32 v229, v225, v183, v130
	v_mul_f32_e32 v146, v225, v146
	v_med3_f32 v235, v235, s36, v218
	v_mov_b32_dpp v147, v229 row_shr:1 row_mask:0xf bank_mask:0xf
	v_mul_f32_e32 v147, v229, v147
	v_mul_f32_e32 v235, 0xbfb8aa3b, v235
	v_exp_f32_e32 v235, v235
	v_mov_b32_dpp v224, v147 row_shr:2 row_mask:0xf bank_mask:0xf
	v_mul_f32_e32 v147, v147, v224
	v_max_f32_e32 v224, v26, v26
	v_med3_f32 v224, v224, s36, v218
	v_mul_f32_e32 v224, 0xbfb8aa3b, v224
	v_exp_f32_e32 v224, v224
	v_mov_b32_dpp v226, v147 row_shr:4 row_mask:0xf bank_mask:0xf
	v_mul_f32_e32 v147, v147, v226
	v_max_f32_e32 v236, v11, v11
	v_med3_f32 v236, v236, s36, v218
	v_mov_b32_dpp v227, v147 row_shr:8 row_mask:0xf bank_mask:0xf
	v_mul_f32_e32 v147, v147, v227
	v_add_f32_e32 v227, 1.0, v224
	v_rcp_f32_e32 v226, v147
	v_rcp_f32_e32 v227, v227
	ds_bpermute_b32 v225, v154, v147
	v_mul_f32_e32 v230, v58, v147
	v_mul_f32_e32 v226, v146, v226
	v_fma_f32 v146, v227, v183, v130
	v_mul_f32_e32 v147, v224, v183
	v_mov_b32_e32 v224, 1.0
	v_mul_f32_e32 v147, v227, v147
	v_max_f32_e32 v227, v10, v10
	v_mov_b32_dpp v224, v146 row_shr:1 row_mask:0xf bank_mask:0xf
	v_mul_f32_e32 v146, v146, v224
	v_mov_b32_e32 v224, 1.0
	v_med3_f32 v227, v227, s36, v218
	v_mul_f32_e32 v227, 0xbfb8aa3b, v227
	v_mov_b32_dpp v224, v146 row_shr:2 row_mask:0xf bank_mask:0xf
	v_mul_f32_e32 v146, v146, v224
	v_mov_b32_e32 v224, 1.0
	v_exp_f32_e32 v227, v227
	v_mul_f32_e32 v236, 0xbfb8aa3b, v236
	v_mov_b32_dpp v224, v146 row_shr:4 row_mask:0xf bank_mask:0xf
	v_mul_f32_e32 v146, v146, v224
	v_mov_b32_e32 v224, 1.0
	v_exp_f32_e32 v236, v236
	v_add_f32_e32 v237, 1.0, v235
	v_mov_b32_dpp v224, v146 row_shr:8 row_mask:0xf bank_mask:0xf
	v_mul_f32_e32 v146, v146, v224
	ds_bpermute_b32 v224, v154, v146
	s_waitcnt lgkmcnt(1)
; __device__ __forceinline__ float fexp(float x) { return __builtin_amdgcn_exp2f(x * 1.4426950408889634f); }
; __device__ __forceinline__ float frcp(float x) { return __builtin_amdgcn_rcpf(x); }
;     __device__ __forceinline__ void operator()(Acc& acc, const Unit& u, int wr, int wc, int fr, int fq) const {
;     ...
;                     for (int i = 0; i < 4; ++i) {
;                         const float lbv = lb4[n][i], oml = 1.0f - lbv;
;                         float carry = 1.f;
; #pragma unroll
;                         for (int m = 0; m < 4; ++m) {
;                             float x = acc[ai][1][m][n][i]; x = fminf(fmaxf(x, -30.f), 30.f);
;                             const float ex = fexp(-x), s = frcp(1.0f + ex);
;                             const float f = lbv + oml * s, kk = oml * ex * s;
;                             const float p = row16_prefix_mul(f);
;                             const float eb = carry * p;
;                             carry *= __shfl(p, 15, 16);
;                             float qv = acc[ai][0][m][n][i] * eb, kv = kk * frcp(eb);
;                             asm volatile("" : "+v"(qv), "+v"(kv));
;                             acc[ai][0][m][n][i] = qv; acc[ai][1][m][n][i] = kv;
;                         }
;                         el[n][i] = carry;
;                         __builtin_amdgcn_sched_barrier(0);
;                     }
;                 if (fr == 0) { float* ep = ELAST + (size_t)(u.pm * 4 + ai * 2 + wr) * 512 + hk0; *(f32x4*)ep = el[0]; *(f32x4*)(ep + 4) = el[1]; }
	v_mul_f32_e32 v146, v146, v225
	v_mul_f32_e32 v229, v46, v146
	v_rcp_f32_e32 v237, v237
	v_mul_f32_e32 v235, v235, v180
	s_waitcnt lgkmcnt(0)
	v_mul_f32_e32 v231, v225, v224
	v_add_f32_e32 v225, 1.0, v227
	v_rcp_f32_e32 v224, v146
	v_rcp_f32_e32 v232, v225
	v_fma_f32 v238, v237, v180, v131
	v_mul_f32_e32 v237, v237, v235
	v_mul_f32_e32 v225, v147, v224
	v_fma_f32 v146, v232, v183, v130
	v_mov_b32_e32 v224, 1.0
	v_mul_f32_e32 v147, v227, v183
	v_mul_f32_e32 v147, v232, v147
	v_mov_b32_dpp v224, v146 row_shr:1 row_mask:0xf bank_mask:0xf
	v_mul_f32_e32 v146, v146, v224
	v_mov_b32_e32 v224, 1.0
	s_nop 1
	v_mov_b32_dpp v224, v146 row_shr:2 row_mask:0xf bank_mask:0xf
	v_mul_f32_e32 v146, v146, v224
	v_mov_b32_e32 v224, 1.0
	s_nop 1
	v_mov_b32_dpp v224, v146 row_shr:4 row_mask:0xf bank_mask:0xf
	v_mul_f32_e32 v146, v146, v224
	v_mov_b32_e32 v224, 1.0
	s_nop 1
	v_mov_b32_dpp v224, v146 row_shr:8 row_mask:0xf bank_mask:0xf
	v_mul_f32_e32 v146, v146, v224
	v_max_f32_e32 v224, v2, v2
	v_med3_f32 v224, v224, s36, v218
	v_mul_f32_e32 v224, 0xbfb8aa3b, v224
	v_exp_f32_e32 v232, v224
	v_mul_f32_e32 v224, v231, v146
	v_rcp_f32_e32 v233, v224
	ds_bpermute_b32 v146, v154, v146
	v_add_f32_e32 v227, 1.0, v232
	v_rcp_f32_e32 v234, v227
	v_mul_f32_e32 v227, v30, v224
	v_mul_f32_e32 v224, v147, v233
	v_mul_f32_e32 v147, v232, v183
	v_max_f32_e32 v232, v43, v43
	v_med3_f32 v232, v232, s36, v218
	v_mul_f32_e32 v232, 0xbfb8aa3b, v232
	v_fma_f32 v130, v234, v183, v130
	v_mov_b32_e32 v183, 1.0
	v_exp_f32_e32 v232, v232
	s_waitcnt lgkmcnt(0)
	v_mul_f32_e32 v146, v231, v146
	v_mov_b32_dpp v183, v130 row_shr:1 row_mask:0xf bank_mask:0xf
	v_mul_f32_e32 v130, v130, v183
	v_mov_b32_e32 v183, 1.0
	v_add_f32_e32 v233, 1.0, v232
	v_rcp_f32_e32 v233, v233
	v_mov_b32_dpp v183, v130 row_shr:2 row_mask:0xf bank_mask:0xf
	v_mul_f32_e32 v130, v130, v183
	v_mov_b32_e32 v183, 1.0
	v_mul_f32_e32 v232, v232, v180
	v_mul_f32_e32 v147, v234, v147
	v_mov_b32_dpp v183, v130 row_shr:4 row_mask:0xf bank_mask:0xf
	v_mul_f32_e32 v130, v130, v183
	v_mov_b32_e32 v183, 1.0
	v_fma_f32 v234, v233, v180, v131
	v_mul_f32_e32 v232, v233, v232
	v_mov_b32_dpp v183, v130 row_shr:8 row_mask:0xf bank_mask:0xf
	v_mul_f32_e32 v183, v130, v183
	ds_bpermute_b32 v130, v154, v183
	v_add_f32_e32 v233, 1.0, v236
	v_mul_f32_e32 v183, v146, v183
	v_rcp_f32_e32 v233, v233
	v_rcp_f32_e32 v235, v183
	v_mul_f32_e32 v231, v236, v180
	v_fma_f32 v239, v233, v180, v131
	v_mul_f32_e32 v233, v233, v231
	v_mul_f32_e32 v231, v14, v183
	v_mul_f32_e32 v183, v147, v235
	v_mov_b32_e32 v147, 1.0
	v_mov_b32_e32 v236, 1.0
	s_nop 0
	v_mov_b32_dpp v147, v234 row_shr:1 row_mask:0xf bank_mask:0xf
	v_mul_f32_e32 v147, v234, v147
	v_mov_b32_e32 v234, 1.0
	s_nop 1
	v_mov_b32_dpp v234, v147 row_shr:2 row_mask:0xf bank_mask:0xf
	v_mul_f32_e32 v147, v147, v234
	v_mov_b32_e32 v234, 1.0
	s_nop 1
	v_mov_b32_dpp v234, v147 row_shr:4 row_mask:0xf bank_mask:0xf
	v_mul_f32_e32 v147, v147, v234
	v_mov_b32_e32 v234, 1.0
	s_nop 1
	v_mov_b32_dpp v234, v147 row_shr:8 row_mask:0xf bank_mask:0xf
	v_mul_f32_e32 v147, v147, v234
	ds_bpermute_b32 v234, v154, v147
	v_mul_f32_e32 v235, v59, v147
	v_rcp_f32_e32 v147, v147
	s_nop 0
	v_mul_f32_e32 v232, v232, v147
	v_mov_b32_e32 v147, 1.0
	s_nop 1
	v_mov_b32_dpp v147, v238 row_shr:1 row_mask:0xf bank_mask:0xf
	v_mul_f32_e32 v147, v238, v147
	v_mov_b32_e32 v238, 1.0
	s_nop 0
	v_mov_b32_dpp v236, v147 row_shr:2 row_mask:0xf bank_mask:0xf
	v_mul_f32_e32 v147, v147, v236
	v_mov_b32_e32 v236, 1.0
	s_nop 1
	v_mov_b32_dpp v236, v147 row_shr:4 row_mask:0xf bank_mask:0xf
	v_mul_f32_e32 v147, v147, v236
	v_mov_b32_e32 v236, 1.0
	s_nop 1
	v_mov_b32_dpp v236, v147 row_shr:8 row_mask:0xf bank_mask:0xf
	v_mul_f32_e32 v147, v147, v236
	s_waitcnt lgkmcnt(0)
	v_mul_f32_e32 v236, v147, v234
	ds_bpermute_b32 v147, v154, v147
	s_waitcnt lgkmcnt(0)
	v_mul_f32_e32 v147, v234, v147
	v_mul_f32_e32 v234, v47, v236
	v_rcp_f32_e32 v236, v236
	s_nop 0
	v_mul_f32_e32 v236, v237, v236
	v_mov_b32_e32 v237, 1.0
	s_nop 1
	v_mov_b32_dpp v237, v239 row_shr:1 row_mask:0xf bank_mask:0xf
	v_mul_f32_e32 v237, v239, v237
	s_nop 1
	v_mov_b32_dpp v238, v237 row_shr:2 row_mask:0xf bank_mask:0xf
	v_mul_f32_e32 v237, v237, v238
	v_mov_b32_e32 v238, 1.0
	s_nop 1
	v_mov_b32_dpp v238, v237 row_shr:4 row_mask:0xf bank_mask:0xf
	v_mul_f32_e32 v237, v237, v238
	v_mov_b32_e32 v238, 1.0
	s_nop 1
	v_mov_b32_dpp v238, v237 row_shr:8 row_mask:0xf bank_mask:0xf
	v_mul_f32_e32 v237, v237, v238
	v_mul_f32_e32 v238, v147, v237
	ds_bpermute_b32 v237, v154, v237
	s_waitcnt lgkmcnt(0)
	v_mul_f32_e32 v147, v147, v237
	v_mul_f32_e32 v237, v31, v238
	v_rcp_f32_e32 v238, v238
	s_nop 0
	v_mul_f32_e32 v233, v233, v238
	v_max_f32_e32 v238, v3, v3
	v_med3_f32 v238, v238, s36, v218
	v_mul_f32_e32 v238, 0xbfb8aa3b, v238
	v_exp_f32_e32 v238, v238
	s_nop 0
	v_add_f32_e32 v239, 1.0, v238
	v_rcp_f32_e32 v239, v239
	s_nop 0
	v_fmac_f32_e32 v131, v239, v180
	v_mul_f32_e32 v180, v238, v180
	v_mov_b32_e32 v238, 1.0
	v_mul_f32_e32 v180, v239, v180
	s_nop 0
	v_mov_b32_dpp v238, v131 row_shr:1 row_mask:0xf bank_mask:0xf
	v_mul_f32_e32 v131, v131, v238
	v_mov_b32_e32 v238, 1.0
	s_nop 1
	v_mov_b32_dpp v238, v131 row_shr:2 row_mask:0xf bank_mask:0xf
	v_mul_f32_e32 v131, v131, v238
	v_mov_b32_e32 v238, 1.0
	s_nop 1
	v_mov_b32_dpp v238, v131 row_shr:4 row_mask:0xf bank_mask:0xf
	v_mul_f32_e32 v131, v131, v238
	v_mov_b32_e32 v238, 1.0
	s_nop 1
	v_mov_b32_dpp v238, v131 row_shr:8 row_mask:0xf bank_mask:0xf
	v_mul_f32_e32 v131, v131, v238
	v_mul_f32_e32 v238, v147, v131
	ds_bpermute_b32 v131, v154, v131
	v_mul_f32_e32 v154, v15, v238
	v_rcp_f32_e32 v238, v238
	s_nop 0
	v_mul_f32_e32 v180, v180, v238
	s_and_saveexec_b64 s[4:5], vcc
	s_cbranch_execz .LBB0_195
	s_lshl_b32 s12, s84, 2
	s_add_i32 s48, s77, s12
	s_ashr_i32 s49, s48, 31
	s_lshl_b64 s[48:49], s[48:49], 11
	s_add_u32 s48, s55, s48
	s_addc_u32 s49, s58, s49
	v_pk_mul_f32 v[134:135], v[142:143], v[134:135]
	v_pk_mul_f32 v[132:133], v[140:141], v[132:133]
	v_lshl_add_u64 v[136:137], v[136:137], 2, s[48:49]
	s_waitcnt lgkmcnt(0)
	v_pk_mul_f32 v[130:131], v[146:147], v[130:131]
	v_pk_mul_f32 v[128:129], v[144:145], v[128:129]
	global_store_dwordx4 v[136:137], v[132:135], off sc1
	global_store_dwordx4 v[136:137], v[128:131], off offset:16 sc1
; __device__ __forceinline__ u32x4 pack8(const f32x4& a, const f32x4& b) { u32x4 w; w.x = cvt_pk_bf16(a[0], a[1]); w.y = cvt_pk_bf16(a[2], a[3]); w.z = cvt_pk_bf16(b[0], b[1]); w.w = cvt_pk_bf16(b[2], b[3]); return w; }
;     __device__ __forceinline__ void operator()(Acc& acc, const Unit& u, int wr, int wc, int fr, int fq) const {
;     ...
;                 for (int m = 0; m < 4; ++m) { const size_t o = (size_t)(row0 + ai * HALF + m * 16) * 512 + hk0;
;                     *(u32x4*)(QT + o) = pack8(acc[ai][0][m][0], acc[ai][0][m][1]); *(u32x4*)(KT + o) = pack8(acc[ai][1][m][0], acc[ai][1][m][1]); }
.LBB0_195:
	s_or_b64 exec, exec, s[4:5]
	v_lshl_add_u64 v[132:133], v[138:139], 0, s[66:67]
	v_cvt_pk_bf16_f32 v128, v153, v175
	v_cvt_pk_bf16_f32 v129, v190, v195
	v_cvt_pk_bf16_f32 v130, v204, v220
	s_waitcnt lgkmcnt(0)
	v_cvt_pk_bf16_f32 v131, v230, v235
	v_lshl_add_u64 v[134:135], s[74:75], 0, v[132:133]
	v_lshl_add_u64 v[132:133], s[0:1], 0, v[132:133]
	s_mov_b64 s[4:5], 0x24000
	global_store_dwordx4 v[134:135], v[128:131], off sc1
	s_nop 1
	v_cvt_pk_bf16_f32 v128, v150, v157
	v_cvt_pk_bf16_f32 v129, v187, v192
	v_cvt_pk_bf16_f32 v130, v201, v206
	v_cvt_pk_bf16_f32 v131, v226, v232
	global_store_dwordx4 v[132:133], v[128:131], off sc1
	v_lshl_add_u64 v[132:133], v[138:139], 0, s[4:5]
	v_lshl_add_u64 v[134:135], s[74:75], 0, v[132:133]
	v_cvt_pk_bf16_f32 v128, v152, v159
	v_cvt_pk_bf16_f32 v129, v189, v194
	v_cvt_pk_bf16_f32 v130, v203, v219
	v_cvt_pk_bf16_f32 v131, v229, v234
	v_lshl_add_u64 v[132:133], s[0:1], 0, v[132:133]
	s_mov_b64 s[4:5], 0x28000
	global_store_dwordx4 v[134:135], v[128:131], off sc1
	s_nop 1
	v_cvt_pk_bf16_f32 v128, v149, v176
	v_cvt_pk_bf16_f32 v129, v186, v196
	v_cvt_pk_bf16_f32 v130, v200, v221
	v_cvt_pk_bf16_f32 v131, v225, v236
	global_store_dwordx4 v[132:133], v[128:131], off sc1
	v_lshl_add_u64 v[132:133], v[138:139], 0, s[4:5]
	v_lshl_add_u64 v[134:135], s[74:75], 0, v[132:133]
	v_cvt_pk_bf16_f32 v128, v151, v177
	v_cvt_pk_bf16_f32 v129, v188, v197
	v_cvt_pk_bf16_f32 v130, v202, v222
	v_cvt_pk_bf16_f32 v131, v227, v237
	v_lshl_add_u64 v[132:133], s[0:1], 0, v[132:133]
	s_mov_b64 s[4:5], 0x2c000
	global_store_dwordx4 v[134:135], v[128:131], off sc1
	s_nop 1
	v_cvt_pk_bf16_f32 v128, v148, v158
	v_cvt_pk_bf16_f32 v129, v185, v193
	v_cvt_pk_bf16_f32 v130, v199, v207
	v_cvt_pk_bf16_f32 v131, v224, v233
	global_store_dwordx4 v[132:133], v[128:131], off sc1
	v_lshl_add_u64 v[132:133], v[138:139], 0, s[4:5]
	v_lshl_add_u64 v[134:135], s[74:75], 0, v[132:133]
	v_cvt_pk_bf16_f32 v128, v156, v173
	v_cvt_pk_bf16_f32 v129, v191, v178
	v_cvt_pk_bf16_f32 v130, v205, v179
	v_cvt_pk_bf16_f32 v131, v231, v154
	v_lshl_add_u64 v[132:133], s[0:1], 0, v[132:133]
	global_store_dwordx4 v[134:135], v[128:131], off sc1
	s_nop 1
	v_cvt_pk_bf16_f32 v128, v155, v184
	v_cvt_pk_bf16_f32 v129, v181, v198
	v_cvt_pk_bf16_f32 v130, v182, v223
	v_cvt_pk_bf16_f32 v131, v183, v180
	global_store_dwordx4 v[132:133], v[128:131], off sc1

; __device__ __forceinline__ u32x4 pack8(const f32x4& a, const f32x4& b) { u32x4 w; w.x = cvt_pk_bf16(a[0], a[1]); w.y = cvt_pk_bf16(a[2], a[3]); w.z = cvt_pk_bf16(b[0], b[1]); w.w = cvt_pk_bf16(b[2], b[3]); return w; }
;     __device__ __forceinline__ void operator()(Acc& acc, const Unit& u, int wr, int wc, int fr, int fq) const {
;     ...
;         if (u.kind == 1) {
; #pragma unroll
;             for (int ai = 0; ai < 2; ++ai)
; #pragma unroll
;                 for (int m = 0; m < 4; ++m)
; #pragma unroll
;                     for (int bj = 0; bj < 2; ++bj) *(u32x4*)(KVM + (size_t)(row0 + ai * HALF + m * 16) * 1024 + u.pn * 256 + bj * HALF + cw) = pack8(acc[ai][bj][m][0], acc[ai][bj][m][1]);
;             return;
.LBB0_199:
	v_ashrrev_i32_e32 v175, 31, v174
	v_readlane_b32 s4, v254, 53
	v_lshlrev_b64 v[128:129], 11, v[174:175]
	v_readlane_b32 s5, v254, 54
	v_cvt_pk_bf16_f32 v124, v124, v125
	v_cvt_pk_bf16_f32 v125, v126, v127
	v_cvt_pk_bf16_f32 v126, v120, v121
	v_ashrrev_i32_e32 v173, 31, v172
	v_cvt_pk_bf16_f32 v127, v122, v123
	s_nop 0
	v_lshl_add_u64 v[120:121], s[4:5], 0, v[128:129]
	s_lshl_b32 s4, s40, 8
	s_ashr_i32 s5, s4, 31
	v_lshl_add_u64 v[120:121], s[4:5], 1, v[120:121]
	v_lshl_add_u64 v[120:121], v[172:173], 1, v[120:121]
	s_mov_b32 s4, 0x8000
	global_store_dwordx4 v[120:121], v[124:127], off sc1
	v_cvt_pk_bf16_f32 v112, v112, v113
	v_cvt_pk_bf16_f32 v113, v114, v115
	v_cvt_pk_bf16_f32 v114, v104, v105
	v_cvt_pk_bf16_f32 v115, v106, v107
	global_store_dwordx4 v[120:121], v[112:115], off offset:256 sc1
	v_cvt_pk_bf16_f32 v104, v116, v117
	v_cvt_pk_bf16_f32 v105, v118, v119
	v_cvt_pk_bf16_f32 v106, v108, v109
	v_cvt_pk_bf16_f32 v107, v110, v111
	v_add_co_u32_e32 v110, vcc, s4, v120
	v_lshl_add_u64 v[108:109], v[120:121], 0, s[24:25]
	s_nop 0
	v_addc_co_u32_e32 v111, vcc, 0, v121, vcc
	s_mov_b64 s[4:5], 0x10000
	global_store_dwordx4 v[110:111], v[104:107], off sc1
	v_cvt_pk_bf16_f32 v96, v96, v97
	v_cvt_pk_bf16_f32 v97, v98, v99
	v_cvt_pk_bf16_f32 v98, v88, v89
	v_cvt_pk_bf16_f32 v99, v90, v91
	global_store_dwordx4 v[108:109], v[96:99], off offset:256 sc1
	v_cvt_pk_bf16_f32 v88, v100, v101
	v_cvt_pk_bf16_f32 v89, v102, v103
	v_cvt_pk_bf16_f32 v90, v92, v93
	v_lshl_add_u64 v[92:93], v[120:121], 0, s[4:5]
	s_mov_b32 s4, 0x10000
	v_cvt_pk_bf16_f32 v91, v94, v95
	v_add_co_u32_e32 v94, vcc, s4, v120
	s_mov_b64 s[4:5], 0x18000
	s_nop 0
	v_addc_co_u32_e32 v95, vcc, 0, v121, vcc
	global_store_dwordx4 v[94:95], v[88:91], off sc1
	v_cvt_pk_bf16_f32 v80, v80, v81
	v_cvt_pk_bf16_f32 v81, v82, v83
	v_cvt_pk_bf16_f32 v82, v72, v73
	v_cvt_pk_bf16_f32 v83, v74, v75
	global_store_dwordx4 v[92:93], v[80:83], off offset:256 sc1
	v_cvt_pk_bf16_f32 v72, v84, v85
	v_cvt_pk_bf16_f32 v73, v86, v87
	v_cvt_pk_bf16_f32 v74, v76, v77
	v_lshl_add_u64 v[76:77], v[120:121], 0, s[4:5]
	s_mov_b32 s4, 0x18000
	v_cvt_pk_bf16_f32 v75, v78, v79
	v_add_co_u32_e32 v78, vcc, s4, v120
	s_mov_b64 s[4:5], 0x40000
	s_nop 0
	v_addc_co_u32_e32 v79, vcc, 0, v121, vcc
	global_store_dwordx4 v[78:79], v[72:75], off sc1
	v_cvt_pk_bf16_f32 v68, v68, v69
	v_cvt_pk_bf16_f32 v69, v70, v71
	v_cvt_pk_bf16_f32 v70, v64, v65
	v_cvt_pk_bf16_f32 v71, v66, v67
	global_store_dwordx4 v[76:77], v[68:71], off offset:256 sc1
	v_cvt_pk_bf16_f32 v60, v60, v61
	v_cvt_pk_bf16_f32 v61, v62, v63
	v_cvt_pk_bf16_f32 v62, v56, v57
	v_lshl_add_u64 v[56:57], v[120:121], 0, s[4:5]
	s_mov_b32 s4, 0x40000
	v_cvt_pk_bf16_f32 v63, v58, v59
	v_add_co_u32_e32 v58, vcc, s4, v120
	s_mov_b64 s[4:5], 0x48000
	s_nop 0
	v_addc_co_u32_e32 v59, vcc, 0, v121, vcc
	global_store_dwordx4 v[58:59], v[60:63], off sc1
	v_cvt_pk_bf16_f32 v48, v48, v49
	v_cvt_pk_bf16_f32 v49, v50, v51
	v_cvt_pk_bf16_f32 v50, v40, v41
	v_cvt_pk_bf16_f32 v51, v42, v43
	global_store_dwordx4 v[56:57], v[48:51], off offset:256 sc1
	v_cvt_pk_bf16_f32 v40, v52, v53
	v_cvt_pk_bf16_f32 v41, v54, v55
	v_cvt_pk_bf16_f32 v42, v44, v45
	v_lshl_add_u64 v[44:45], v[120:121], 0, s[4:5]
	s_mov_b32 s4, 0x48000
	v_cvt_pk_bf16_f32 v43, v46, v47
	v_add_co_u32_e32 v46, vcc, s4, v120
	s_mov_b64 s[4:5], 0x50000
	s_nop 0
	v_addc_co_u32_e32 v47, vcc, 0, v121, vcc
	global_store_dwordx4 v[46:47], v[40:43], off sc1
	v_cvt_pk_bf16_f32 v32, v32, v33
	v_cvt_pk_bf16_f32 v33, v34, v35
	v_cvt_pk_bf16_f32 v34, v24, v25
	v_cvt_pk_bf16_f32 v35, v26, v27
	global_store_dwordx4 v[44:45], v[32:35], off offset:256 sc1
	v_cvt_pk_bf16_f32 v24, v36, v37
	v_cvt_pk_bf16_f32 v25, v38, v39
	v_cvt_pk_bf16_f32 v26, v28, v29
	v_lshl_add_u64 v[28:29], v[120:121], 0, s[4:5]
	s_mov_b32 s4, 0x50000
	v_cvt_pk_bf16_f32 v27, v30, v31
	v_add_co_u32_e32 v30, vcc, s4, v120
	s_mov_b64 s[4:5], 0x58000
	s_nop 0
	v_addc_co_u32_e32 v31, vcc, 0, v121, vcc
	global_store_dwordx4 v[30:31], v[24:27], off sc1
	v_cvt_pk_bf16_f32 v16, v16, v17
	v_cvt_pk_bf16_f32 v17, v18, v19
	v_cvt_pk_bf16_f32 v18, v8, v9
	v_cvt_pk_bf16_f32 v19, v10, v11
	global_store_dwordx4 v[28:29], v[16:19], off offset:256 sc1
	v_cvt_pk_bf16_f32 v8, v20, v21
	v_cvt_pk_bf16_f32 v9, v22, v23
	v_cvt_pk_bf16_f32 v10, v12, v13
	v_lshl_add_u64 v[12:13], v[120:121], 0, s[4:5]
	s_mov_b32 s4, 0x58000
	v_cvt_pk_bf16_f32 v11, v14, v15
	v_add_co_u32_e32 v14, vcc, s4, v120
	s_nop 1
	v_addc_co_u32_e32 v15, vcc, 0, v121, vcc
	global_store_dwordx4 v[14:15], v[8:11], off sc1
	v_cvt_pk_bf16_f32 v4, v4, v5
	v_cvt_pk_bf16_f32 v5, v6, v7
	v_cvt_pk_bf16_f32 v6, v0, v1
	v_cvt_pk_bf16_f32 v7, v2, v3
	global_store_dwordx4 v[12:13], v[4:7], off offset:256 sc1
	s_and_b64 vcc, exec, s[6:7]
	s_mov_b64 s[4:5], -1
	s_cbranch_vccnz .LBB0_161

; __device__ __forceinline__ void hgrn_mfma(Frame& F, int b, int h) {
;     ...
;         auto hgrn_sgload = [&](int cc, int tb2) __attribute__((always_inline)) {
;             const bf16_t* sgb = SG + (rbase + 64 * cc) * 512 + colh + 32 * (w - 4);
; #pragma unroll
;             for (int j = 0; j < 2; ++j) { const int idx = lane + 64 * j, row = idx >> 2, c8 = idx & 3, t = 32 * tb2 + row; sgp[tb2][j] = *(const u32x4*)(sgb + (unsigned)(t * 512 + 8 * c8)); }
;         };
;         auto hgrn_finalize = [&](int cc, int tb2) __attribute__((always_inline)) {
;             const int vb = w - 4; const size_t row0 = rbase + 64 * cc;
;             bf16_t* mxb = MIX + row0 * 1024 + colh + 32 * vb;
;             const LAS float* rq = rowsq + (cc & 1) * 256; const LAS unsigned char* sb_ = stg + (cc & 1) * 20480 + tb2 * 2560;
; #pragma unroll
;             for (int j = 0; j < 2; ++j) { const int idx = lane + 64 * j, row = idx >> 2, c8 = idx & 3, t = 32 * tb2 + row;
;                 const u32x4 sg = sgp[tb2][j];
;                 const float rstd = frsq(((rq[t] + rq[64 + t]) + (rq[128 + t] + rq[192 + t])) * (1.0f / 128.0f) + EPS);
;                 const u32x4 a = *(const LAS u32x4*)(sb_ + row * 80 + c8 * 16);
;                 u32x4 ov; ov.x = cvtpk(bflo(a.x) * rstd * bflo(sg.x), bfhi(a.x) * rstd * bfhi(sg.x)); ov.y = cvtpk(bflo(a.y) * rstd * bflo(sg.y), bfhi(a.y) * rstd * bfhi(sg.y));
;                 ov.z = cvtpk(bflo(a.z) * rstd * bflo(sg.z), bfhi(a.z) * rstd * bfhi(sg.z)); ov.w = cvtpk(bflo(a.w) * rstd * bflo(sg.w), bfhi(a.w) * rstd * bfhi(sg.w));
;                 *(u32x4*)(mxb + (unsigned)(t * 1024 + 8 * c8)) = ov; }
;         };
;         for (int c = 0; c < 32; ++c) {
;             const LAS unsigned char* Qi = img + (c & 1) * 49152; const LAS unsigned char* Ki = Qi + 16384;
;             u32x4 tmp[12]; f32x4 etmp = {0.f, 0.f, 0.f, 0.f};
;             const size_t nrow0 = rbase + 64 * ((c + 1 < 32) ? c + 1 : c);
;             const unsigned ploff = (unsigned)(ht >> 4) * 512u + 8u * (unsigned)(ht & 15);
; #pragma unroll
;             for (int i = 0; i < 12; ++i) { const int tensor = i >> 2;
;                 const bf16_t* tb_ = (tensor == 0 ? QT : tensor == 1 ? KT : V) + nrow0 * 512 + colh + (i & 3) * 8192;
;                 tmp[i] = *(const u32x4*)(tb_ + ploff); }
;             if (ht < 32) etmp = *(const f32x4*)(ELAST + (nrow0 >> 6) * 512 + colh + (unsigned)(4 * ht));
.LBB0_544:
	s_or_b64 exec, exec, s[68:69]
	s_and_b32 s66, s73, 1
	s_lshl_b32 s67, s66, 10
	s_add_i32 s67, s67, 0
	s_add_i32 s67, s67, 0x19800
	v_lshl_add_u32 v139, v136, 2, s67
	ds_read2st64_b32 v[0:1], v139 offset1:1
	ds_read2st64_b32 v[2:3], v139 offset0:2 offset1:3
	s_mulk_i32 s66, 0x5000
	s_add_i32 s66, s41, s66
	s_waitcnt vmcnt(15)
	v_lshlrev_b32_e32 v12, 16, v20
	s_waitcnt lgkmcnt(1)
	v_mov_b32_e32 v4, v0
	s_waitcnt lgkmcnt(0)
	v_mov_b32_e32 v5, v2
	v_mov_b32_e32 v2, v1
	v_pk_add_f32 v[0:1], v[4:5], v[2:3]
	v_and_b32_e32 v13, 0xffff0000, v20
	v_add_f32_e32 v0, v0, v1
	v_fmamk_f32 v4, v0, 0x3c000000, v89
	v_add_u32_e32 v0, s66, v135
	v_add_u32_e32 v138, v0, v124
	ds_read_b128 v[0:3], v138
	v_rsq_f32_e32 v8, v4
	v_add_u32_e32 v4, s66, v125
	v_add_u32_e32 v91, v4, v124
	ds_read_b128 v[4:7], v91
	s_waitcnt lgkmcnt(1)
	v_lshlrev_b32_e32 v10, 16, v0
	v_and_b32_e32 v11, 0xffff0000, v0
	v_pk_mul_f32 v[10:11], v[8:9], v[10:11] op_sel_hi:[0,1]
	v_pk_mul_f32 v[10:11], v[10:11], v[12:13]
	v_lshlrev_b32_e32 v12, 16, v21
	v_cvt_pk_bf16_f32 v0, v10, v11
	v_lshlrev_b32_e32 v10, 16, v1
	v_and_b32_e32 v11, 0xffff0000, v1
	v_pk_mul_f32 v[10:11], v[8:9], v[10:11] op_sel_hi:[0,1]
	v_and_b32_e32 v13, 0xffff0000, v21
	v_pk_mul_f32 v[10:11], v[10:11], v[12:13]
	v_lshlrev_b32_e32 v12, 16, v22
	v_cvt_pk_bf16_f32 v1, v10, v11
	v_lshlrev_b32_e32 v10, 16, v2
	v_and_b32_e32 v11, 0xffff0000, v2
	v_pk_mul_f32 v[10:11], v[8:9], v[10:11] op_sel_hi:[0,1]
	v_and_b32_e32 v13, 0xffff0000, v22
	v_lshl_add_u32 v140, v126, 2, s67
	v_pk_mul_f32 v[10:11], v[10:11], v[12:13]
	ds_read2st64_b32 v[12:13], v140 offset1:1
	ds_read2st64_b32 v[14:15], v140 offset0:2 offset1:3
	v_cvt_pk_bf16_f32 v2, v10, v11
	v_lshlrev_b32_e32 v10, 16, v3
	v_and_b32_e32 v11, 0xffff0000, v3
	v_pk_mul_f32 v[8:9], v[8:9], v[10:11] op_sel_hi:[0,1]
	v_lshlrev_b32_e32 v10, 16, v23
	v_and_b32_e32 v11, 0xffff0000, v23
	v_pk_mul_f32 v[8:9], v[8:9], v[10:11]
	s_waitcnt lgkmcnt(1)
	v_mov_b32_e32 v10, v12
	s_waitcnt lgkmcnt(0)
	v_mov_b32_e32 v11, v14
	v_mov_b32_e32 v14, v13
	v_pk_add_f32 v[10:11], v[10:11], v[14:15]
	v_cvt_pk_bf16_f32 v3, v8, v9
	v_add_f32_e32 v10, v10, v11
	v_fmamk_f32 v10, v10, 0x3c000000, v89
	v_rsq_f32_e32 v10, v10
	v_lshl_add_u64 v[8:9], v[98:99], 0, s[42:43]
	global_store_dwordx4 v[8:9], v[0:3], off sc1
	s_andn2_b64 vcc, exec, s[46:47]
	s_add_i32 s72, s73, 1
	v_lshlrev_b32_e32 v0, 16, v4
	v_and_b32_e32 v1, 0xffff0000, v4
	v_pk_mul_f32 v[0:1], v[10:11], v[0:1] op_sel_hi:[0,1]
	s_waitcnt vmcnt(15)
	v_lshlrev_b32_e32 v2, 16, v16
	v_and_b32_e32 v3, 0xffff0000, v16
	v_pk_mul_f32 v[0:1], v[0:1], v[2:3]
	v_lshlrev_b32_e32 v2, 16, v5
	v_and_b32_e32 v3, 0xffff0000, v5
	v_pk_mul_f32 v[2:3], v[10:11], v[2:3] op_sel_hi:[0,1]
	v_lshlrev_b32_e32 v4, 16, v17
	v_and_b32_e32 v5, 0xffff0000, v17
	v_pk_mul_f32 v[2:3], v[2:3], v[4:5]
	v_cvt_pk_bf16_f32 v0, v0, v1
	v_cvt_pk_bf16_f32 v1, v2, v3
	v_lshlrev_b32_e32 v2, 16, v6
	v_and_b32_e32 v3, 0xffff0000, v6
	v_pk_mul_f32 v[2:3], v[10:11], v[2:3] op_sel_hi:[0,1]
	v_lshlrev_b32_e32 v4, 16, v18
	v_and_b32_e32 v5, 0xffff0000, v18
	v_pk_mul_f32 v[2:3], v[2:3], v[4:5]
	v_lshlrev_b32_e32 v4, 16, v7
	v_and_b32_e32 v5, 0xffff0000, v7
	v_pk_mul_f32 v[4:5], v[10:11], v[4:5] op_sel_hi:[0,1]
	v_lshlrev_b32_e32 v6, 16, v19
	v_and_b32_e32 v7, 0xffff0000, v19
	v_pk_mul_f32 v[4:5], v[4:5], v[6:7]
	v_cvt_pk_bf16_f32 v2, v2, v3
	v_cvt_pk_bf16_f32 v3, v4, v5
	v_lshl_add_u64 v[4:5], v[96:97], 0, s[42:43]
	global_store_dwordx4 v[4:5], v[0:3], off sc1
	s_nop 1
	v_lshl_add_u64 v[0:1], v[106:107], 0, s[42:43]
	global_load_dwordx4 v[20:23], v[0:1], off
	v_lshl_add_u64 v[0:1], v[104:105], 0, s[42:43]
	global_load_dwordx4 v[16:19], v[0:1], off
	s_cbranch_vccnz .LBB0_552
	s_bitcmp1_b32 s72, 0
	s_cselect_b32 s66, 0xc000, 0
	s_add_i32 s66, s66, 0
	s_add_i32 s67, s66, s62
	s_add_i32 s66, s66, s63
	v_add_u32_e32 v141, s67, v122
	v_add_u32_e32 v166, s66, v122
	v_add_u32_e32 v167, s67, v123
	v_add_u32_e32 v170, s66, v123
	ds_read_b128 v[0:3], v141 offset:16384
	ds_read_b128 v[142:145], v141 offset:16896
	ds_read_b128 v[4:7], v166
	ds_read_b128 v[146:149], v166 offset:512
	ds_read_b128 v[150:153], v167 offset:16384
	ds_read_b128 v[154:157], v167 offset:16896
	ds_read_b128 v[158:161], v170
	ds_read_b128 v[162:165], v170 offset:512
	s_waitcnt lgkmcnt(5)
	v_mfma_f32_32x32x16_bf16 v[0:15], v[0:3], v[4:7], 0
	s_waitcnt lgkmcnt(1)
	v_mfma_f32_32x32x16_bf16 v[0:15], v[150:153], v[158:161], v[0:15]
	v_mfma_f32_32x32x16_bf16 v[0:15], v[142:145], v[146:149], v[0:15]
	s_waitcnt lgkmcnt(0)
	v_mfma_f32_32x32x16_bf16 v[0:15], v[154:157], v[162:165], v[0:15]
	ds_read_b128 v[142:145], v141 offset:17408
	ds_read_b128 v[146:149], v141 offset:17920
	ds_read_b128 v[150:153], v166 offset:1024
	ds_read_b128 v[154:157], v166 offset:1536
	ds_read_b128 v[158:161], v167 offset:17408
	ds_read_b128 v[162:165], v167 offset:17920
	ds_read_b128 v[166:169], v170 offset:1024
	ds_read_b128 v[170:173], v170 offset:1536
	s_waitcnt lgkmcnt(5)
	v_mfma_f32_32x32x16_bf16 v[0:15], v[142:145], v[150:153], v[0:15]
	s_waitcnt lgkmcnt(1)
	v_mfma_f32_32x32x16_bf16 v[0:15], v[158:161], v[166:169], v[0:15]
	v_mfma_f32_32x32x16_bf16 v[0:15], v[146:149], v[154:157], v[0:15]
	s_waitcnt lgkmcnt(0)
	v_mfma_f32_32x32x16_bf16 v[0:15], v[162:165], v[170:173], v[0:15]
	s_cmp_lt_i32 s3, 6
	s_cbranch_scc1 .LBB0_547
	s_cmp_eq_u32 s3, 6
	s_cselect_b64 s[66:67], -1, 0
	s_cbranch_execz .LBB0_548
	s_branch .LBB0_549

; #define LAS __attribute__((address_space(3)))
; __device__ __forceinline__ float frsq(float x) { return __builtin_amdgcn_rsqf(x); }
; __device__ __forceinline__ unsigned cvtpk(float lo, float hi) { f32x2_t v = {lo, hi}; bf16x2_t b = __builtin_convertvector(v, bf16x2_t); return __builtin_bit_cast(unsigned, b); }
; #define HG_BAR() asm volatile("s_waitcnt lgkmcnt(0)\n\ts_barrier" ::: "memory")
; __device__ __forceinline__ void hgrn_mfma(Frame& F, int b, int h) {
;     ...
;         auto hgrn_finalize = [&](int cc, int tb2) __attribute__((always_inline)) {
;             const int vb = w - 4; const size_t row0 = rbase + 64 * cc;
;             bf16_t* mxb = MIX + row0 * 1024 + colh + 32 * vb;
;             const LAS float* rq = rowsq + (cc & 1) * 256; const LAS unsigned char* sb_ = stg + (cc & 1) * 20480 + tb2 * 2560;
; #pragma unroll
;             for (int j = 0; j < 2; ++j) { const int idx = lane + 64 * j, row = idx >> 2, c8 = idx & 3, t = 32 * tb2 + row;
;                 const u32x4 sg = sgp[tb2][j];
;                 const float rstd = frsq(((rq[t] + rq[64 + t]) + (rq[128 + t] + rq[192 + t])) * (1.0f / 128.0f) + EPS);
;                 const u32x4 a = *(const LAS u32x4*)(sb_ + row * 80 + c8 * 16);
;                 u32x4 ov; ov.x = cvtpk(bflo(a.x) * rstd * bflo(sg.x), bfhi(a.x) * rstd * bfhi(sg.x)); ov.y = cvtpk(bflo(a.y) * rstd * bflo(sg.y), bfhi(a.y) * rstd * bfhi(sg.y));
;                 ov.z = cvtpk(bflo(a.z) * rstd * bflo(sg.z), bfhi(a.z) * rstd * bfhi(sg.z)); ov.w = cvtpk(bflo(a.w) * rstd * bflo(sg.w), bfhi(a.w) * rstd * bfhi(sg.w));
;                 *(u32x4*)(mxb + (unsigned)(t * 1024 + 8 * c8)) = ov; }
;         };
;     ...
;             if (c > 0) hgrn_finalize(c - 1, 1);
;             hgrn_sgload(c, 1);
;             HG_BAR();
.LBB0_556:
	ds_read2_b32 v[0:1], v139 offset0:32 offset1:96
	ds_read2_b32 v[2:3], v139 offset0:160 offset1:224
	s_waitcnt vmcnt(17)
	v_lshlrev_b32_e32 v8, 16, v28
	v_and_b32_e32 v9, 0xffff0000, v28
	s_add_i32 s71, s71, 64
	s_waitcnt lgkmcnt(1)
	v_mov_b32_e32 v4, v0
	s_waitcnt lgkmcnt(0)
	v_mov_b32_e32 v5, v2
	v_mov_b32_e32 v2, v1
	v_pk_add_f32 v[0:1], v[4:5], v[2:3]
	v_lshl_add_u64 v[96:97], v[96:97], 0, s[54:55]
	v_add_f32_e32 v0, v0, v1
	v_fmamk_f32 v0, v0, 0x3c000000, v89
	v_rsq_f32_e32 v4, v0
	ds_read_b128 v[0:3], v138 offset:2560
	v_lshl_add_u64 v[98:99], v[98:99], 0, s[54:55]
	v_lshl_add_u64 v[104:105], v[104:105], 0, s[58:59]
	v_lshl_add_u64 v[106:107], v[106:107], 0, s[58:59]
	s_cmp_eq_u32 s72, 31
	s_waitcnt lgkmcnt(0)
	v_lshlrev_b32_e32 v6, 16, v0
	v_and_b32_e32 v7, 0xffff0000, v0
	v_pk_mul_f32 v[6:7], v[4:5], v[6:7] op_sel_hi:[0,1]
	v_pk_mul_f32 v[6:7], v[6:7], v[8:9]
	v_lshlrev_b32_e32 v8, 16, v29
	v_cvt_pk_bf16_f32 v0, v6, v7
	v_lshlrev_b32_e32 v6, 16, v1
	v_and_b32_e32 v7, 0xffff0000, v1
	v_pk_mul_f32 v[6:7], v[4:5], v[6:7] op_sel_hi:[0,1]
	v_and_b32_e32 v9, 0xffff0000, v29
	v_pk_mul_f32 v[6:7], v[6:7], v[8:9]
	v_lshlrev_b32_e32 v8, 16, v30
	v_cvt_pk_bf16_f32 v1, v6, v7
	v_lshlrev_b32_e32 v6, 16, v2
	v_and_b32_e32 v7, 0xffff0000, v2
	v_pk_mul_f32 v[6:7], v[4:5], v[6:7] op_sel_hi:[0,1]
	v_and_b32_e32 v9, 0xffff0000, v30
	v_pk_mul_f32 v[6:7], v[6:7], v[8:9]
	s_waitcnt vmcnt(16)
	v_lshlrev_b32_e32 v8, 16, v24
	v_cvt_pk_bf16_f32 v2, v6, v7
	v_lshlrev_b32_e32 v6, 16, v3
	v_and_b32_e32 v7, 0xffff0000, v3
	v_pk_mul_f32 v[4:5], v[4:5], v[6:7] op_sel_hi:[0,1]
	v_lshlrev_b32_e32 v6, 16, v31
	v_and_b32_e32 v7, 0xffff0000, v31
	v_pk_mul_f32 v[4:5], v[4:5], v[6:7]
	v_and_b32_e32 v9, 0xffff0000, v24
	v_cvt_pk_bf16_f32 v3, v4, v5
	v_lshl_add_u64 v[4:5], v[92:93], 0, s[42:43]
	global_store_dwordx4 v[4:5], v[0:3], off sc1
	ds_read2_b32 v[0:1], v140 offset0:32 offset1:96
	ds_read2_b32 v[2:3], v140 offset0:160 offset1:224
	v_lshl_add_u64 v[92:93], v[92:93], 0, s[54:55]
	s_waitcnt lgkmcnt(1)
	v_mov_b32_e32 v4, v0
	s_waitcnt lgkmcnt(0)
	v_mov_b32_e32 v5, v2
	v_mov_b32_e32 v2, v1
	v_pk_add_f32 v[0:1], v[4:5], v[2:3]
	ds_read_b128 v[2:5], v91 offset:2560
	v_add_f32_e32 v0, v0, v1
	v_fmamk_f32 v0, v0, 0x3c000000, v89
	v_rsq_f32_e32 v0, v0
	s_waitcnt lgkmcnt(0)
	v_lshlrev_b32_e32 v6, 16, v2
	v_and_b32_e32 v7, 0xffff0000, v2
	v_pk_mul_f32 v[6:7], v[0:1], v[6:7] op_sel_hi:[0,1]
	v_pk_mul_f32 v[6:7], v[6:7], v[8:9]
	v_lshlrev_b32_e32 v8, 16, v25
	v_cvt_pk_bf16_f32 v2, v6, v7
	v_lshlrev_b32_e32 v6, 16, v3
	v_and_b32_e32 v7, 0xffff0000, v3
	v_pk_mul_f32 v[6:7], v[0:1], v[6:7] op_sel_hi:[0,1]
	v_and_b32_e32 v9, 0xffff0000, v25
	v_pk_mul_f32 v[6:7], v[6:7], v[8:9]
	v_lshlrev_b32_e32 v8, 16, v26
	v_cvt_pk_bf16_f32 v3, v6, v7
	v_lshlrev_b32_e32 v6, 16, v4
	v_and_b32_e32 v7, 0xffff0000, v4
	v_pk_mul_f32 v[6:7], v[0:1], v[6:7] op_sel_hi:[0,1]
	v_and_b32_e32 v9, 0xffff0000, v26
	v_pk_mul_f32 v[6:7], v[6:7], v[8:9]
	s_nop 0
	v_cvt_pk_bf16_f32 v4, v6, v7
	v_lshlrev_b32_e32 v6, 16, v5
	v_and_b32_e32 v7, 0xffff0000, v5
	v_pk_mul_f32 v[0:1], v[0:1], v[6:7] op_sel_hi:[0,1]
	v_lshlrev_b32_e32 v6, 16, v27
	v_and_b32_e32 v7, 0xffff0000, v27
	v_pk_mul_f32 v[0:1], v[0:1], v[6:7]
	s_nop 0
	v_cvt_pk_bf16_f32 v5, v0, v1
	v_lshl_add_u64 v[0:1], v[94:95], 0, s[42:43]
	global_store_dwordx4 v[0:1], v[2:5], off sc1
	v_lshl_add_u64 v[0:1], v[102:103], 0, s[42:43]
	global_load_dwordx4 v[28:31], v[0:1], off
	v_lshl_add_u64 v[0:1], v[100:101], 0, s[42:43]
	global_load_dwordx4 v[24:27], v[0:1], off
	s_waitcnt lgkmcnt(0)
	s_barrier
	v_lshl_add_u64 v[94:95], v[94:95], 0, s[54:55]
	v_lshl_add_u64 v[100:101], v[100:101], 0, s[58:59]
	v_lshl_add_u64 v[102:103], v[102:103], 0, s[58:59]
	s_cbranch_scc1 .LBB0_558
	s_mov_b32 s73, s72
	s_branch .LBB0_542
; #define LAS __attribute__((address_space(3)))
; __device__ __forceinline__ float frsq(float x) { return __builtin_amdgcn_rsqf(x); }
; __device__ __forceinline__ unsigned cvtpk(float lo, float hi) { f32x2_t v = {lo, hi}; bf16x2_t b = __builtin_convertvector(v, bf16x2_t); return __builtin_bit_cast(unsigned, b); }
; __device__ __forceinline__ void hgrn_mfma(Frame& F, int b, int h) {
;     ...
;         auto hgrn_finalize = [&](int cc, int tb2) __attribute__((always_inline)) {
;             const int vb = w - 4; const size_t row0 = rbase + 64 * cc;
;             bf16_t* mxb = MIX + row0 * 1024 + colh + 32 * vb;
;             const LAS float* rq = rowsq + (cc & 1) * 256; const LAS unsigned char* sb_ = stg + (cc & 1) * 20480 + tb2 * 2560;
; #pragma unroll
;             for (int j = 0; j < 2; ++j) { const int idx = lane + 64 * j, row = idx >> 2, c8 = idx & 3, t = 32 * tb2 + row;
;                 const u32x4 sg = sgp[tb2][j];
;                 const float rstd = frsq(((rq[t] + rq[64 + t]) + (rq[128 + t] + rq[192 + t])) * (1.0f / 128.0f) + EPS);
;                 const u32x4 a = *(const LAS u32x4*)(sb_ + row * 80 + c8 * 16);
;                 u32x4 ov; ov.x = cvtpk(bflo(a.x) * rstd * bflo(sg.x), bfhi(a.x) * rstd * bfhi(sg.x)); ov.y = cvtpk(bflo(a.y) * rstd * bflo(sg.y), bfhi(a.y) * rstd * bfhi(sg.y));
;                 ov.z = cvtpk(bflo(a.z) * rstd * bflo(sg.z), bfhi(a.z) * rstd * bfhi(sg.z)); ov.w = cvtpk(bflo(a.w) * rstd * bflo(sg.w), bfhi(a.w) * rstd * bfhi(sg.w));
;                 *(u32x4*)(mxb + (unsigned)(t * 1024 + 8 * c8)) = ov; }
;         };
;     ...
;         hgrn_finalize(31, 0); hgrn_finalize(31, 1);
.LBB0_558:
	s_add_u32 s4, s92, s52
	s_addc_u32 s5, s93, s53
	s_add_u32 s4, s4, s40
	s_addc_u32 s5, s5, 0
	s_lshl_b32 s6, s65, 1
	s_add_u32 s4, s4, s6
	s_addc_u32 s5, s5, 0
	s_add_u32 s4, s4, 0xb3e0000
	s_addc_u32 s5, s5, 0
	s_add_i32 s6, 0, 0x19c00
	v_lshl_add_u32 v1, v136, 2, s6
	ds_read2_b32 v[4:5], v1 offset1:32
	ds_read2_b32 v[6:7], v1 offset0:128 offset1:160
	ds_read2_b32 v[8:9], v1 offset0:64 offset1:96
	ds_read2_b32 v[10:11], v1 offset0:192 offset1:224
	s_waitcnt vmcnt(15)
	v_mov_b32_e32 v48, 0x358637bd
	s_waitcnt lgkmcnt(3)
	v_mov_b32_e32 v12, v4
	s_waitcnt lgkmcnt(2)
	v_mov_b32_e32 v13, v6
	s_waitcnt lgkmcnt(1)
	v_mov_b32_e32 v14, v8
	s_waitcnt lgkmcnt(0)
	v_mov_b32_e32 v15, v10
	v_pk_add_f32 v[12:13], v[12:13], v[14:15]
	v_add3_u32 v6, s41, v135, v124
	v_add_f32_e32 v4, v12, v13
	ds_read_b128 v[12:15], v6 offset:20480
	ds_read_b128 v[32:35], v6 offset:23040
	v_fmamk_f32 v4, v4, 0x3c000000, v48
	v_rsq_f32_e32 v4, v4
	s_waitcnt vmcnt(5)
	v_lshlrev_b32_e32 v38, 16, v20
	s_waitcnt lgkmcnt(1)
	v_lshlrev_b32_e32 v36, 16, v12
	v_and_b32_e32 v37, 0xffff0000, v12
	v_pk_mul_f32 v[36:37], v[4:5], v[36:37] op_sel_hi:[0,1]
	v_and_b32_e32 v39, 0xffff0000, v20
	v_pk_mul_f32 v[36:37], v[36:37], v[38:39]
	v_lshlrev_b32_e32 v20, 16, v21
	v_cvt_pk_bf16_f32 v12, v36, v37
	v_lshlrev_b32_e32 v36, 16, v13
	v_and_b32_e32 v37, 0xffff0000, v13
	v_pk_mul_f32 v[36:37], v[4:5], v[36:37] op_sel_hi:[0,1]
	v_and_b32_e32 v21, 0xffff0000, v21
	v_pk_mul_f32 v[20:21], v[36:37], v[20:21]
	v_lshlrev_b32_e32 v36, 16, v22
	v_cvt_pk_bf16_f32 v13, v20, v21
	v_lshlrev_b32_e32 v20, 16, v14
	v_and_b32_e32 v21, 0xffff0000, v14
	v_pk_mul_f32 v[20:21], v[4:5], v[20:21] op_sel_hi:[0,1]
	v_and_b32_e32 v37, 0xffff0000, v22
	v_pk_mul_f32 v[20:21], v[20:21], v[36:37]
	v_lshlrev_b32_e32 v22, 16, v23
	v_cvt_pk_bf16_f32 v14, v20, v21
	v_lshlrev_b32_e32 v20, 16, v15
	v_and_b32_e32 v21, 0xffff0000, v15
	v_pk_mul_f32 v[20:21], v[4:5], v[20:21] op_sel_hi:[0,1]
	v_lshl_add_u32 v4, v126, 2, s6
	ds_read2_b32 v[36:37], v4 offset1:32
	ds_read2_b32 v[38:39], v4 offset0:128 offset1:160
	ds_read2_b32 v[40:41], v4 offset0:64 offset1:96
	ds_read2_b32 v[42:43], v4 offset0:192 offset1:224
	v_and_b32_e32 v23, 0xffff0000, v23
	v_mov_b32_e32 v91, 0
	v_pk_mul_f32 v[20:21], v[20:21], v[22:23]
	v_add3_u32 v6, s41, v125, v124
	v_cvt_pk_bf16_f32 v15, v20, v21
	v_lshl_add_u64 v[20:21], v[90:91], 1, s[4:5]
	global_store_dwordx4 v[20:21], v[12:15], off offset:-256 sc1
	s_waitcnt vmcnt(5)
	v_lshlrev_b32_e32 v46, 16, v16
	v_and_b32_e32 v47, 0xffff0000, v16
	s_waitcnt lgkmcnt(3)
	v_mov_b32_e32 v12, v36
	s_waitcnt lgkmcnt(2)
	v_mov_b32_e32 v13, v38
	s_waitcnt lgkmcnt(1)
	v_mov_b32_e32 v14, v40
	s_waitcnt lgkmcnt(0)
	v_mov_b32_e32 v15, v42
	v_pk_add_f32 v[20:21], v[12:13], v[14:15]
	ds_read_b128 v[12:15], v6 offset:20480
	v_add_f32_e32 v4, v20, v21
	v_fmamk_f32 v4, v4, 0x3c000000, v48
	v_rsq_f32_e32 v4, v4
	ds_read_b128 v[20:23], v6 offset:23040
	s_waitcnt lgkmcnt(1)
	v_lshlrev_b32_e32 v44, 16, v12
	v_and_b32_e32 v45, 0xffff0000, v12
	v_pk_mul_f32 v[44:45], v[4:5], v[44:45] op_sel_hi:[0,1]
	v_pk_mul_f32 v[44:45], v[44:45], v[46:47]
	v_lshlrev_b32_e32 v16, 16, v17
	v_cvt_pk_bf16_f32 v12, v44, v45
	v_lshlrev_b32_e32 v44, 16, v13
	v_and_b32_e32 v45, 0xffff0000, v13
	v_pk_mul_f32 v[44:45], v[4:5], v[44:45] op_sel_hi:[0,1]
	v_and_b32_e32 v17, 0xffff0000, v17
	v_pk_mul_f32 v[16:17], v[44:45], v[16:17]
	v_lshlrev_b32_e32 v44, 16, v18
	v_cvt_pk_bf16_f32 v13, v16, v17
	v_lshlrev_b32_e32 v16, 16, v14
	v_and_b32_e32 v17, 0xffff0000, v14
	v_pk_mul_f32 v[16:17], v[4:5], v[16:17] op_sel_hi:[0,1]
	v_and_b32_e32 v45, 0xffff0000, v18
	v_pk_mul_f32 v[16:17], v[16:17], v[44:45]
	v_mov_b32_e32 v6, v5
	v_cvt_pk_bf16_f32 v14, v16, v17
	v_lshlrev_b32_e32 v16, 16, v15
	v_and_b32_e32 v17, 0xffff0000, v15
	v_mov_b32_e32 v10, v9
	v_pk_mul_f32 v[16:17], v[4:5], v[16:17] op_sel_hi:[0,1]
	v_pk_add_f32 v[4:5], v[6:7], v[10:11]
	s_waitcnt vmcnt(2)
	v_lshlrev_b32_e32 v6, 16, v28
	v_add_f32_e32 v4, v4, v5
	v_fmamk_f32 v4, v4, 0x3c000000, v48
	v_rsq_f32_e32 v8, v4
	v_lshlrev_b32_e32 v4, 16, v32
	v_and_b32_e32 v5, 0xffff0000, v32
	v_and_b32_e32 v7, 0xffff0000, v28
	v_pk_mul_f32 v[4:5], v[8:9], v[4:5] op_sel_hi:[0,1]
	v_pk_mul_f32 v[4:5], v[4:5], v[6:7]
	v_lshlrev_b32_e32 v6, 16, v33
	v_and_b32_e32 v7, 0xffff0000, v33
	v_pk_mul_f32 v[6:7], v[8:9], v[6:7] op_sel_hi:[0,1]
	v_lshlrev_b32_e32 v10, 16, v29
	v_and_b32_e32 v11, 0xffff0000, v29
	v_pk_mul_f32 v[6:7], v[6:7], v[10:11]
	v_cvt_pk_bf16_f32 v4, v4, v5
	v_cvt_pk_bf16_f32 v5, v6, v7
	v_lshlrev_b32_e32 v6, 16, v34
	v_and_b32_e32 v7, 0xffff0000, v34
	v_pk_mul_f32 v[6:7], v[8:9], v[6:7] op_sel_hi:[0,1]
	v_lshlrev_b32_e32 v10, 16, v30
	v_and_b32_e32 v11, 0xffff0000, v30
	v_pk_mul_f32 v[6:7], v[6:7], v[10:11]
	v_lshlrev_b32_e32 v10, 16, v35
	v_and_b32_e32 v11, 0xffff0000, v35
	v_pk_mul_f32 v[8:9], v[8:9], v[10:11] op_sel_hi:[0,1]
	v_lshlrev_b32_e32 v10, 16, v31
	v_and_b32_e32 v11, 0xffff0000, v31
	v_pk_mul_f32 v[8:9], v[8:9], v[10:11]
	v_mov_b32_e32 v38, v37
	v_mov_b32_e32 v42, v41
	v_cvt_pk_bf16_f32 v6, v6, v7
	v_cvt_pk_bf16_f32 v7, v8, v9
	v_pk_add_f32 v[8:9], v[38:39], v[42:43]
	v_lshl_or_b32 v0, v136, 10, v137
	v_add_f32_e32 v8, v8, v9
	v_fmac_f32_e32 v48, 0x3c000000, v8
	v_lshlrev_b32_e32 v18, 16, v19
	v_and_b32_e32 v19, 0xffff0000, v19
	v_rsq_f32_e32 v8, v48
	v_mov_b32_e32 v89, v91
	v_add_u32_e32 v2, 0x8000, v0
	v_mov_b32_e32 v3, v91
	v_pk_mul_f32 v[16:17], v[16:17], v[18:19]
	v_lshl_add_u64 v[2:3], v[2:3], 1, s[4:5]
	v_cvt_pk_bf16_f32 v15, v16, v17
	v_lshl_add_u64 v[16:17], v[88:89], 1, s[4:5]
	global_store_dwordx4 v[16:17], v[12:15], off offset:-256 sc1
	global_store_dwordx4 v[2:3], v[4:7], off offset:-256 sc1
	s_waitcnt lgkmcnt(0)
	v_lshlrev_b32_e32 v2, 16, v20
	v_and_b32_e32 v3, 0xffff0000, v20
	v_pk_mul_f32 v[2:3], v[8:9], v[2:3] op_sel_hi:[0,1]
	s_waitcnt vmcnt(3)
	v_lshlrev_b32_e32 v4, 16, v24
	v_and_b32_e32 v5, 0xffff0000, v24
	v_pk_mul_f32 v[2:3], v[2:3], v[4:5]
	v_lshlrev_b32_e32 v4, 16, v21
	v_and_b32_e32 v5, 0xffff0000, v21
	v_pk_mul_f32 v[4:5], v[8:9], v[4:5] op_sel_hi:[0,1]
	v_lshlrev_b32_e32 v6, 16, v25
	v_and_b32_e32 v7, 0xffff0000, v25
	v_pk_mul_f32 v[4:5], v[4:5], v[6:7]
	v_cvt_pk_bf16_f32 v2, v2, v3
	v_cvt_pk_bf16_f32 v3, v4, v5
	v_lshlrev_b32_e32 v4, 16, v22
	v_and_b32_e32 v5, 0xffff0000, v22
	v_pk_mul_f32 v[4:5], v[8:9], v[4:5] op_sel_hi:[0,1]
	v_lshlrev_b32_e32 v6, 16, v26
	v_and_b32_e32 v7, 0xffff0000, v26
	v_pk_mul_f32 v[4:5], v[4:5], v[6:7]
	v_lshlrev_b32_e32 v6, 16, v23
	v_and_b32_e32 v7, 0xffff0000, v23
	v_lshl_or_b32 v0, v126, 10, v137
	v_pk_mul_f32 v[6:7], v[8:9], v[6:7] op_sel_hi:[0,1]
	v_lshlrev_b32_e32 v8, 16, v27
	v_and_b32_e32 v9, 0xffff0000, v27
	v_add_u32_e32 v0, 0x8000, v0
	v_mov_b32_e32 v1, v91
	v_pk_mul_f32 v[6:7], v[6:7], v[8:9]
	v_cvt_pk_bf16_f32 v4, v4, v5
	v_cvt_pk_bf16_f32 v5, v6, v7
	v_lshl_add_u64 v[0:1], v[0:1], 1, s[4:5]
	s_mov_b64 s[4:5], 0
	global_store_dwordx4 v[0:1], v[2:5], off offset:-256 sc1

; #define LAS __attribute__((address_space(3)))
; __device__ __forceinline__ float frcp(float x) { return __builtin_amdgcn_rcpf(x); }
; #define MFMA32(a, b, c) __builtin_amdgcn_mfma_f32_32x32x16_bf16((a), (b), (c), 0, 0, 0)
; __device__ __forceinline__ s16x4 ds_tr(const LAS unsigned char* p) { return __builtin_bit_cast(s16x4, __builtin_amdgcn_ds_read_tr16_b64_v4i16((LAS v4i16_t*)p)); }
; __device__ __forceinline__ void swa_compute(Frame& F, int u) {
;     ...
;         for (int j = 0; j < 5; ++j) {
;             const int kt = a + j;
;             if (n == 0 && kt < 4) continue;
;             const LAS unsigned char* Kt = Kimg + kt * 4096; const LAS unsigned char* Vt = Vimg + kt * 4096;
;             f32x16 acc;
; #pragma unroll
;             for (int r = 0; r < 16; ++r) acc[r] = -C2;
; #pragma unroll
;             for (int ks = 0; ks < 4; ++ks) { const bf16x8 kf = *(const LAS bf16x8*)(Kt + ((ks & 1) ? kbo : kbe) + 512 * (ks >> 1)); acc = MFMA32(kf, qf[ks], acc); }
; #pragma unroll
;             for (int r = 0; r < 16; ++r) { const int kl = (r & 3) + 8 * (r >> 2) + 4 * hi;
;                 const bool valid = (j == 0) ? (r32 < kl) : ((j == 4) ? (kl <= r32) : true);
;                 const float p = valid ? __builtin_amdgcn_exp2f(acc[r]) : 0.f; acc[r] = p; lsum += p; }
;             const bf16x8 pa0 = pack_step(acc, 0), pa1 = pack_step(acc, 1);
; #pragma unroll
;             for (int s = 0; s < 2; ++s)
; #pragma unroll
;                 for (int c = 0; c < 2; ++c) { const bf16x8 vf = cat8(ds_tr(Vt + s * 2048 + c * 512 + vb0), ds_tr(Vt + s * 2048 + c * 512 + vb1)); o[c] = MFMA32(vf, s ? pa1 : pa0, o[c]); }
;         }
;         lsum += __shfl_xor(lsum, 32);
;         const float inv = frcp(lsum + __builtin_amdgcn_exp2f(sinkv * 1.4426950408889634f - C2));
; #pragma unroll
;         for (int c = 0; c < 2; ++c)
; #pragma unroll
;             for (int g = 0; g < 4; ++g) { u32x2 w; w.x = cvtpk(o[c][4 * g] * inv, o[c][4 * g + 1] * inv); w.y = cvtpk(o[c][4 * g + 2] * inv, o[c][4 * g + 3] * inv);
;                 *(LAS u32x2*)(stg + r32 * 144 + (32 * c + 8 * g + 4 * hi) * 2) = w; }
; #pragma unroll
;         for (int jj = 0; jj < 4; ++jj) { const int idx = lane + 64 * jj, row = idx >> 3, c8 = idx & 7;
;             const u32x4 v = *(const LAS u32x4*)(stg + row * 144 + 16 * c8);
;             *(u32x4*)(MIX + (size_t)(R0 + row) * 1024 + 512 + hq * 64 + 8 * c8) = v; }
.LBB0_596:
	v_add_u32_e32 v9, s60, v168
	v_add_u32_e32 v48, v9, v171
	ds_read_b128 v[10:13], v48
	v_add_u32_e32 v9, v9, v172
	s_mov_b32 s61, 0x3fb8aa3b
	v_fma_f32 v0, v173, s61, -v174
	v_exp_f32_e32 v175, v0
	v_mov_b32_e32 v0, s49
	v_mad_u32_u24 v7, v167, s68, v0
	v_and_b32_e32 v176, 7, v152
	v_ashrrev_i32_e32 v174, 3, v152
	s_waitcnt vmcnt(3) lgkmcnt(0)
	v_mfma_f32_32x32x16_bf16 v[32:47], v[10:13], v[140:143], v[16:31]
	ds_read_b128 v[10:13], v9
	v_lshlrev_b32_e32 v0, 4, v176
	v_add_u32_e32 v2, s49, v0
	v_mul_lo_u32 v6, v174, s68
	s_lshl_b32 s52, s52, 1
	v_add_u32_e32 v3, 64, v152
	v_ashrrev_i32_e32 v173, 3, v3
	v_mul_lo_u32 v5, v173, s68
	s_waitcnt vmcnt(2) lgkmcnt(0)
	v_mfma_f32_32x32x16_bf16 v[32:47], v[10:13], v[136:139], v[32:47]
	ds_read_b128 v[10:13], v48 offset:512
	v_add_u32_e32 v3, 0x80, v152
	v_ashrrev_i32_e32 v15, 3, v3
	v_mul_lo_u32 v4, v15, s68
	v_add_u32_e32 v3, 0xc0, v152
	v_ashrrev_i32_e32 v14, 3, v3
	v_mul_lo_u32 v3, v14, s68
	s_waitcnt vmcnt(1) lgkmcnt(0)
	v_mfma_f32_32x32x16_bf16 v[32:47], v[10:13], v[132:135], v[32:47]
	ds_read_b128 v[10:13], v9 offset:512
	v_add_u32_e32 v132, v7, v150
	v_add_u32_e32 v133, v2, v6
	v_add_u32_e32 v134, v2, v5
	v_add_u32_e32 v135, v2, v4
	v_add_u32_e32 v136, v2, v3
	s_waitcnt vmcnt(0) lgkmcnt(0)
	v_mfma_f32_32x32x16_bf16 v[32:47], v[10:13], v[128:131], v[32:47]
	s_nop 11
	v_exp_f32_e32 v9, v32
	v_exp_f32_e32 v10, v33
	v_exp_f32_e32 v11, v34
	v_exp_f32_e32 v12, v35
	v_cndmask_b32_e64 v9, v9, 0, s[42:43]
	v_exp_f32_e32 v13, v36
	v_add_f32_e32 v8, v8, v9
	v_cndmask_b32_e64 v10, 0, v10, s[40:41]
	v_exp_f32_e32 v32, v37
	v_add_f32_e32 v8, v10, v8
	v_cndmask_b32_e64 v11, v11, 0, s[36:37]
	v_exp_f32_e32 v33, v38
	v_add_f32_e32 v8, v11, v8
	v_cndmask_b32_e64 v12, v12, 0, s[38:39]
	v_exp_f32_e32 v34, v39
	v_add_f32_e32 v8, v12, v8
	v_cndmask_b32_e64 v13, v13, 0, s[30:31]
	v_exp_f32_e32 v35, v40
	v_add_f32_e32 v8, v13, v8
	v_cndmask_b32_e64 v32, v32, 0, s[34:35]
	v_exp_f32_e32 v36, v41
	v_add_f32_e32 v8, v32, v8
	v_cndmask_b32_e64 v33, v33, 0, s[28:29]
	v_exp_f32_e32 v37, v42
	v_add_f32_e32 v8, v33, v8
	v_cndmask_b32_e64 v34, v34, 0, s[24:25]
	v_exp_f32_e32 v38, v43
	v_add_f32_e32 v8, v34, v8
	v_cndmask_b32_e64 v35, v35, 0, s[26:27]
	v_exp_f32_e32 v39, v44
	v_add_f32_e32 v8, v35, v8
	v_cndmask_b32_e64 v36, v36, 0, s[22:23]
	v_exp_f32_e32 v40, v45
	v_add_f32_e32 v8, v36, v8
	v_cndmask_b32_e64 v37, v37, 0, s[18:19]
	v_exp_f32_e32 v41, v46
	v_add_f32_e32 v8, v37, v8
	v_cndmask_b32_e64 v38, v38, 0, s[20:21]
	v_add_f32_e32 v8, v38, v8
	v_cndmask_b32_e64 v39, v39, 0, s[14:15]
	v_add_f32_e32 v8, v39, v8
	v_cndmask_b32_e64 v40, v40, 0, s[16:17]
	v_add_f32_e32 v8, v40, v8
	v_cndmask_b32_e64 v41, v41, 0, s[10:11]
	v_add_f32_e32 v42, v41, v8
	v_exp_f32_e32 v8, v47
	s_nop 0
	v_cndmask_b32_e64 v43, v8, 0, s[12:13]
	v_cvt_pk_bf16_f32 v8, v9, v10
	v_cvt_pk_bf16_f32 v9, v11, v12
	v_add_u32_e32 v12, s60, v170
	v_cvt_pk_bf16_f32 v10, v13, v32
	v_add_u32_e32 v13, v12, v151
	v_add_u32_e32 v12, v12, v169
	v_cvt_pk_bf16_f32 v11, v33, v34
	v_cvt_pk_bf16_f32 v32, v35, v36
	v_cvt_pk_bf16_f32 v33, v37, v38
	v_cvt_pk_bf16_f32 v34, v39, v40
	ds_read_b64_tr_b16 v[36:37], v13 offset:32768
	ds_read_b64_tr_b16 v[38:39], v12 offset:33792
	s_waitcnt lgkmcnt(0)
	v_mfma_f32_32x32x16_bf16 v[80:95], v[36:39], v[8:11], v[80:95]
	ds_read_b64_tr_b16 v[36:37], v13 offset:33280
	ds_read_b64_tr_b16 v[38:39], v12 offset:34304
	v_cvt_pk_bf16_f32 v35, v41, v43
	s_or_b32 s60, s63, s71
	s_waitcnt lgkmcnt(0)
	v_mfma_f32_32x32x16_bf16 v[64:79], v[36:39], v[8:11], v[64:79]
	ds_read_b64_tr_b16 v[8:9], v13 offset:34816
	ds_read_b64_tr_b16 v[10:11], v12 offset:35840
	s_waitcnt lgkmcnt(0)
	v_mfma_f32_32x32x16_bf16 v[80:95], v[8:11], v[32:35], v[80:95]
	ds_read_b64_tr_b16 v[8:9], v13 offset:35328
	ds_read_b64_tr_b16 v[10:11], v12 offset:36352
	s_waitcnt lgkmcnt(0)
	v_mfma_f32_32x32x16_bf16 v[64:79], v[8:11], v[32:35], v[64:79]
	v_add_f32_e32 v8, v43, v42
	ds_bpermute_b32 v9, v153, v8
	s_waitcnt lgkmcnt(0)
	v_add_f32_e32 v8, v8, v9
	v_add_f32_e32 v8, v175, v8
	v_rcp_f32_e32 v8, v8
	s_nop 1
	v_pk_mul_f32 v[10:11], v[80:81], v[8:9] op_sel_hi:[1,0]
	v_pk_mul_f32 v[12:13], v[82:83], v[8:9] op_sel_hi:[1,0]
	v_cvt_pk_bf16_f32 v10, v10, v11
	v_cvt_pk_bf16_f32 v11, v12, v13
	v_pk_mul_f32 v[12:13], v[84:85], v[8:9] op_sel_hi:[1,0]
	v_pk_mul_f32 v[32:33], v[86:87], v[8:9] op_sel_hi:[1,0]
	v_cvt_pk_bf16_f32 v12, v12, v13
	v_cvt_pk_bf16_f32 v13, v32, v33
	ds_write2_b64 v132, v[10:11], v[12:13] offset1:2
	v_pk_mul_f32 v[10:11], v[88:89], v[8:9] op_sel_hi:[1,0]
	v_pk_mul_f32 v[12:13], v[90:91], v[8:9] op_sel_hi:[1,0]
	v_cvt_pk_bf16_f32 v10, v10, v11
	v_cvt_pk_bf16_f32 v11, v12, v13
	v_pk_mul_f32 v[12:13], v[92:93], v[8:9] op_sel_hi:[1,0]
	v_pk_mul_f32 v[32:33], v[94:95], v[8:9] op_sel_hi:[1,0]
	v_cvt_pk_bf16_f32 v12, v12, v13
	v_cvt_pk_bf16_f32 v13, v32, v33
	ds_write2_b64 v132, v[10:11], v[12:13] offset0:4 offset1:6
	v_pk_mul_f32 v[10:11], v[64:65], v[8:9] op_sel_hi:[1,0]
	v_pk_mul_f32 v[12:13], v[66:67], v[8:9] op_sel_hi:[1,0]
	v_cvt_pk_bf16_f32 v10, v10, v11
	v_cvt_pk_bf16_f32 v11, v12, v13
	v_pk_mul_f32 v[12:13], v[68:69], v[8:9] op_sel_hi:[1,0]
	v_pk_mul_f32 v[32:33], v[70:71], v[8:9] op_sel_hi:[1,0]
	v_cvt_pk_bf16_f32 v12, v12, v13
	v_cvt_pk_bf16_f32 v13, v32, v33
	ds_write2_b64 v132, v[10:11], v[12:13] offset0:8 offset1:10
	v_pk_mul_f32 v[10:11], v[72:73], v[8:9] op_sel_hi:[1,0]
	v_pk_mul_f32 v[12:13], v[74:75], v[8:9] op_sel_hi:[1,0]
	v_cvt_pk_bf16_f32 v10, v10, v11
	v_cvt_pk_bf16_f32 v11, v12, v13
	v_pk_mul_f32 v[12:13], v[76:77], v[8:9] op_sel_hi:[1,0]
	v_pk_mul_f32 v[8:9], v[78:79], v[8:9] op_sel_hi:[1,0]
	v_cvt_pk_bf16_f32 v12, v12, v13
	v_cvt_pk_bf16_f32 v13, v8, v9
	ds_write2_b64 v132, v[10:11], v[12:13] offset0:12 offset1:14
	v_add_u32_e32 v10, s72, v174
	v_ashrrev_i32_e32 v11, 31, v10
	v_lshlrev_b64 v[10:11], 11, v[10:11]
	ds_read_b128 v[6:9], v133
	v_lshl_add_u64 v[10:11], s[92:93], 0, v[10:11]
	v_lshl_add_u64 v[10:11], v[10:11], 0, s[52:53]
	v_lshl_add_u64 v[10:11], v[10:11], 0, v[0:1]
	v_add_co_u32_e32 v10, vcc, s69, v10
	v_add_u32_e32 v32, s64, v170
	s_nop 0
	v_addc_co_u32_e32 v11, vcc, 0, v11, vcc
	s_waitcnt lgkmcnt(0)
; #define LAS __attribute__((address_space(3)))
; __device__ __forceinline__ void swa_compute(Frame& F, int u) {
;     ...
;     for (int aa = 0; aa < 2; ++aa) {
;         const int a = (F.wave & 1) * 2 + aa;
;         const int R0 = b * SEQ + n * 128 + 32 * a;
;         const bf16_t* qp = SQ + (size_t)(R0 + r32) * 512 + hq * 64 + 8 * hi;
;         bf16x8 qf[4];
; #pragma unroll
;         for (int ks = 0; ks < 4; ++ks) qf[ks] = *(const bf16x8*)(qp + 16 * ks);
;         f32x16 o[2]; float lsum = 0.f;
; #pragma unroll
;         for (int c = 0; c < 2; ++c)
; #pragma unroll
;             for (int r = 0; r < 16; ++r) o[c][r] = 0.f;
;         for (int j = 0; j < 5; ++j) {
;             const int kt = a + j;
;             if (n == 0 && kt < 4) continue;
;             const LAS unsigned char* Kt = Kimg + kt * 4096; const LAS unsigned char* Vt = Vimg + kt * 4096;
;             f32x16 acc;
; #pragma unroll
;             for (int r = 0; r < 16; ++r) acc[r] = -C2;
; #pragma unroll
;             for (int ks = 0; ks < 4; ++ks) { const bf16x8 kf = *(const LAS bf16x8*)(Kt + ((ks & 1) ? kbo : kbe) + 512 * (ks >> 1)); acc = MFMA32(kf, qf[ks], acc); }
; #pragma unroll
;             for (int r = 0; r < 16; ++r) { const int kl = (r & 3) + 8 * (r >> 2) + 4 * hi;
;                 const bool valid = (j == 0) ? (r32 < kl) : ((j == 4) ? (kl <= r32) : true);
;                 const float p = valid ? __builtin_amdgcn_exp2f(acc[r]) : 0.f; acc[r] = p; lsum += p; }
;             const bf16x8 pa0 = pack_step(acc, 0), pa1 = pack_step(acc, 1);
; #pragma unroll
;             for (int s = 0; s < 2; ++s)
; #pragma unroll
;                 for (int c = 0; c < 2; ++c) { const bf16x8 vf = cat8(ds_tr(Vt + s * 2048 + c * 512 + vb0), ds_tr(Vt + s * 2048 + c * 512 + vb1)); o[c] = MFMA32(vf, s ? pa1 : pa0, o[c]); }
;         }
;         lsum += __shfl_xor(lsum, 32);
;         const float inv = frcp(lsum + __builtin_amdgcn_exp2f(sinkv * 1.4426950408889634f - C2));
; #pragma unroll
;         for (int c = 0; c < 2; ++c)
; #pragma unroll
;             for (int g = 0; g < 4; ++g) { u32x2 w; w.x = cvtpk(o[c][4 * g] * inv, o[c][4 * g + 1] * inv); w.y = cvtpk(o[c][4 * g + 2] * inv, o[c][4 * g + 3] * inv);
;                 *(LAS u32x2*)(stg + r32 * 144 + (32 * c + 8 * g + 4 * hi) * 2) = w; }
; #pragma unroll
;         for (int jj = 0; jj < 4; ++jj) { const int idx = lane + 64 * jj, row = idx >> 3, c8 = idx & 7;
	global_store_dwordx4 v[10:11], v[6:9], off offset:1024 sc1
	v_add_u32_e32 v10, s72, v173
	v_ashrrev_i32_e32 v11, 31, v10
	v_lshlrev_b64 v[10:11], 11, v[10:11]
	ds_read_b128 v[6:9], v134
	v_lshl_add_u64 v[10:11], s[92:93], 0, v[10:11]
	v_lshl_add_u64 v[10:11], v[10:11], 0, s[52:53]
	v_lshl_add_u64 v[10:11], v[10:11], 0, v[0:1]
	v_add_co_u32_e32 v10, vcc, s69, v10
	v_add_u32_e32 v137, v32, v151
	s_nop 0
	v_addc_co_u32_e32 v11, vcc, 0, v11, vcc
	s_waitcnt lgkmcnt(0)
	global_store_dwordx4 v[10:11], v[6:9], off offset:1024 sc1
	ds_read_b128 v[4:7], v135
	s_nop 0
	v_add_u32_e32 v8, s72, v15
	v_ashrrev_i32_e32 v9, 31, v8
	v_lshlrev_b64 v[8:9], 11, v[8:9]
	v_lshl_add_u64 v[8:9], s[92:93], 0, v[8:9]
	v_lshl_add_u64 v[8:9], v[8:9], 0, s[52:53]
	v_lshl_add_u64 v[8:9], v[8:9], 0, v[0:1]
	v_add_co_u32_e32 v8, vcc, s69, v8
	s_nop 1
	v_addc_co_u32_e32 v9, vcc, 0, v9, vcc
	s_waitcnt lgkmcnt(0)
	global_store_dwordx4 v[8:9], v[4:7], off offset:1024 sc1
	ds_read_b128 v[2:5], v136
	s_nop 0
	v_add_u32_e32 v6, s72, v14
	v_ashrrev_i32_e32 v7, 31, v6
	v_lshlrev_b64 v[6:7], 11, v[6:7]
	v_lshl_add_u64 v[6:7], s[92:93], 0, v[6:7]
	v_lshl_add_u64 v[6:7], v[6:7], 0, s[52:53]
	v_lshl_add_u64 v[6:7], v[6:7], 0, v[0:1]
	v_add_co_u32_e32 v6, vcc, 0xb000000, v6
	v_add_u32_e32 v0, s64, v168
	s_nop 0
	v_addc_co_u32_e32 v7, vcc, 0, v7, vcc
	s_waitcnt lgkmcnt(0)
	global_store_dwordx4 v[6:7], v[2:5], off offset:1024 sc1
	s_and_b64 vcc, exec, s[44:45]
	v_add_u32_e32 v139, v0, v171
	v_or_b32_e32 v2, s60, v167
	v_ashrrev_i32_e32 v3, 31, v2
	v_lshlrev_b64 v[2:3], 10, v[2:3]
	v_lshl_add_u64 v[2:3], v[148:149], 0, v[2:3]
	global_load_dwordx4 v[128:131], v[2:3], off
	global_load_dwordx4 v[10:13], v[2:3], off offset:32
	global_load_dwordx4 v[6:9], v[2:3], off offset:64
	s_nop 0
	global_load_dwordx4 v[2:5], v[2:3], off offset:96
	v_add_u32_e32 v138, v0, v172
	v_add_u32_e32 v0, v32, v169
	s_cbranch_vccnz .LBB0_606
	ds_read_b128 v[48:51], v139
	ds_read_b128 v[52:55], v139 offset:512
	s_waitcnt vmcnt(3) lgkmcnt(1)
	v_mfma_f32_32x32x16_bf16 v[32:47], v[48:51], v[128:131], v[16:31]
	ds_read_b128 v[48:51], v138
	ds_read_b128 v[56:59], v138 offset:512
	s_waitcnt vmcnt(2) lgkmcnt(1)
	v_mfma_f32_32x32x16_bf16 v[32:47], v[48:51], v[10:13], v[32:47]
	s_waitcnt vmcnt(1)
	v_mfma_f32_32x32x16_bf16 v[32:47], v[52:55], v[6:9], v[32:47]
	ds_read_b64_tr_b16 v[48:49], v137 offset:32768
	ds_read_b64_tr_b16 v[52:53], v137 offset:33280
	ds_read_b64_tr_b16 v[60:61], v137 offset:34816
	ds_read_b64_tr_b16 v[140:141], v137 offset:35328
	ds_read_b64_tr_b16 v[50:51], v0 offset:33792
	ds_read_b64_tr_b16 v[54:55], v0 offset:34304
	ds_read_b64_tr_b16 v[62:63], v0 offset:35840
	ds_read_b64_tr_b16 v[142:143], v0 offset:36352
	s_waitcnt vmcnt(0) lgkmcnt(8)
	v_mfma_f32_32x32x16_bf16 v[32:47], v[56:59], v[2:5], v[32:47]
	s_nop 11
	v_exp_f32_e32 v32, v32
	v_exp_f32_e32 v33, v33
	v_exp_f32_e32 v34, v34
	v_exp_f32_e32 v35, v35
	v_exp_f32_e32 v36, v36
	v_exp_f32_e32 v37, v37
	v_exp_f32_e32 v38, v38
	v_exp_f32_e32 v39, v39
	v_cndmask_b32_e64 v32, 0, v32, s[42:43]
	v_cndmask_b32_e64 v56, v33, 0, s[40:41]
	v_cndmask_b32_e64 v57, 0, v34, s[36:37]
	v_cndmask_b32_e64 v58, 0, v35, s[38:39]
	v_cndmask_b32_e64 v36, 0, v36, s[30:31]
	v_cndmask_b32_e64 v37, 0, v37, s[34:35]
	v_cndmask_b32_e64 v38, 0, v38, s[28:29]
	v_cndmask_b32_e64 v39, 0, v39, s[24:25]
	v_add_f32_e32 v59, 0, v32
	v_cvt_pk_bf16_f32 v32, v32, v56
	v_cvt_pk_bf16_f32 v33, v57, v58
	v_cvt_pk_bf16_f32 v34, v36, v37
	v_cvt_pk_bf16_f32 v35, v38, v39
	v_add_f32_e32 v56, v56, v59
	v_exp_f32_e32 v44, v44
	s_waitcnt lgkmcnt(3)
	v_mfma_f32_32x32x16_bf16 v[80:95], v[48:51], v[32:35], 0
	v_add_f32_e32 v48, v57, v56
	v_add_f32_e32 v48, v58, v48
	v_add_f32_e32 v36, v36, v48
	v_add_f32_e32 v36, v37, v36
	v_add_f32_e32 v36, v38, v36
	v_exp_f32_e32 v40, v40
	v_exp_f32_e32 v41, v41
	s_waitcnt lgkmcnt(2)
	v_mfma_f32_32x32x16_bf16 v[64:79], v[52:55], v[32:35], 0
	v_exp_f32_e32 v42, v42
	v_exp_f32_e32 v43, v43
	v_add_f32_e32 v36, v39, v36
	v_cndmask_b32_e64 v37, 0, v44, s[14:15]
	v_exp_f32_e32 v38, v45
	v_exp_f32_e32 v39, v46
	v_exp_f32_e32 v44, v47
	v_cndmask_b32_e64 v40, 0, v40, s[26:27]
	v_cndmask_b32_e64 v41, 0, v41, s[22:23]
	v_cndmask_b32_e64 v42, 0, v42, s[18:19]
	v_cndmask_b32_e64 v43, 0, v43, s[20:21]
	v_cndmask_b32_e64 v38, 0, v38, s[16:17]
	v_cndmask_b32_e64 v39, 0, v39, s[10:11]
	v_cndmask_b32_e64 v44, 0, v44, s[12:13]
	v_cvt_pk_bf16_f32 v32, v40, v41
	v_cvt_pk_bf16_f32 v33, v42, v43
	v_cvt_pk_bf16_f32 v34, v37, v38
	v_cvt_pk_bf16_f32 v35, v39, v44
	v_add_f32_e32 v36, v40, v36
	v_add_f32_e32 v36, v41, v36
	s_waitcnt lgkmcnt(1)
	v_mfma_f32_32x32x16_bf16 v[80:95], v[60:63], v[32:35], v[80:95]
	v_add_f32_e32 v36, v42, v36
	v_add_f32_e32 v36, v43, v36
	v_add_f32_e32 v36, v37, v36
	v_add_f32_e32 v36, v38, v36
	v_add_f32_e32 v36, v39, v36
	s_waitcnt lgkmcnt(0)
	v_mfma_f32_32x32x16_bf16 v[64:79], v[140:143], v[32:35], v[64:79]
	v_add_f32_e32 v140, v44, v36
	s_andn2_b64 vcc, exec, s[58:59]
	s_cbranch_vccnz .LBB0_599

; #define LAS __attribute__((address_space(3)))
; #define MFMA32(a, b, c) __builtin_amdgcn_mfma_f32_32x32x16_bf16((a), (b), (c), 0, 0, 0)
; __device__ __forceinline__ s16x4 ds_tr(const LAS unsigned char* p) { return __builtin_bit_cast(s16x4, __builtin_amdgcn_ds_read_tr16_b64_v4i16((LAS v4i16_t*)p)); }
; __device__ __forceinline__ bf16x8 cat8(s16x4 lo, s16x4 hi) { return (bf16x8){lo[0], lo[1], lo[2], lo[3], hi[0], hi[1], hi[2], hi[3]}; }
; __device__ __forceinline__ void swa_compute(Frame& F, int u) {
;     ...
;         for (int j = 0; j < 5; ++j) {
;             const int kt = a + j;
;             if (n == 0 && kt < 4) continue;
;             const LAS unsigned char* Kt = Kimg + kt * 4096; const LAS unsigned char* Vt = Vimg + kt * 4096;
;             f32x16 acc;
; #pragma unroll
;             for (int r = 0; r < 16; ++r) acc[r] = -C2;
; #pragma unroll
;             for (int ks = 0; ks < 4; ++ks) { const bf16x8 kf = *(const LAS bf16x8*)(Kt + ((ks & 1) ? kbo : kbe) + 512 * (ks >> 1)); acc = MFMA32(kf, qf[ks], acc); }
; #pragma unroll
;             for (int r = 0; r < 16; ++r) { const int kl = (r & 3) + 8 * (r >> 2) + 4 * hi;
;                 const bool valid = (j == 0) ? (r32 < kl) : ((j == 4) ? (kl <= r32) : true);
;                 const float p = valid ? __builtin_amdgcn_exp2f(acc[r]) : 0.f; acc[r] = p; lsum += p; }
;             const bf16x8 pa0 = pack_step(acc, 0), pa1 = pack_step(acc, 1);
; #pragma unroll
;             for (int s = 0; s < 2; ++s)
; #pragma unroll
;                 for (int c = 0; c < 2; ++c) { const bf16x8 vf = cat8(ds_tr(Vt + s * 2048 + c * 512 + vb0), ds_tr(Vt + s * 2048 + c * 512 + vb1)); o[c] = MFMA32(vf, s ? pa1 : pa0, o[c]); }
.LBB0_602:
	ds_read_b128 v[80:83], v139 offset:12288
	ds_read_b128 v[84:87], v139 offset:12800
	s_waitcnt vmcnt(3) lgkmcnt(1)
	v_mfma_f32_32x32x16_bf16 v[64:79], v[80:83], v[128:131], v[16:31]
	ds_read_b128 v[80:83], v138 offset:12288
	ds_read_b128 v[88:91], v138 offset:12800
	s_waitcnt vmcnt(2) lgkmcnt(1)
	v_mfma_f32_32x32x16_bf16 v[64:79], v[80:83], v[10:13], v[64:79]
	s_waitcnt vmcnt(1)
	v_mfma_f32_32x32x16_bf16 v[64:79], v[84:87], v[6:9], v[64:79]
	ds_read_b128 v[80:83], v139 offset:16384
	ds_read_b128 v[84:87], v139 offset:16896
	s_waitcnt lgkmcnt(1)
	v_mfma_f32_32x32x16_bf16 v[16:31], v[80:83], v[128:131], v[16:31]
	ds_read_b128 v[80:83], v138 offset:16384
	ds_read_b128 v[92:95], v138 offset:16896
	s_waitcnt vmcnt(0)
	v_mfma_f32_32x32x16_bf16 v[64:79], v[88:91], v[2:5], v[64:79]
	s_waitcnt lgkmcnt(1)
	v_mfma_f32_32x32x16_bf16 v[16:31], v[80:83], v[10:13], v[16:31]
	s_nop 9
	v_exp_f32_e32 v64, v64
	v_exp_f32_e32 v88, v65
	v_exp_f32_e32 v89, v66
	v_exp_f32_e32 v90, v67
	v_exp_f32_e32 v91, v68
	v_exp_f32_e32 v131, v76
	v_add_f32_e32 v76, v141, v64
	v_mfma_f32_32x32x16_bf16 v[16:31], v[84:87], v[6:9], v[16:31]
	v_exp_f32_e32 v128, v69
	v_add_f32_e32 v76, v88, v76
	v_exp_f32_e32 v129, v70
	v_add_f32_e32 v10, v89, v76
	v_exp_f32_e32 v130, v71
	v_add_f32_e32 v10, v90, v10
	v_exp_f32_e32 v72, v72
	v_add_f32_e32 v10, v91, v10
	v_exp_f32_e32 v73, v73
	v_add_f32_e32 v10, v128, v10
	v_exp_f32_e32 v74, v74
	v_add_f32_e32 v10, v129, v10
	v_exp_f32_e32 v75, v75
	v_add_f32_e32 v10, v130, v10
	v_add_f32_e32 v10, v72, v10
	s_waitcnt lgkmcnt(0)
	v_mfma_f32_32x32x16_bf16 v[16:31], v[92:95], v[2:5], v[16:31]
	v_exp_f32_e32 v138, v77
	v_add_f32_e32 v12, v73, v10
	v_exp_f32_e32 v78, v78
	v_exp_f32_e32 v139, v79
	v_add_f32_e32 v8, v74, v12
	v_add_f32_e32 v8, v75, v8
	v_add_f32_e32 v8, v131, v8
	v_add_f32_e32 v8, v138, v8
	v_cvt_pk_bf16_f32 v68, v72, v73
	v_cvt_pk_bf16_f32 v69, v74, v75
	v_cvt_pk_bf16_f32 v71, v78, v139
	ds_read_b64_tr_b16 v[6:7], v137 offset:45056
	ds_read_b64_tr_b16 v[10:11], v137 offset:45568
	ds_read_b64_tr_b16 v[72:73], v137 offset:47104
	ds_read_b64_tr_b16 v[76:77], v137 offset:47616
	v_add_f32_e32 v80, v78, v8
	ds_read_b64_tr_b16 v[8:9], v0 offset:46080
	ds_read_b64_tr_b16 v[12:13], v0 offset:46592
	ds_read_b64_tr_b16 v[74:75], v0 offset:48128
	ds_read_b64_tr_b16 v[78:79], v0 offset:48640
	v_cvt_pk_bf16_f32 v64, v64, v88
	v_cvt_pk_bf16_f32 v65, v89, v90
	v_cvt_pk_bf16_f32 v66, v91, v128
	v_cvt_pk_bf16_f32 v67, v129, v130
	v_exp_f32_e32 v2, v16
	v_exp_f32_e32 v3, v17
	s_waitcnt lgkmcnt(3)
	v_mfma_f32_32x32x16_bf16 v[48:63], v[6:9], v[64:67], v[48:63]
	v_exp_f32_e32 v7, v20
	v_exp_f32_e32 v8, v21
	v_exp_f32_e32 v5, v18
	v_exp_f32_e32 v6, v19
	v_add_f32_e32 v4, v139, v80
	v_cndmask_b32_e64 v2, v2, 0, s[42:43]
	v_add_f32_e32 v4, v4, v2
	s_waitcnt lgkmcnt(2)
	v_mfma_f32_32x32x16_bf16 v[32:47], v[10:13], v[64:67], v[32:47]
	v_cndmask_b32_e64 v10, v7, 0, s[30:31]
	v_exp_f32_e32 v7, v22
	v_cndmask_b32_e64 v11, v8, 0, s[34:35]
	v_exp_f32_e32 v8, v23
	v_cndmask_b32_e64 v3, 0, v3, s[40:41]
	v_cndmask_b32_e64 v12, v7, 0, s[28:29]
	v_exp_f32_e32 v7, v24
	v_add_f32_e32 v4, v3, v4
	v_cndmask_b32_e64 v5, v5, 0, s[36:37]
	v_cvt_pk_bf16_f32 v70, v131, v138
	v_cndmask_b32_e64 v24, v7, 0, s[26:27]
	v_exp_f32_e32 v7, v25
	v_add_f32_e32 v4, v5, v4
	v_cndmask_b32_e64 v6, v6, 0, s[38:39]
	v_cndmask_b32_e64 v13, v8, 0, s[24:25]
	v_exp_f32_e32 v8, v26
	v_cndmask_b32_e64 v25, v7, 0, s[22:23]
	v_exp_f32_e32 v7, v27
	v_add_f32_e32 v4, v6, v4
	s_waitcnt lgkmcnt(1)
	v_mfma_f32_32x32x16_bf16 v[48:63], v[72:75], v[68:71], v[48:63]
	v_add_f32_e32 v4, v10, v4
	v_add_f32_e32 v4, v11, v4
	v_add_f32_e32 v4, v12, v4
	v_cndmask_b32_e64 v26, v8, 0, s[18:19]
	v_cndmask_b32_e64 v64, v7, 0, s[20:21]
	v_cvt_pk_bf16_f32 v2, v2, v3
	v_cvt_pk_bf16_f32 v3, v5, v6
	ds_read_b64_tr_b16 v[6:7], v137 offset:49152
	ds_read_b64_tr_b16 v[8:9], v0 offset:50176
	v_add_f32_e32 v4, v13, v4
	s_waitcnt lgkmcnt(2)
	v_mfma_f32_32x32x16_bf16 v[32:47], v[76:79], v[68:71], v[32:47]
	v_add_f32_e32 v4, v24, v4
	v_add_f32_e32 v4, v25, v4
	v_exp_f32_e32 v28, v28
	v_add_f32_e32 v27, v26, v4
	v_exp_f32_e32 v29, v29
	v_cvt_pk_bf16_f32 v4, v10, v11
	v_cvt_pk_bf16_f32 v5, v12, v13
	ds_read_b64_tr_b16 v[10:11], v137 offset:49664
	ds_read_b64_tr_b16 v[16:17], v137 offset:51200
	ds_read_b64_tr_b16 v[20:21], v137 offset:51712
	ds_read_b64_tr_b16 v[12:13], v0 offset:50688
	ds_read_b64_tr_b16 v[18:19], v0 offset:52224
	ds_read_b64_tr_b16 v[22:23], v0 offset:52736
	s_waitcnt lgkmcnt(6)
; #define LAS __attribute__((address_space(3)))
; __device__ __forceinline__ float frcp(float x) { return __builtin_amdgcn_rcpf(x); }
; #define MFMA32(a, b, c) __builtin_amdgcn_mfma_f32_32x32x16_bf16((a), (b), (c), 0, 0, 0)
; __device__ __forceinline__ unsigned cvtpk(float lo, float hi) { f32x2_t v = {lo, hi}; bf16x2_t b = __builtin_convertvector(v, bf16x2_t); return __builtin_bit_cast(unsigned, b); }
; __device__ __forceinline__ s16x4 ds_tr(const LAS unsigned char* p) { return __builtin_bit_cast(s16x4, __builtin_amdgcn_ds_read_tr16_b64_v4i16((LAS v4i16_t*)p)); }
; __device__ __forceinline__ bf16x8 cat8(s16x4 lo, s16x4 hi) { return (bf16x8){lo[0], lo[1], lo[2], lo[3], hi[0], hi[1], hi[2], hi[3]}; }
; __device__ __forceinline__ void swa_compute(Frame& F, int u) {
;     ...
;             for (int r = 0; r < 16; ++r) { const int kl = (r & 3) + 8 * (r >> 2) + 4 * hi;
;                 const bool valid = (j == 0) ? (r32 < kl) : ((j == 4) ? (kl <= r32) : true);
;                 const float p = valid ? __builtin_amdgcn_exp2f(acc[r]) : 0.f; acc[r] = p; lsum += p; }
;             const bf16x8 pa0 = pack_step(acc, 0), pa1 = pack_step(acc, 1);
; #pragma unroll
;             for (int s = 0; s < 2; ++s)
; #pragma unroll
;                 for (int c = 0; c < 2; ++c) { const bf16x8 vf = cat8(ds_tr(Vt + s * 2048 + c * 512 + vb0), ds_tr(Vt + s * 2048 + c * 512 + vb1)); o[c] = MFMA32(vf, s ? pa1 : pa0, o[c]); }
;         }
;         lsum += __shfl_xor(lsum, 32);
;         const float inv = frcp(lsum + __builtin_amdgcn_exp2f(sinkv * 1.4426950408889634f - C2));
; #pragma unroll
;         for (int c = 0; c < 2; ++c)
; #pragma unroll
;             for (int g = 0; g < 4; ++g) { u32x2 w; w.x = cvtpk(o[c][4 * g] * inv, o[c][4 * g + 1] * inv); w.y = cvtpk(o[c][4 * g + 2] * inv, o[c][4 * g + 3] * inv);
;                 *(LAS u32x2*)(stg + r32 * 144 + (32 * c + 8 * g + 4 * hi) * 2) = w; }
; #pragma unroll
;         for (int jj = 0; jj < 4; ++jj) { const int idx = lane + 64 * jj, row = idx >> 3, c8 = idx & 7;
;             const u32x4 v = *(const LAS u32x4*)(stg + row * 144 + 16 * c8);
;             *(u32x4*)(MIX + (size_t)(R0 + row) * 1024 + 512 + hq * 64 + 8 * c8) = v; }
; __device__ __forceinline__ void swa_units(Frame& F, int u0, int stride) {
;     ...
;         __syncthreads();
;         swa_stage(F, kt_, vt_);
;         __syncthreads();
	v_mfma_f32_32x32x16_bf16 v[48:63], v[6:9], v[2:5], v[48:63]
	v_exp_f32_e32 v8, v30
	v_exp_f32_e32 v9, v31
	v_add_f32_e32 v0, v64, v27
	v_cndmask_b32_e64 v6, v28, 0, s[14:15]
	v_add_f32_e32 v0, v6, v0
	v_cndmask_b32_e64 v7, v29, 0, s[16:17]
	v_add_f32_e32 v0, v7, v0
	s_waitcnt lgkmcnt(2)
	v_mfma_f32_32x32x16_bf16 v[32:47], v[10:13], v[2:5], v[32:47]
	v_cndmask_b32_e64 v5, v8, 0, s[10:11]
	v_add_f32_e32 v0, v5, v0
	v_cndmask_b32_e64 v8, v9, 0, s[12:13]
	v_add_f32_e32 v0, v8, v0
	v_cvt_pk_bf16_f32 v4, v6, v7
	ds_bpermute_b32 v6, v153, v0
	v_cvt_pk_bf16_f32 v2, v24, v25
	v_cvt_pk_bf16_f32 v3, v26, v64
	v_cvt_pk_bf16_f32 v5, v5, v8
	v_lshlrev_b32_e32 v8, 3, v176
	s_waitcnt lgkmcnt(0)
	v_add_f32_e32 v0, v0, v6
	v_mfma_f32_32x32x16_bf16 v[48:63], v[16:19], v[2:5], v[48:63]
	v_add_f32_e32 v0, v175, v0
	v_rcp_f32_e32 v0, v0
	s_mov_b64 s[10:11], -1
	v_mfma_f32_32x32x16_bf16 v[32:47], v[20:23], v[2:5], v[32:47]
	s_nop 7
	v_mul_f32_e64 v2, v48, v0
	v_mul_f32_e64 v3, v49, v0
	v_mul_f32_e64 v4, v50, v0
	v_mul_f32_e64 v5, v51, v0
	v_cvt_pk_bf16_f32 v2, v2, v3
	v_cvt_pk_bf16_f32 v3, v4, v5
	v_pk_mul_f32 v[4:5], v[52:53], v[0:1] op_sel_hi:[1,0]
	v_pk_mul_f32 v[6:7], v[54:55], v[0:1] op_sel_hi:[1,0]
	v_cvt_pk_bf16_f32 v4, v4, v5
	v_cvt_pk_bf16_f32 v5, v6, v7
	ds_write2_b64 v132, v[2:3], v[4:5] offset1:2
	v_pk_mul_f32 v[2:3], v[56:57], v[0:1] op_sel_hi:[1,0]
	v_pk_mul_f32 v[4:5], v[58:59], v[0:1] op_sel_hi:[1,0]
	v_cvt_pk_bf16_f32 v2, v2, v3
	v_cvt_pk_bf16_f32 v3, v4, v5
	v_pk_mul_f32 v[4:5], v[60:61], v[0:1] op_sel_hi:[1,0]
	v_pk_mul_f32 v[6:7], v[62:63], v[0:1] op_sel_hi:[1,0]
	v_cvt_pk_bf16_f32 v4, v4, v5
	v_cvt_pk_bf16_f32 v5, v6, v7
	ds_write2_b64 v132, v[2:3], v[4:5] offset0:4 offset1:6
	v_pk_mul_f32 v[2:3], v[32:33], v[0:1] op_sel_hi:[1,0]
	v_pk_mul_f32 v[4:5], v[34:35], v[0:1] op_sel_hi:[1,0]
	v_cvt_pk_bf16_f32 v2, v2, v3
	v_cvt_pk_bf16_f32 v3, v4, v5
	v_pk_mul_f32 v[4:5], v[36:37], v[0:1] op_sel_hi:[1,0]
	v_pk_mul_f32 v[6:7], v[38:39], v[0:1] op_sel_hi:[1,0]
	v_cvt_pk_bf16_f32 v4, v4, v5
	v_cvt_pk_bf16_f32 v5, v6, v7
	ds_write2_b64 v132, v[2:3], v[4:5] offset0:8 offset1:10
	v_pk_mul_f32 v[2:3], v[40:41], v[0:1] op_sel_hi:[1,0]
	v_pk_mul_f32 v[4:5], v[42:43], v[0:1] op_sel_hi:[1,0]
	v_cvt_pk_bf16_f32 v2, v2, v3
	v_cvt_pk_bf16_f32 v3, v4, v5
	v_pk_mul_f32 v[4:5], v[44:45], v[0:1] op_sel_hi:[1,0]
	v_pk_mul_f32 v[6:7], v[46:47], v[0:1] op_sel_hi:[1,0]
	v_cvt_pk_bf16_f32 v4, v4, v5
	v_cvt_pk_bf16_f32 v5, v6, v7
	v_add_u32_e32 v6, s60, v174
	v_ashrrev_i32_e32 v7, 31, v6
	ds_write2_b64 v132, v[2:3], v[4:5] offset0:12 offset1:14
	v_lshlrev_b64 v[6:7], 11, v[6:7]
	ds_read_b128 v[2:5], v133
	v_lshl_add_u64 v[6:7], s[92:93], 0, v[6:7]
	v_lshl_add_u64 v[6:7], v[6:7], 0, s[52:53]
	v_lshlrev_b32_e32 v0, 1, v8
	v_lshl_add_u64 v[6:7], v[6:7], 0, v[0:1]
	v_add_co_u32_e32 v10, vcc, s69, v6
	s_nop 1
	v_addc_co_u32_e32 v11, vcc, 0, v7, vcc
	ds_read_b128 v[6:9], v134
	s_waitcnt lgkmcnt(1)
	global_store_dwordx4 v[10:11], v[2:5], off offset:1024 sc1
	s_nop 1
	v_add_u32_e32 v2, s60, v173
	v_ashrrev_i32_e32 v3, 31, v2
	v_lshlrev_b64 v[2:3], 11, v[2:3]
	v_lshl_add_u64 v[2:3], s[92:93], 0, v[2:3]
	v_lshl_add_u64 v[2:3], v[2:3], 0, s[52:53]
	v_lshl_add_u64 v[2:3], v[2:3], 0, v[0:1]
	v_add_co_u32_e32 v2, vcc, s69, v2
	s_nop 1
	v_addc_co_u32_e32 v3, vcc, 0, v3, vcc
	s_waitcnt lgkmcnt(0)
	global_store_dwordx4 v[2:3], v[6:9], off offset:1024 sc1
	ds_read_b128 v[2:5], v135
	s_nop 0
	v_add_u32_e32 v6, s60, v15
	v_ashrrev_i32_e32 v7, 31, v6
	v_lshlrev_b64 v[6:7], 11, v[6:7]
	v_lshl_add_u64 v[6:7], s[92:93], 0, v[6:7]
	v_lshl_add_u64 v[6:7], v[6:7], 0, s[52:53]
	v_lshl_add_u64 v[6:7], v[6:7], 0, v[0:1]
	v_add_co_u32_e32 v10, vcc, s69, v6
	s_nop 1
	v_addc_co_u32_e32 v11, vcc, 0, v7, vcc
	ds_read_b128 v[6:9], v136
	s_waitcnt lgkmcnt(1)
	global_store_dwordx4 v[10:11], v[2:5], off offset:1024 sc1
	s_nop 1
	v_add_u32_e32 v2, s60, v14
	v_ashrrev_i32_e32 v3, 31, v2
	v_lshlrev_b64 v[2:3], 11, v[2:3]
	v_lshl_add_u64 v[2:3], s[92:93], 0, v[2:3]
	v_lshl_add_u64 v[2:3], v[2:3], 0, s[52:53]
	v_lshl_add_u64 v[2:3], v[2:3], 0, v[0:1]
	v_add_co_u32_e32 v2, vcc, 0xb000000, v2
	s_nop 1
	v_addc_co_u32_e32 v3, vcc, 0, v3, vcc
	s_andn2_b64 vcc, exec, s[54:55]
	s_waitcnt lgkmcnt(0)
	global_store_dwordx4 v[2:3], v[6:9], off offset:1024 sc1
	s_cbranch_vccnz .LBB0_585
	s_add_i32 s48, s48, s65
	s_add_i32 s66, s66, s67
	s_mov_b64 s[10:11], 0
	s_barrier
	ds_write_b128 v162, v[96:99]
	ds_write_b128 v162, v[100:103] offset:32768
	ds_write_b128 v163, v[104:107]
	ds_write_b128 v163, v[108:111] offset:32768
	ds_write_b128 v164, v[112:115]
	ds_write_b128 v164, v[116:119] offset:32768
	ds_write_b128 v165, v[120:123]
	ds_write_b128 v165, v[124:127] offset:32768
	s_waitcnt lgkmcnt(0)
	s_barrier
	s_branch .LBB0_585
